# combo33: combo23 + the mid-segment s_setprio 0 / s_setprio 1 flip pairs between the two 16-MFMA runs of each GEMM compute segment deleted
# speedup vs baseline: 1.0007x; 1.0007x over previous
; #define PG8_STAGE(bufoff, gbase, voff) do { _Pragma("unroll") for (int _i = 0; _i < 2; ++_i) \
;         __builtin_amdgcn_global_load_lds((const unsigned*)((const char*)(gbase) + (voff)[_i]), (PG8_LAS unsigned*)(lds + (bufoff) + ldsw + _i * 8192), 16, 0, 0); } while (0)
; #define PG8_LDA(dst, b, h) do { _Pragma("unroll") for (int m = 0; m < 4; ++m) _Pragma("unroll") for (int k = 0; k < 2; ++k) dst[m][k] = *(const PG8_LAS bf16x8*)(lds + PG8_SA(b, h) + aoff + m * 2048 + k * 1024); } while (0)
; #define PG8_LDB(dst, b, h) do { _Pragma("unroll") for (int n = 0; n < 2; ++n) _Pragma("unroll") for (int k = 0; k < 2; ++k) dst[n][k] = *(const PG8_LAS bf16x8*)(lds + PG8_SB(b, h) + boff + n * 2048 + k * 1024); } while (0)
; #define PG8_MMA(ai, bj, At, Bt) do { __builtin_amdgcn_s_setprio(1); _Pragma("unroll") for (int m = 0; m < 4; ++m) _Pragma("unroll") for (int n = 0; n < 2; ++n) _Pragma("unroll") for (int k = 0; k < 2; ++k) \
;         acc[ai][bj][m][n] = __builtin_amdgcn_mfma_f32_16x16x32_bf16(Bt[n][k], At[m][k], acc[ai][bj][m][n], 0, 0, 0); __builtin_amdgcn_s_setprio(0); } while (0)
; #define PG8_WAIT_V(n) asm volatile("s_waitcnt vmcnt(" #n ")" ::: "memory")
; #define PG8_WAIT_L(n) asm volatile("s_waitcnt lgkmcnt(" #n ")" ::: "memory")
; template <class Epi, class Sched, bool ALIGN_EPI = false, bool SP2 = false>
; __device__ __forceinline__ void gemm_phase(PG8_LAS unsigned char* lds, const Gemm g, const Sched& S, const Epi& E) {
;     ...
;             const bool last = (t == nt - 2);
;             const char* a1 = cA + (size_t)(t + 1) * kstep;
;             const char* a2 = last ? nA : cA + (size_t)(t + 2) * kstep; const char* b2 = last ? nB : cB + (size_t)(t + 2) * kstep;
;             const char* a3 = a2 + kstep; const char* b3 = b2 + kstep;
;             if (last && has_next) S.a_ready(nxt);
;             if constexpr (SP2) {
;             PG8_LDB(B0, 0, 0); PG8_LDB(B1, 0, 1); PG8_SCHED; PG8_LDA(At, 0, 0); PG8_STAGE(PG8_SA(1, 1), a1 + hstep, voffA);
;             PG8_WAIT_V(8); PG8_WAIT_L(0); PG8_BAR; PG8_MMA(0, 0, At, B0); PG8_MMA(0, 1, At, B1); PG8_BAR; PG8_SCHED;
;             PG8_LDA(At, 0, 1); PG8_STAGE(PG8_SB(0, 0), b2, voffB); PG8_STAGE(PG8_SB(0, 1), b2 + hstep, voffB); PG8_STAGE(PG8_SA(0, 0), a2, voffA);
;             PG8_WAIT_V(8); PG8_WAIT_L(0); PG8_BAR; PG8_MMA(1, 0, At, B0); PG8_MMA(1, 1, At, B1); PG8_BAR; PG8_SCHED;
.LBB0_212:
	s_add_u32 s18, s2, 0xfffc0080
	s_addc_u32 s19, s3, -1
	s_add_i32 s41, 0, 0x10000
	s_cmp_eq_u32 s40, 12
	s_cselect_b32 s21, s11, s19
	s_cselect_b32 s20, s34, s18
	s_cselect_b32 s19, s13, s37
	s_cselect_b32 s18, s35, s36
	s_add_i32 s44, 0, 0x14000
	v_add_u32_e32 v140, s41, v169
	v_add_u32_e32 v158, s44, v169
	ds_read_b128 v[128:131], v140
	ds_read_b128 v[132:135], v140 offset:1024
	ds_read_b128 v[136:139], v140 offset:2048
	ds_read_b128 v[140:143], v140 offset:3072
	ds_read_b128 v[154:157], v158
	ds_read_b128 v[172:175], v158 offset:1024
	ds_read_b128 v[176:179], v158 offset:2048
	ds_read_b128 v[180:183], v158 offset:3072
	v_lshl_add_u64 v[158:159], s[2:3], 0, v[150:151]
	s_add_i32 m0, s23, 0xc000
	ds_read_b128 v[184:187], v171
	ds_read_b128 v[206:209], v171 offset:1024
	ds_read_b128 v[210:213], v171 offset:2048
	ds_read_b128 v[214:217], v171 offset:3072
	ds_read_b128 v[218:221], v171 offset:4096
	ds_read_b128 v[222:225], v171 offset:5120
	ds_read_b128 v[226:229], v171 offset:6144
	ds_read_b128 v[230:233], v171 offset:7168
	global_load_lds_dwordx4 v[158:159], off
	v_lshl_add_u64 v[158:159], s[2:3], 0, v[152:153]
	s_add_i32 m0, s23, 0xe000
	s_nop 0
	global_load_lds_dwordx4 v[158:159], off
	s_waitcnt vmcnt(8)
	s_waitcnt lgkmcnt(0)
	s_barrier
	s_setprio 1
	s_waitcnt lgkmcnt(0)
	v_mfma_f32_16x16x32_bf16 v[124:127], v[128:131], v[184:187], v[124:127]
	v_mfma_f32_16x16x32_bf16 v[120:123], v[136:139], v[184:187], v[120:123]
	v_mfma_f32_16x16x32_bf16 v[108:111], v[128:131], v[210:213], v[108:111]
	v_mfma_f32_16x16x32_bf16 v[104:107], v[136:139], v[210:213], v[104:107]
	v_mfma_f32_16x16x32_bf16 v[92:95], v[128:131], v[218:221], v[92:95]
	v_mfma_f32_16x16x32_bf16 v[88:91], v[136:139], v[218:221], v[88:91]
	v_mfma_f32_16x16x32_bf16 v[76:79], v[128:131], v[226:229], v[76:79]
	v_mfma_f32_16x16x32_bf16 v[72:75], v[136:139], v[226:229], v[72:75]
	v_mfma_f32_16x16x32_bf16 v[124:127], v[132:135], v[206:209], v[124:127]
	v_mfma_f32_16x16x32_bf16 v[120:123], v[140:143], v[206:209], v[120:123]
	v_mfma_f32_16x16x32_bf16 v[108:111], v[132:135], v[214:217], v[108:111]
	v_mfma_f32_16x16x32_bf16 v[104:107], v[140:143], v[214:217], v[104:107]
	v_mfma_f32_16x16x32_bf16 v[92:95], v[132:135], v[222:225], v[92:95]
	v_mfma_f32_16x16x32_bf16 v[88:91], v[140:143], v[222:225], v[88:91]
	v_mfma_f32_16x16x32_bf16 v[76:79], v[132:135], v[230:233], v[76:79]
	v_mfma_f32_16x16x32_bf16 v[72:75], v[140:143], v[230:233], v[72:75]
	v_mfma_f32_16x16x32_bf16 v[116:119], v[154:157], v[184:187], v[116:119]
	v_mfma_f32_16x16x32_bf16 v[112:115], v[176:179], v[184:187], v[112:115]
	v_mfma_f32_16x16x32_bf16 v[100:103], v[154:157], v[210:213], v[100:103]
	v_mfma_f32_16x16x32_bf16 v[96:99], v[176:179], v[210:213], v[96:99]
	v_mfma_f32_16x16x32_bf16 v[84:87], v[154:157], v[218:221], v[84:87]
	v_mfma_f32_16x16x32_bf16 v[80:83], v[176:179], v[218:221], v[80:83]
	v_mfma_f32_16x16x32_bf16 v[68:71], v[154:157], v[226:229], v[68:71]
	v_mfma_f32_16x16x32_bf16 v[64:67], v[176:179], v[226:229], v[64:67]
	v_mfma_f32_16x16x32_bf16 v[116:119], v[172:175], v[206:209], v[116:119]
	v_mfma_f32_16x16x32_bf16 v[112:115], v[180:183], v[206:209], v[112:115]
	v_mfma_f32_16x16x32_bf16 v[100:103], v[172:175], v[214:217], v[100:103]
	v_mfma_f32_16x16x32_bf16 v[96:99], v[180:183], v[214:217], v[96:99]
	v_mfma_f32_16x16x32_bf16 v[84:87], v[172:175], v[222:225], v[84:87]
	v_mfma_f32_16x16x32_bf16 v[80:83], v[180:183], v[222:225], v[80:83]
	v_mfma_f32_16x16x32_bf16 v[68:71], v[172:175], v[230:233], v[68:71]
	v_mfma_f32_16x16x32_bf16 v[64:67], v[180:183], v[230:233], v[64:67]
	s_setprio 0
	s_barrier
	s_add_i32 s41, s41, s22
	v_lshl_add_u64 v[158:159], s[18:19], 0, v[160:161]
	s_mov_b32 m0, s41
	ds_read_b128 v[184:187], v171 offset:16384
	ds_read_b128 v[206:209], v171 offset:17408
	ds_read_b128 v[210:213], v171 offset:18432
	ds_read_b128 v[214:217], v171 offset:19456
	ds_read_b128 v[218:221], v171 offset:20480
	ds_read_b128 v[222:225], v171 offset:21504
	ds_read_b128 v[226:229], v171 offset:22528
	ds_read_b128 v[230:233], v171 offset:23552
	global_load_lds_dwordx4 v[158:159], off
	s_add_i32 m0, s41, 0x2000
	s_add_u32 s42, s18, 0x40000
	v_lshl_add_u64 v[162:163], s[18:19], 0, v[144:145]
	s_addc_u32 s43, s19, 0
	s_add_i32 s41, s44, s22
	global_load_lds_dwordx4 v[162:163], off
	v_lshl_add_u64 v[164:165], s[42:43], 0, v[160:161]
	s_mov_b32 m0, s41
	v_lshl_add_u64 v[188:189], s[20:21], 0, v[146:147]
	global_load_lds_dwordx4 v[164:165], off
	v_lshl_add_u64 v[164:165], s[42:43], 0, v[144:145]
	s_add_i32 m0, s41, 0x2000
	s_nop 0
	global_load_lds_dwordx4 v[164:165], off
	v_lshl_add_u64 v[164:165], s[20:21], 0, v[148:149]
	s_mov_b32 m0, s23
	s_nop 0
	global_load_lds_dwordx4 v[164:165], off
	s_mov_b32 m0, s24
	s_nop 0
	global_load_lds_dwordx4 v[188:189], off
	s_waitcnt vmcnt(8)
	s_waitcnt lgkmcnt(0)
	s_barrier
; #define PG8_STAGE(bufoff, gbase, voff) do { _Pragma("unroll") for (int _i = 0; _i < 2; ++_i) \
;         __builtin_amdgcn_global_load_lds((const unsigned*)((const char*)(gbase) + (voff)[_i]), (PG8_LAS unsigned*)(lds + (bufoff) + ldsw + _i * 8192), 16, 0, 0); } while (0)
; #define PG8_LDA(dst, b, h) do { _Pragma("unroll") for (int m = 0; m < 4; ++m) _Pragma("unroll") for (int k = 0; k < 2; ++k) dst[m][k] = *(const PG8_LAS bf16x8*)(lds + PG8_SA(b, h) + aoff + m * 2048 + k * 1024); } while (0)
; #define PG8_LDB(dst, b, h) do { _Pragma("unroll") for (int n = 0; n < 2; ++n) _Pragma("unroll") for (int k = 0; k < 2; ++k) dst[n][k] = *(const PG8_LAS bf16x8*)(lds + PG8_SB(b, h) + boff + n * 2048 + k * 1024); } while (0)
; #define PG8_MMA(ai, bj, At, Bt) do { __builtin_amdgcn_s_setprio(1); _Pragma("unroll") for (int m = 0; m < 4; ++m) _Pragma("unroll") for (int n = 0; n < 2; ++n) _Pragma("unroll") for (int k = 0; k < 2; ++k) \
;         acc[ai][bj][m][n] = __builtin_amdgcn_mfma_f32_16x16x32_bf16(Bt[n][k], At[m][k], acc[ai][bj][m][n], 0, 0, 0); __builtin_amdgcn_s_setprio(0); } while (0)
; #define PG8_WAIT_V(n) asm volatile("s_waitcnt vmcnt(" #n ")" ::: "memory")
; #define PG8_WAIT_L(n) asm volatile("s_waitcnt lgkmcnt(" #n ")" ::: "memory")
; #define PG8_BAR __builtin_amdgcn_s_barrier()
; #define PG8_SCHED __builtin_amdgcn_sched_barrier(0)
; template <class Epi, class Sched, bool ALIGN_EPI = false, bool SP2 = false>
; __device__ __forceinline__ void gemm_phase(PG8_LAS unsigned char* lds, const Gemm g, const Sched& S, const Epi& E) {
;     ...
;             PG8_WAIT_V(8); PG8_WAIT_L(0); PG8_BAR; PG8_MMA(1, 0, At, B0); PG8_MMA(1, 1, At, B1); PG8_BAR; PG8_SCHED;
;             PG8_LDB(B0, 1, 0); PG8_LDB(B1, 1, 1); PG8_SCHED; PG8_LDA(At, 1, 0); PG8_STAGE(PG8_SA(0, 1), a2 + hstep, voffA);
;             PG8_WAIT_V(8); PG8_WAIT_L(0); PG8_BAR; PG8_MMA(0, 0, At, B0); PG8_MMA(0, 1, At, B1); PG8_BAR; PG8_SCHED;
	s_setprio 1
	s_waitcnt lgkmcnt(0)
	v_mfma_f32_16x16x32_bf16 v[60:63], v[128:131], v[184:187], v[60:63]
	v_mfma_f32_16x16x32_bf16 v[56:59], v[136:139], v[184:187], v[56:59]
	v_mfma_f32_16x16x32_bf16 v[44:47], v[128:131], v[210:213], v[44:47]
	v_mfma_f32_16x16x32_bf16 v[40:43], v[136:139], v[210:213], v[40:43]
	v_mfma_f32_16x16x32_bf16 v[28:31], v[128:131], v[218:221], v[28:31]
	v_mfma_f32_16x16x32_bf16 v[24:27], v[136:139], v[218:221], v[24:27]
	v_mfma_f32_16x16x32_bf16 v[12:15], v[128:131], v[226:229], v[12:15]
	v_mfma_f32_16x16x32_bf16 v[8:11], v[136:139], v[226:229], v[8:11]
	v_mfma_f32_16x16x32_bf16 v[60:63], v[132:135], v[206:209], v[60:63]
	v_mfma_f32_16x16x32_bf16 v[56:59], v[140:143], v[206:209], v[56:59]
	v_mfma_f32_16x16x32_bf16 v[44:47], v[132:135], v[214:217], v[44:47]
	v_mfma_f32_16x16x32_bf16 v[40:43], v[140:143], v[214:217], v[40:43]
	v_mfma_f32_16x16x32_bf16 v[28:31], v[132:135], v[222:225], v[28:31]
	v_mfma_f32_16x16x32_bf16 v[24:27], v[140:143], v[222:225], v[24:27]
	v_mfma_f32_16x16x32_bf16 v[12:15], v[132:135], v[230:233], v[12:15]
	v_mfma_f32_16x16x32_bf16 v[8:11], v[140:143], v[230:233], v[8:11]
	v_mfma_f32_16x16x32_bf16 v[52:55], v[154:157], v[184:187], v[52:55]
	v_mfma_f32_16x16x32_bf16 v[48:51], v[176:179], v[184:187], v[48:51]
	v_mfma_f32_16x16x32_bf16 v[36:39], v[154:157], v[210:213], v[36:39]
	v_mfma_f32_16x16x32_bf16 v[32:35], v[176:179], v[210:213], v[32:35]
	v_mfma_f32_16x16x32_bf16 v[20:23], v[154:157], v[218:221], v[20:23]
	v_mfma_f32_16x16x32_bf16 v[16:19], v[176:179], v[218:221], v[16:19]
	v_mfma_f32_16x16x32_bf16 v[4:7], v[154:157], v[226:229], v[4:7]
	v_mfma_f32_16x16x32_bf16 v[0:3], v[176:179], v[226:229], v[0:3]
	v_mfma_f32_16x16x32_bf16 v[52:55], v[172:175], v[206:209], v[52:55]
	v_mfma_f32_16x16x32_bf16 v[48:51], v[180:183], v[206:209], v[48:51]
	v_mfma_f32_16x16x32_bf16 v[36:39], v[172:175], v[214:217], v[36:39]
	v_mfma_f32_16x16x32_bf16 v[32:35], v[180:183], v[214:217], v[32:35]
	v_mfma_f32_16x16x32_bf16 v[20:23], v[172:175], v[222:225], v[20:23]
	v_mfma_f32_16x16x32_bf16 v[16:19], v[180:183], v[222:225], v[16:19]
	v_mfma_f32_16x16x32_bf16 v[4:7], v[172:175], v[230:233], v[4:7]
	v_mfma_f32_16x16x32_bf16 v[0:3], v[180:183], v[230:233], v[0:3]
	s_setprio 0
	s_barrier
	s_add_i32 s41, 0, 0x18000
	s_add_i32 s42, 0, 0x1c000
	v_add_u32_e32 v140, s41, v169
	v_add_u32_e32 v166, s42, v169
	ds_read_b128 v[128:131], v140
	ds_read_b128 v[132:135], v140 offset:1024
	ds_read_b128 v[136:139], v140 offset:2048
	ds_read_b128 v[140:143], v140 offset:3072
	ds_read_b128 v[154:157], v166
	ds_read_b128 v[172:175], v166 offset:1024
	ds_read_b128 v[176:179], v166 offset:2048
	ds_read_b128 v[180:183], v166 offset:3072
	s_add_u32 s20, s20, 0x40000
	s_addc_u32 s21, s21, 0
	s_mov_b32 m0, s25
	v_lshl_add_u64 v[194:195], s[20:21], 0, v[148:149]
	ds_read_b128 v[184:187], v171 offset:32768
	ds_read_b128 v[206:209], v171 offset:33792
	ds_read_b128 v[210:213], v171 offset:34816
	ds_read_b128 v[214:217], v171 offset:35840
	ds_read_b128 v[218:221], v171 offset:36864
	ds_read_b128 v[222:225], v171 offset:37888
	ds_read_b128 v[226:229], v171 offset:38912
	ds_read_b128 v[230:233], v171 offset:39936
	global_load_lds_dwordx4 v[194:195], off
	v_lshl_add_u64 v[194:195], s[20:21], 0, v[146:147]
	s_mov_b32 m0, s26
	s_nop 0
	global_load_lds_dwordx4 v[194:195], off
	s_waitcnt vmcnt(8)
	s_waitcnt lgkmcnt(0)
	s_barrier
	s_setprio 1
	s_waitcnt lgkmcnt(0)
	v_mfma_f32_16x16x32_bf16 v[124:127], v[128:131], v[184:187], v[124:127]
	v_mfma_f32_16x16x32_bf16 v[120:123], v[136:139], v[184:187], v[120:123]
	v_mfma_f32_16x16x32_bf16 v[108:111], v[128:131], v[210:213], v[108:111]
	v_mfma_f32_16x16x32_bf16 v[104:107], v[136:139], v[210:213], v[104:107]
	v_mfma_f32_16x16x32_bf16 v[92:95], v[128:131], v[218:221], v[92:95]
	v_mfma_f32_16x16x32_bf16 v[88:91], v[136:139], v[218:221], v[88:91]
	v_mfma_f32_16x16x32_bf16 v[76:79], v[128:131], v[226:229], v[76:79]
	v_mfma_f32_16x16x32_bf16 v[72:75], v[136:139], v[226:229], v[72:75]
	v_mfma_f32_16x16x32_bf16 v[124:127], v[132:135], v[206:209], v[124:127]
	v_mfma_f32_16x16x32_bf16 v[120:123], v[140:143], v[206:209], v[120:123]
	v_mfma_f32_16x16x32_bf16 v[108:111], v[132:135], v[214:217], v[108:111]
	v_mfma_f32_16x16x32_bf16 v[104:107], v[140:143], v[214:217], v[104:107]
	v_mfma_f32_16x16x32_bf16 v[92:95], v[132:135], v[222:225], v[92:95]
	v_mfma_f32_16x16x32_bf16 v[88:91], v[140:143], v[222:225], v[88:91]
	v_mfma_f32_16x16x32_bf16 v[76:79], v[132:135], v[230:233], v[76:79]
	v_mfma_f32_16x16x32_bf16 v[72:75], v[140:143], v[230:233], v[72:75]
	v_mfma_f32_16x16x32_bf16 v[116:119], v[154:157], v[184:187], v[116:119]
	v_mfma_f32_16x16x32_bf16 v[112:115], v[176:179], v[184:187], v[112:115]
	v_mfma_f32_16x16x32_bf16 v[100:103], v[154:157], v[210:213], v[100:103]
	v_mfma_f32_16x16x32_bf16 v[96:99], v[176:179], v[210:213], v[96:99]
	v_mfma_f32_16x16x32_bf16 v[84:87], v[154:157], v[218:221], v[84:87]
	v_mfma_f32_16x16x32_bf16 v[80:83], v[176:179], v[218:221], v[80:83]
	v_mfma_f32_16x16x32_bf16 v[68:71], v[154:157], v[226:229], v[68:71]
	v_mfma_f32_16x16x32_bf16 v[64:67], v[176:179], v[226:229], v[64:67]
	v_mfma_f32_16x16x32_bf16 v[116:119], v[172:175], v[206:209], v[116:119]
	v_mfma_f32_16x16x32_bf16 v[112:115], v[180:183], v[206:209], v[112:115]
	v_mfma_f32_16x16x32_bf16 v[100:103], v[172:175], v[214:217], v[100:103]
	v_mfma_f32_16x16x32_bf16 v[96:99], v[180:183], v[214:217], v[96:99]
	v_mfma_f32_16x16x32_bf16 v[84:87], v[172:175], v[222:225], v[84:87]
	v_mfma_f32_16x16x32_bf16 v[80:83], v[180:183], v[222:225], v[80:83]
	v_mfma_f32_16x16x32_bf16 v[68:71], v[172:175], v[230:233], v[68:71]
	v_mfma_f32_16x16x32_bf16 v[64:67], v[180:183], v[230:233], v[64:67]
	s_setprio 0
	s_barrier
; #define PG8_STAGE(bufoff, gbase, voff) do { _Pragma("unroll") for (int _i = 0; _i < 2; ++_i) \
;         __builtin_amdgcn_global_load_lds((const unsigned*)((const char*)(gbase) + (voff)[_i]), (PG8_LAS unsigned*)(lds + (bufoff) + ldsw + _i * 8192), 16, 0, 0); } while (0)
; #define PG8_LDA(dst, b, h) do { _Pragma("unroll") for (int m = 0; m < 4; ++m) _Pragma("unroll") for (int k = 0; k < 2; ++k) dst[m][k] = *(const PG8_LAS bf16x8*)(lds + PG8_SA(b, h) + aoff + m * 2048 + k * 1024); } while (0)
; #define PG8_MMA(ai, bj, At, Bt) do { __builtin_amdgcn_s_setprio(1); _Pragma("unroll") for (int m = 0; m < 4; ++m) _Pragma("unroll") for (int n = 0; n < 2; ++n) _Pragma("unroll") for (int k = 0; k < 2; ++k) \
;         acc[ai][bj][m][n] = __builtin_amdgcn_mfma_f32_16x16x32_bf16(Bt[n][k], At[m][k], acc[ai][bj][m][n], 0, 0, 0); __builtin_amdgcn_s_setprio(0); } while (0)
; #define PG8_WAIT_V(n) asm volatile("s_waitcnt vmcnt(" #n ")" ::: "memory")
; #define PG8_WAIT_L(n) asm volatile("s_waitcnt lgkmcnt(" #n ")" ::: "memory")
; #define PG8_BAR __builtin_amdgcn_s_barrier()
; #define PG8_SCHED __builtin_amdgcn_sched_barrier(0)
; template <class Epi, class Sched, bool ALIGN_EPI = false, bool SP2 = false>
; __device__ __forceinline__ void gemm_phase(PG8_LAS unsigned char* lds, const Gemm g, const Sched& S, const Epi& E) {
;     ...
;             PG8_LDA(At, 1, 1); PG8_STAGE(PG8_SB(1, 0), b3, voffB); PG8_STAGE(PG8_SB(1, 1), b3 + hstep, voffB); PG8_STAGE(PG8_SA(1, 0), a3, voffA);
;             PG8_WAIT_V(8); PG8_WAIT_L(0); PG8_BAR; PG8_MMA(1, 0, At, B0); PG8_MMA(1, 1, At, B1); PG8_BAR; PG8_SCHED;
	s_add_i32 s20, s41, s22
	v_lshl_add_u64 v[158:159], v[158:159], 0, s[38:39]
	s_mov_b32 m0, s20
	ds_read_b128 v[184:187], v171 offset:49152
	ds_read_b128 v[206:209], v171 offset:50176
	ds_read_b128 v[210:213], v171 offset:51200
	ds_read_b128 v[214:217], v171 offset:52224
	ds_read_b128 v[218:221], v171 offset:53248
	ds_read_b128 v[222:225], v171 offset:54272
	ds_read_b128 v[226:229], v171 offset:55296
	ds_read_b128 v[230:233], v171 offset:56320
	global_load_lds_dwordx4 v[158:159], off
	s_add_i32 m0, s20, 0x2000
	s_add_u32 s18, s18, 0x40080
	v_lshl_add_u64 v[158:159], v[162:163], 0, s[38:39]
	s_addc_u32 s19, s19, 0
	s_add_i32 s20, s42, s22
	global_load_lds_dwordx4 v[158:159], off
	v_lshl_add_u64 v[158:159], s[18:19], 0, v[160:161]
	s_mov_b32 m0, s20
	s_nop 0
	global_load_lds_dwordx4 v[158:159], off
	v_lshl_add_u64 v[158:159], s[18:19], 0, v[144:145]
	s_add_i32 m0, s20, 0x2000
	s_nop 0
	global_load_lds_dwordx4 v[158:159], off
	v_lshl_add_u64 v[158:159], v[164:165], 0, s[38:39]
	s_mov_b32 m0, s29
	s_nop 0
	global_load_lds_dwordx4 v[158:159], off
	v_lshl_add_u64 v[158:159], v[188:189], 0, s[38:39]
	s_mov_b32 m0, s30
	s_nop 0
	global_load_lds_dwordx4 v[158:159], off
	s_waitcnt vmcnt(8)
	s_waitcnt lgkmcnt(0)
	s_barrier
	s_setprio 1
	s_waitcnt lgkmcnt(0)
	v_mfma_f32_16x16x32_bf16 v[60:63], v[128:131], v[184:187], v[60:63]
	v_mfma_f32_16x16x32_bf16 v[56:59], v[136:139], v[184:187], v[56:59]
	v_mfma_f32_16x16x32_bf16 v[44:47], v[128:131], v[210:213], v[44:47]
	v_mfma_f32_16x16x32_bf16 v[40:43], v[136:139], v[210:213], v[40:43]
	v_mfma_f32_16x16x32_bf16 v[28:31], v[128:131], v[218:221], v[28:31]
	v_mfma_f32_16x16x32_bf16 v[24:27], v[136:139], v[218:221], v[24:27]
	v_mfma_f32_16x16x32_bf16 v[12:15], v[128:131], v[226:229], v[12:15]
	v_mfma_f32_16x16x32_bf16 v[8:11], v[136:139], v[226:229], v[8:11]
	v_mfma_f32_16x16x32_bf16 v[60:63], v[132:135], v[206:209], v[60:63]
	v_mfma_f32_16x16x32_bf16 v[56:59], v[140:143], v[206:209], v[56:59]
	v_mfma_f32_16x16x32_bf16 v[44:47], v[132:135], v[214:217], v[44:47]
	v_mfma_f32_16x16x32_bf16 v[40:43], v[140:143], v[214:217], v[40:43]
	v_mfma_f32_16x16x32_bf16 v[28:31], v[132:135], v[222:225], v[28:31]
	v_mfma_f32_16x16x32_bf16 v[24:27], v[140:143], v[222:225], v[24:27]
	v_mfma_f32_16x16x32_bf16 v[12:15], v[132:135], v[230:233], v[12:15]
	v_mfma_f32_16x16x32_bf16 v[8:11], v[140:143], v[230:233], v[8:11]
	v_mfma_f32_16x16x32_bf16 v[52:55], v[154:157], v[184:187], v[52:55]
	v_mfma_f32_16x16x32_bf16 v[48:51], v[176:179], v[184:187], v[48:51]
	v_mfma_f32_16x16x32_bf16 v[36:39], v[154:157], v[210:213], v[36:39]
	v_mfma_f32_16x16x32_bf16 v[32:35], v[176:179], v[210:213], v[32:35]
	v_mfma_f32_16x16x32_bf16 v[20:23], v[154:157], v[218:221], v[20:23]
	v_mfma_f32_16x16x32_bf16 v[16:19], v[176:179], v[218:221], v[16:19]
	v_mfma_f32_16x16x32_bf16 v[4:7], v[154:157], v[226:229], v[4:7]
	v_mfma_f32_16x16x32_bf16 v[0:3], v[176:179], v[226:229], v[0:3]
	v_mfma_f32_16x16x32_bf16 v[52:55], v[172:175], v[206:209], v[52:55]
	v_mfma_f32_16x16x32_bf16 v[48:51], v[180:183], v[206:209], v[48:51]
	v_mfma_f32_16x16x32_bf16 v[36:39], v[172:175], v[214:217], v[36:39]
	v_mfma_f32_16x16x32_bf16 v[32:35], v[180:183], v[214:217], v[32:35]
	v_mfma_f32_16x16x32_bf16 v[20:23], v[172:175], v[222:225], v[20:23]
	v_mfma_f32_16x16x32_bf16 v[16:19], v[180:183], v[222:225], v[16:19]
	v_mfma_f32_16x16x32_bf16 v[4:7], v[172:175], v[230:233], v[4:7]
	v_mfma_f32_16x16x32_bf16 v[0:3], v[180:183], v[230:233], v[0:3]
	s_setprio 0
	s_barrier
	s_add_i32 s40, s40, 2
	s_add_u32 s2, s2, 0x100
	s_addc_u32 s3, s3, 0
	s_add_u32 s36, s36, 0x100
	s_addc_u32 s37, s37, 0
	s_cmp_gt_u32 s40, 13
	s_cbranch_scc0 .LBB0_212
	s_and_b64 vcc, exec, s[8:9]
	s_cbranch_vccz .LBB0_215
	s_barrier

; #define PG8_STAGE(bufoff, gbase, voff) do { _Pragma("unroll") for (int _i = 0; _i < 2; ++_i) \
;         __builtin_amdgcn_global_load_lds((const unsigned*)((const char*)(gbase) + (voff)[_i]), (PG8_LAS unsigned*)(lds + (bufoff) + ldsw + _i * 8192), 16, 0, 0); } while (0)
; #define PG8_LDA(dst, b, h) do { _Pragma("unroll") for (int m = 0; m < 4; ++m) _Pragma("unroll") for (int k = 0; k < 2; ++k) dst[m][k] = *(const PG8_LAS bf16x8*)(lds + PG8_SA(b, h) + aoff + m * 2048 + k * 1024); } while (0)
; #define PG8_LDB(dst, b, h) do { _Pragma("unroll") for (int n = 0; n < 2; ++n) _Pragma("unroll") for (int k = 0; k < 2; ++k) dst[n][k] = *(const PG8_LAS bf16x8*)(lds + PG8_SB(b, h) + boff + n * 2048 + k * 1024); } while (0)
; #define PG8_MMA(ai, bj, At, Bt) do { __builtin_amdgcn_s_setprio(1); _Pragma("unroll") for (int m = 0; m < 4; ++m) _Pragma("unroll") for (int n = 0; n < 2; ++n) _Pragma("unroll") for (int k = 0; k < 2; ++k) \
;         acc[ai][bj][m][n] = __builtin_amdgcn_mfma_f32_16x16x32_bf16(Bt[n][k], At[m][k], acc[ai][bj][m][n], 0, 0, 0); __builtin_amdgcn_s_setprio(0); } while (0)
; #define PG8_WAIT_V(n) asm volatile("s_waitcnt vmcnt(" #n ")" ::: "memory")
; #define PG8_WAIT_L(n) asm volatile("s_waitcnt lgkmcnt(" #n ")" ::: "memory")
; #define PG8_BAR __builtin_amdgcn_s_barrier()
; #define PG8_SCHED __builtin_amdgcn_sched_barrier(0)
; template <class Epi, class Sched, bool ALIGN_EPI = false, bool SP2 = false>
; __device__ __forceinline__ void gemm_phase(PG8_LAS unsigned char* lds, const Gemm g, const Sched& S, const Epi& E) {
;     ...
;             const bool last = (t == nt - 2);
;             const char* a1 = cA + (size_t)(t + 1) * kstep;
;             const char* a2 = last ? nA : cA + (size_t)(t + 2) * kstep; const char* b2 = last ? nB : cB + (size_t)(t + 2) * kstep;
;             const char* a3 = a2 + kstep; const char* b3 = b2 + kstep;
;             if (last && has_next) S.a_ready(nxt);
;             if constexpr (SP2) {
;             PG8_LDB(B0, 0, 0); PG8_LDB(B1, 0, 1); PG8_SCHED; PG8_LDA(At, 0, 0); PG8_STAGE(PG8_SA(1, 1), a1 + hstep, voffA);
;             PG8_WAIT_V(8); PG8_WAIT_L(0); PG8_BAR; PG8_MMA(0, 0, At, B0); PG8_MMA(0, 1, At, B1); PG8_BAR; PG8_SCHED;
;             PG8_LDA(At, 0, 1); PG8_STAGE(PG8_SB(0, 0), b2, voffB); PG8_STAGE(PG8_SB(0, 1), b2 + hstep, voffB); PG8_STAGE(PG8_SA(0, 0), a2, voffA);
.LBB0_373:
	s_add_i32 s46, s24, 2
	s_add_u32 s47, s0, 0x80
	s_addc_u32 s25, s1, 0
	s_add_i32 s50, 0, 0x10000
	s_cmp_eq_u32 s42, s24
	s_cselect_b32 s25, s21, s25
	s_cselect_b32 s24, s20, s47
	v_add_u32_e32 v140, s50, v141
	s_cselect_b32 s49, s23, s27
	s_cselect_b32 s48, s22, s26
	s_add_i32 s47, 0, 0x14000
	ds_read_b128 v[146:149], v140
	ds_read_b128 v[150:153], v140 offset:1024
	ds_read_b128 v[154:157], v140 offset:2048
	ds_read_b128 v[162:165], v140 offset:3072
	v_add_u32_e32 v140, s47, v141
	ds_read_b128 v[166:169], v140
	ds_read_b128 v[170:173], v140 offset:1024
	ds_read_b128 v[174:177], v140 offset:2048
	ds_read_b128 v[178:181], v140 offset:3072
	v_lshl_add_u64 v[142:143], s[0:1], 0, v[136:137]
	s_add_i32 m0, s31, 0xc000
	ds_read_b128 v[182:185], v145
	ds_read_b128 v[186:189], v145 offset:1024
	ds_read_b128 v[194:197], v145 offset:2048
	ds_read_b128 v[206:209], v145 offset:3072
	ds_read_b128 v[210:213], v145 offset:4096
	ds_read_b128 v[214:217], v145 offset:5120
	ds_read_b128 v[218:221], v145 offset:6144
	ds_read_b128 v[222:225], v145 offset:7168
	global_load_lds_dwordx4 v[142:143], off
	v_lshl_add_u64 v[142:143], s[0:1], 0, v[138:139]
	s_add_i32 m0, s31, 0xe000
	s_nop 0
	global_load_lds_dwordx4 v[142:143], off
	s_waitcnt vmcnt(8)
	s_waitcnt lgkmcnt(0)
	s_barrier
	s_setprio 1
	s_waitcnt lgkmcnt(0)
	v_mfma_f32_16x16x32_bf16 v[124:127], v[146:149], v[182:185], v[124:127]
	v_mfma_f32_16x16x32_bf16 v[120:123], v[154:157], v[182:185], v[120:123]
	v_mfma_f32_16x16x32_bf16 v[108:111], v[146:149], v[194:197], v[108:111]
	v_mfma_f32_16x16x32_bf16 v[104:107], v[154:157], v[194:197], v[104:107]
	v_mfma_f32_16x16x32_bf16 v[92:95], v[146:149], v[210:213], v[92:95]
	v_mfma_f32_16x16x32_bf16 v[88:91], v[154:157], v[210:213], v[88:91]
	v_mfma_f32_16x16x32_bf16 v[76:79], v[146:149], v[218:221], v[76:79]
	v_mfma_f32_16x16x32_bf16 v[72:75], v[154:157], v[218:221], v[72:75]
	v_mfma_f32_16x16x32_bf16 v[124:127], v[150:153], v[186:189], v[124:127]
	v_mfma_f32_16x16x32_bf16 v[120:123], v[162:165], v[186:189], v[120:123]
	v_mfma_f32_16x16x32_bf16 v[108:111], v[150:153], v[206:209], v[108:111]
	v_mfma_f32_16x16x32_bf16 v[104:107], v[162:165], v[206:209], v[104:107]
	v_mfma_f32_16x16x32_bf16 v[92:95], v[150:153], v[214:217], v[92:95]
	v_mfma_f32_16x16x32_bf16 v[88:91], v[162:165], v[214:217], v[88:91]
	v_mfma_f32_16x16x32_bf16 v[76:79], v[150:153], v[222:225], v[76:79]
	v_mfma_f32_16x16x32_bf16 v[72:75], v[162:165], v[222:225], v[72:75]
	v_mfma_f32_16x16x32_bf16 v[116:119], v[166:169], v[182:185], v[116:119]
	v_mfma_f32_16x16x32_bf16 v[112:115], v[174:177], v[182:185], v[112:115]
	v_mfma_f32_16x16x32_bf16 v[100:103], v[166:169], v[194:197], v[100:103]
	v_mfma_f32_16x16x32_bf16 v[96:99], v[174:177], v[194:197], v[96:99]
	v_mfma_f32_16x16x32_bf16 v[84:87], v[166:169], v[210:213], v[84:87]
	v_mfma_f32_16x16x32_bf16 v[80:83], v[174:177], v[210:213], v[80:83]
	v_mfma_f32_16x16x32_bf16 v[68:71], v[166:169], v[218:221], v[68:71]
	v_mfma_f32_16x16x32_bf16 v[64:67], v[174:177], v[218:221], v[64:67]
	v_mfma_f32_16x16x32_bf16 v[116:119], v[170:173], v[186:189], v[116:119]
	v_mfma_f32_16x16x32_bf16 v[112:115], v[178:181], v[186:189], v[112:115]
	v_mfma_f32_16x16x32_bf16 v[100:103], v[170:173], v[206:209], v[100:103]
	v_mfma_f32_16x16x32_bf16 v[96:99], v[178:181], v[206:209], v[96:99]
	v_mfma_f32_16x16x32_bf16 v[84:87], v[170:173], v[214:217], v[84:87]
	v_mfma_f32_16x16x32_bf16 v[80:83], v[178:181], v[214:217], v[80:83]
	v_mfma_f32_16x16x32_bf16 v[68:71], v[170:173], v[222:225], v[68:71]
	v_mfma_f32_16x16x32_bf16 v[64:67], v[178:181], v[222:225], v[64:67]
	s_setprio 0
	s_barrier
	s_add_i32 s50, s50, s30
	v_lshl_add_u64 v[142:143], s[48:49], 0, v[132:133]
	s_mov_b32 m0, s50
	ds_read_b128 v[182:185], v145 offset:16384
	ds_read_b128 v[186:189], v145 offset:17408
	ds_read_b128 v[194:197], v145 offset:18432
	ds_read_b128 v[206:209], v145 offset:19456
	ds_read_b128 v[210:213], v145 offset:20480
	ds_read_b128 v[214:217], v145 offset:21504
	ds_read_b128 v[218:221], v145 offset:22528
	ds_read_b128 v[222:225], v145 offset:23552
	global_load_lds_dwordx4 v[142:143], off
	s_add_i32 m0, s50, 0x2000
	v_lshl_add_u64 v[158:159], s[48:49], 0, v[128:129]
	s_add_u32 s48, s48, s8
	s_addc_u32 s49, s49, s9
	s_add_i32 s47, s47, s30
	global_load_lds_dwordx4 v[158:159], off
	v_lshl_add_u64 v[226:227], s[48:49], 0, v[132:133]
	s_mov_b32 m0, s47
	v_lshl_add_u64 v[228:229], s[48:49], 0, v[128:129]
	global_load_lds_dwordx4 v[226:227], off
	s_add_i32 m0, s47, 0x2000
	v_lshl_add_u64 v[230:231], s[24:25], 0, v[134:135]
	global_load_lds_dwordx4 v[228:229], off
	s_mov_b32 m0, s31
	v_lshl_add_u64 v[232:233], s[24:25], 0, v[130:131]
	global_load_lds_dwordx4 v[230:231], off
	s_mov_b32 m0, s34
	s_nop 0
	global_load_lds_dwordx4 v[232:233], off
	s_waitcnt vmcnt(8)
	s_waitcnt lgkmcnt(0)
	s_barrier
; #define PG8_STAGE(bufoff, gbase, voff) do { _Pragma("unroll") for (int _i = 0; _i < 2; ++_i) \
;         __builtin_amdgcn_global_load_lds((const unsigned*)((const char*)(gbase) + (voff)[_i]), (PG8_LAS unsigned*)(lds + (bufoff) + ldsw + _i * 8192), 16, 0, 0); } while (0)
; #define PG8_LDA(dst, b, h) do { _Pragma("unroll") for (int m = 0; m < 4; ++m) _Pragma("unroll") for (int k = 0; k < 2; ++k) dst[m][k] = *(const PG8_LAS bf16x8*)(lds + PG8_SA(b, h) + aoff + m * 2048 + k * 1024); } while (0)
; #define PG8_LDB(dst, b, h) do { _Pragma("unroll") for (int n = 0; n < 2; ++n) _Pragma("unroll") for (int k = 0; k < 2; ++k) dst[n][k] = *(const PG8_LAS bf16x8*)(lds + PG8_SB(b, h) + boff + n * 2048 + k * 1024); } while (0)
; #define PG8_MMA(ai, bj, At, Bt) do { __builtin_amdgcn_s_setprio(1); _Pragma("unroll") for (int m = 0; m < 4; ++m) _Pragma("unroll") for (int n = 0; n < 2; ++n) _Pragma("unroll") for (int k = 0; k < 2; ++k) \
;         acc[ai][bj][m][n] = __builtin_amdgcn_mfma_f32_16x16x32_bf16(Bt[n][k], At[m][k], acc[ai][bj][m][n], 0, 0, 0); __builtin_amdgcn_s_setprio(0); } while (0)
; #define PG8_WAIT_V(n) asm volatile("s_waitcnt vmcnt(" #n ")" ::: "memory")
; #define PG8_WAIT_L(n) asm volatile("s_waitcnt lgkmcnt(" #n ")" ::: "memory")
; #define PG8_BAR __builtin_amdgcn_s_barrier()
; #define PG8_SCHED __builtin_amdgcn_sched_barrier(0)
; template <class Epi, class Sched, bool ALIGN_EPI = false, bool SP2 = false>
; __device__ __forceinline__ void gemm_phase(PG8_LAS unsigned char* lds, const Gemm g, const Sched& S, const Epi& E) {
;     ...
;             PG8_WAIT_V(8); PG8_WAIT_L(0); PG8_BAR; PG8_MMA(1, 0, At, B0); PG8_MMA(1, 1, At, B1); PG8_BAR; PG8_SCHED;
;             PG8_LDB(B0, 1, 0); PG8_LDB(B1, 1, 1); PG8_SCHED; PG8_LDA(At, 1, 0); PG8_STAGE(PG8_SA(0, 1), a2 + hstep, voffA);
;             PG8_WAIT_V(8); PG8_WAIT_L(0); PG8_BAR; PG8_MMA(0, 0, At, B0); PG8_MMA(0, 1, At, B1); PG8_BAR; PG8_SCHED;
	s_setprio 1
	s_waitcnt lgkmcnt(0)
	v_mfma_f32_16x16x32_bf16 v[60:63], v[146:149], v[182:185], v[60:63]
	v_mfma_f32_16x16x32_bf16 v[56:59], v[154:157], v[182:185], v[56:59]
	v_mfma_f32_16x16x32_bf16 v[44:47], v[146:149], v[194:197], v[44:47]
	v_mfma_f32_16x16x32_bf16 v[40:43], v[154:157], v[194:197], v[40:43]
	v_mfma_f32_16x16x32_bf16 v[28:31], v[146:149], v[210:213], v[28:31]
	v_mfma_f32_16x16x32_bf16 v[24:27], v[154:157], v[210:213], v[24:27]
	v_mfma_f32_16x16x32_bf16 v[12:15], v[146:149], v[218:221], v[12:15]
	v_mfma_f32_16x16x32_bf16 v[8:11], v[154:157], v[218:221], v[8:11]
	v_mfma_f32_16x16x32_bf16 v[60:63], v[150:153], v[186:189], v[60:63]
	v_mfma_f32_16x16x32_bf16 v[56:59], v[162:165], v[186:189], v[56:59]
	v_mfma_f32_16x16x32_bf16 v[44:47], v[150:153], v[206:209], v[44:47]
	v_mfma_f32_16x16x32_bf16 v[40:43], v[162:165], v[206:209], v[40:43]
	v_mfma_f32_16x16x32_bf16 v[28:31], v[150:153], v[214:217], v[28:31]
	v_mfma_f32_16x16x32_bf16 v[24:27], v[162:165], v[214:217], v[24:27]
	v_mfma_f32_16x16x32_bf16 v[12:15], v[150:153], v[222:225], v[12:15]
	v_mfma_f32_16x16x32_bf16 v[8:11], v[162:165], v[222:225], v[8:11]
	v_mfma_f32_16x16x32_bf16 v[52:55], v[166:169], v[182:185], v[52:55]
	v_mfma_f32_16x16x32_bf16 v[48:51], v[174:177], v[182:185], v[48:51]
	v_mfma_f32_16x16x32_bf16 v[36:39], v[166:169], v[194:197], v[36:39]
	v_mfma_f32_16x16x32_bf16 v[32:35], v[174:177], v[194:197], v[32:35]
	v_mfma_f32_16x16x32_bf16 v[20:23], v[166:169], v[210:213], v[20:23]
	v_mfma_f32_16x16x32_bf16 v[16:19], v[174:177], v[210:213], v[16:19]
	v_mfma_f32_16x16x32_bf16 v[4:7], v[166:169], v[218:221], v[4:7]
	v_mfma_f32_16x16x32_bf16 v[0:3], v[174:177], v[218:221], v[0:3]
	v_mfma_f32_16x16x32_bf16 v[52:55], v[170:173], v[186:189], v[52:55]
	v_mfma_f32_16x16x32_bf16 v[48:51], v[178:181], v[186:189], v[48:51]
	v_mfma_f32_16x16x32_bf16 v[36:39], v[170:173], v[206:209], v[36:39]
	v_mfma_f32_16x16x32_bf16 v[32:35], v[178:181], v[206:209], v[32:35]
	v_mfma_f32_16x16x32_bf16 v[20:23], v[170:173], v[214:217], v[20:23]
	v_mfma_f32_16x16x32_bf16 v[16:19], v[178:181], v[214:217], v[16:19]
	v_mfma_f32_16x16x32_bf16 v[4:7], v[170:173], v[222:225], v[4:7]
	v_mfma_f32_16x16x32_bf16 v[0:3], v[178:181], v[222:225], v[0:3]
	s_setprio 0
	s_barrier
	s_add_i32 s47, 0, 0x18000
	v_add_u32_e32 v140, s47, v141
	s_add_i32 s48, 0, 0x1c000
	ds_read_b128 v[146:149], v140
	ds_read_b128 v[150:153], v140 offset:1024
	ds_read_b128 v[154:157], v140 offset:2048
	ds_read_b128 v[162:165], v140 offset:3072
	v_add_u32_e32 v140, s48, v141
	ds_read_b128 v[166:169], v140
	ds_read_b128 v[170:173], v140 offset:1024
	ds_read_b128 v[174:177], v140 offset:2048
	ds_read_b128 v[178:181], v140 offset:3072
	s_add_u32 s24, s24, s8
	s_addc_u32 s25, s25, s9
	s_mov_b32 m0, s35
	v_lshl_add_u64 v[234:235], s[24:25], 0, v[134:135]
	ds_read_b128 v[182:185], v145 offset:32768
	ds_read_b128 v[186:189], v145 offset:33792
	ds_read_b128 v[194:197], v145 offset:34816
	ds_read_b128 v[206:209], v145 offset:35840
	ds_read_b128 v[210:213], v145 offset:36864
	ds_read_b128 v[214:217], v145 offset:37888
	ds_read_b128 v[218:221], v145 offset:38912
	ds_read_b128 v[222:225], v145 offset:39936
	global_load_lds_dwordx4 v[234:235], off
	v_lshl_add_u64 v[234:235], s[24:25], 0, v[130:131]
	s_mov_b32 m0, s36
	s_nop 0
	global_load_lds_dwordx4 v[234:235], off
	s_waitcnt vmcnt(8)
	s_waitcnt lgkmcnt(0)
	s_barrier
	s_setprio 1
	s_waitcnt lgkmcnt(0)
	v_mfma_f32_16x16x32_bf16 v[124:127], v[146:149], v[182:185], v[124:127]
	v_mfma_f32_16x16x32_bf16 v[120:123], v[154:157], v[182:185], v[120:123]
	v_mfma_f32_16x16x32_bf16 v[108:111], v[146:149], v[194:197], v[108:111]
	v_mfma_f32_16x16x32_bf16 v[104:107], v[154:157], v[194:197], v[104:107]
	v_mfma_f32_16x16x32_bf16 v[92:95], v[146:149], v[210:213], v[92:95]
	v_mfma_f32_16x16x32_bf16 v[88:91], v[154:157], v[210:213], v[88:91]
	v_mfma_f32_16x16x32_bf16 v[76:79], v[146:149], v[218:221], v[76:79]
	v_mfma_f32_16x16x32_bf16 v[72:75], v[154:157], v[218:221], v[72:75]
	v_mfma_f32_16x16x32_bf16 v[124:127], v[150:153], v[186:189], v[124:127]
	v_mfma_f32_16x16x32_bf16 v[120:123], v[162:165], v[186:189], v[120:123]
	v_mfma_f32_16x16x32_bf16 v[108:111], v[150:153], v[206:209], v[108:111]
	v_mfma_f32_16x16x32_bf16 v[104:107], v[162:165], v[206:209], v[104:107]
	v_mfma_f32_16x16x32_bf16 v[92:95], v[150:153], v[214:217], v[92:95]
	v_mfma_f32_16x16x32_bf16 v[88:91], v[162:165], v[214:217], v[88:91]
	v_mfma_f32_16x16x32_bf16 v[76:79], v[150:153], v[222:225], v[76:79]
	v_mfma_f32_16x16x32_bf16 v[72:75], v[162:165], v[222:225], v[72:75]
	v_mfma_f32_16x16x32_bf16 v[116:119], v[166:169], v[182:185], v[116:119]
	v_mfma_f32_16x16x32_bf16 v[112:115], v[174:177], v[182:185], v[112:115]
	v_mfma_f32_16x16x32_bf16 v[100:103], v[166:169], v[194:197], v[100:103]
	v_mfma_f32_16x16x32_bf16 v[96:99], v[174:177], v[194:197], v[96:99]
	v_mfma_f32_16x16x32_bf16 v[84:87], v[166:169], v[210:213], v[84:87]
	v_mfma_f32_16x16x32_bf16 v[80:83], v[174:177], v[210:213], v[80:83]
	v_mfma_f32_16x16x32_bf16 v[68:71], v[166:169], v[218:221], v[68:71]
	v_mfma_f32_16x16x32_bf16 v[64:67], v[174:177], v[218:221], v[64:67]
	v_mfma_f32_16x16x32_bf16 v[116:119], v[170:173], v[186:189], v[116:119]
	v_mfma_f32_16x16x32_bf16 v[112:115], v[178:181], v[186:189], v[112:115]
	v_mfma_f32_16x16x32_bf16 v[100:103], v[170:173], v[206:209], v[100:103]
	v_mfma_f32_16x16x32_bf16 v[96:99], v[178:181], v[206:209], v[96:99]
	v_mfma_f32_16x16x32_bf16 v[84:87], v[170:173], v[214:217], v[84:87]
	v_mfma_f32_16x16x32_bf16 v[80:83], v[178:181], v[214:217], v[80:83]
	v_mfma_f32_16x16x32_bf16 v[68:71], v[170:173], v[222:225], v[68:71]
	v_mfma_f32_16x16x32_bf16 v[64:67], v[178:181], v[222:225], v[64:67]
	s_setprio 0
	s_barrier
; #define PG8_STAGE(bufoff, gbase, voff) do { _Pragma("unroll") for (int _i = 0; _i < 2; ++_i) \
;         __builtin_amdgcn_global_load_lds((const unsigned*)((const char*)(gbase) + (voff)[_i]), (PG8_LAS unsigned*)(lds + (bufoff) + ldsw + _i * 8192), 16, 0, 0); } while (0)
; #define PG8_LDA(dst, b, h) do { _Pragma("unroll") for (int m = 0; m < 4; ++m) _Pragma("unroll") for (int k = 0; k < 2; ++k) dst[m][k] = *(const PG8_LAS bf16x8*)(lds + PG8_SA(b, h) + aoff + m * 2048 + k * 1024); } while (0)
; #define PG8_MMA(ai, bj, At, Bt) do { __builtin_amdgcn_s_setprio(1); _Pragma("unroll") for (int m = 0; m < 4; ++m) _Pragma("unroll") for (int n = 0; n < 2; ++n) _Pragma("unroll") for (int k = 0; k < 2; ++k) \
;         acc[ai][bj][m][n] = __builtin_amdgcn_mfma_f32_16x16x32_bf16(Bt[n][k], At[m][k], acc[ai][bj][m][n], 0, 0, 0); __builtin_amdgcn_s_setprio(0); } while (0)
; #define PG8_WAIT_V(n) asm volatile("s_waitcnt vmcnt(" #n ")" ::: "memory")
; #define PG8_WAIT_L(n) asm volatile("s_waitcnt lgkmcnt(" #n ")" ::: "memory")
; #define PG8_BAR __builtin_amdgcn_s_barrier()
; #define PG8_SCHED __builtin_amdgcn_sched_barrier(0)
; template <class Epi, class Sched, bool ALIGN_EPI = false, bool SP2 = false>
; __device__ __forceinline__ void gemm_phase(PG8_LAS unsigned char* lds, const Gemm g, const Sched& S, const Epi& E) {
;     ...
;             PG8_LDA(At, 1, 1); PG8_STAGE(PG8_SB(1, 0), b3, voffB); PG8_STAGE(PG8_SB(1, 1), b3 + hstep, voffB); PG8_STAGE(PG8_SA(1, 0), a3, voffA);
;             PG8_WAIT_V(8); PG8_WAIT_L(0); PG8_BAR; PG8_MMA(1, 0, At, B0); PG8_MMA(1, 1, At, B1); PG8_BAR; PG8_SCHED;
	s_add_i32 s24, s47, s30
	v_lshl_add_u64 v[142:143], v[142:143], 0, s[38:39]
	s_mov_b32 m0, s24
	ds_read_b128 v[182:185], v145 offset:49152
	ds_read_b128 v[186:189], v145 offset:50176
	ds_read_b128 v[194:197], v145 offset:51200
	ds_read_b128 v[206:209], v145 offset:52224
	ds_read_b128 v[210:213], v145 offset:53248
	ds_read_b128 v[214:217], v145 offset:54272
	ds_read_b128 v[218:221], v145 offset:55296
	ds_read_b128 v[222:225], v145 offset:56320
	global_load_lds_dwordx4 v[142:143], off
	v_lshl_add_u64 v[142:143], v[158:159], 0, s[38:39]
	s_add_i32 m0, s24, 0x2000
	s_add_i32 s24, s48, s30
	global_load_lds_dwordx4 v[142:143], off
	v_lshl_add_u64 v[142:143], v[226:227], 0, s[38:39]
	s_mov_b32 m0, s24
	s_nop 0
	global_load_lds_dwordx4 v[142:143], off
	v_lshl_add_u64 v[142:143], v[228:229], 0, s[38:39]
	s_add_i32 m0, s24, 0x2000
	s_nop 0
	global_load_lds_dwordx4 v[142:143], off
	v_lshl_add_u64 v[142:143], v[230:231], 0, s[38:39]
	s_mov_b32 m0, s37
	s_nop 0
	global_load_lds_dwordx4 v[142:143], off
	v_lshl_add_u64 v[142:143], v[232:233], 0, s[38:39]
	s_mov_b32 m0, s40
	s_nop 0
	global_load_lds_dwordx4 v[142:143], off
	s_waitcnt vmcnt(8)
	s_waitcnt lgkmcnt(0)
	s_barrier
	s_setprio 1
	s_waitcnt lgkmcnt(0)
	v_mfma_f32_16x16x32_bf16 v[60:63], v[146:149], v[182:185], v[60:63]
	v_mfma_f32_16x16x32_bf16 v[56:59], v[154:157], v[182:185], v[56:59]
	v_mfma_f32_16x16x32_bf16 v[44:47], v[146:149], v[194:197], v[44:47]
	v_mfma_f32_16x16x32_bf16 v[40:43], v[154:157], v[194:197], v[40:43]
	v_mfma_f32_16x16x32_bf16 v[28:31], v[146:149], v[210:213], v[28:31]
	v_mfma_f32_16x16x32_bf16 v[24:27], v[154:157], v[210:213], v[24:27]
	v_mfma_f32_16x16x32_bf16 v[12:15], v[146:149], v[218:221], v[12:15]
	v_mfma_f32_16x16x32_bf16 v[8:11], v[154:157], v[218:221], v[8:11]
	v_mfma_f32_16x16x32_bf16 v[60:63], v[150:153], v[186:189], v[60:63]
	v_mfma_f32_16x16x32_bf16 v[56:59], v[162:165], v[186:189], v[56:59]
	v_mfma_f32_16x16x32_bf16 v[44:47], v[150:153], v[206:209], v[44:47]
	v_mfma_f32_16x16x32_bf16 v[40:43], v[162:165], v[206:209], v[40:43]
	v_mfma_f32_16x16x32_bf16 v[28:31], v[150:153], v[214:217], v[28:31]
	v_mfma_f32_16x16x32_bf16 v[24:27], v[162:165], v[214:217], v[24:27]
	v_mfma_f32_16x16x32_bf16 v[12:15], v[150:153], v[222:225], v[12:15]
	v_mfma_f32_16x16x32_bf16 v[8:11], v[162:165], v[222:225], v[8:11]
	v_mfma_f32_16x16x32_bf16 v[52:55], v[166:169], v[182:185], v[52:55]
	v_mfma_f32_16x16x32_bf16 v[48:51], v[174:177], v[182:185], v[48:51]
	v_mfma_f32_16x16x32_bf16 v[36:39], v[166:169], v[194:197], v[36:39]
	v_mfma_f32_16x16x32_bf16 v[32:35], v[174:177], v[194:197], v[32:35]
	v_mfma_f32_16x16x32_bf16 v[20:23], v[166:169], v[210:213], v[20:23]
	v_mfma_f32_16x16x32_bf16 v[16:19], v[174:177], v[210:213], v[16:19]
	v_mfma_f32_16x16x32_bf16 v[4:7], v[166:169], v[218:221], v[4:7]
	v_mfma_f32_16x16x32_bf16 v[0:3], v[174:177], v[218:221], v[0:3]
	v_mfma_f32_16x16x32_bf16 v[52:55], v[170:173], v[186:189], v[52:55]
	v_mfma_f32_16x16x32_bf16 v[48:51], v[178:181], v[186:189], v[48:51]
	v_mfma_f32_16x16x32_bf16 v[36:39], v[170:173], v[206:209], v[36:39]
	v_mfma_f32_16x16x32_bf16 v[32:35], v[178:181], v[206:209], v[32:35]
	v_mfma_f32_16x16x32_bf16 v[20:23], v[170:173], v[214:217], v[20:23]
	v_mfma_f32_16x16x32_bf16 v[16:19], v[178:181], v[214:217], v[16:19]
	v_mfma_f32_16x16x32_bf16 v[4:7], v[170:173], v[222:225], v[4:7]
	v_mfma_f32_16x16x32_bf16 v[0:3], v[178:181], v[222:225], v[0:3]
	s_setprio 0
	s_barrier
	s_add_u32 s0, s0, 0x100
	s_addc_u32 s1, s1, 0
	s_add_u32 s26, s26, 0x100
	s_addc_u32 s27, s27, 0
	s_cmp_ge_i32 s46, s41
	s_mov_b32 s24, s46
	s_cbranch_scc0 .LBB0_373
	s_movk_i32 s49, 0x4000

; #define PG8_STAGE(bufoff, gbase, voff) do { _Pragma("unroll") for (int _i = 0; _i < 2; ++_i) \
;         __builtin_amdgcn_global_load_lds((const unsigned*)((const char*)(gbase) + (voff)[_i]), (PG8_LAS unsigned*)(lds + (bufoff) + ldsw + _i * 8192), 16, 0, 0); } while (0)
; #define PG8_LDA(dst, b, h) do { _Pragma("unroll") for (int m = 0; m < 4; ++m) _Pragma("unroll") for (int k = 0; k < 2; ++k) dst[m][k] = *(const PG8_LAS bf16x8*)(lds + PG8_SA(b, h) + aoff + m * 2048 + k * 1024); } while (0)
; #define PG8_LDB(dst, b, h) do { _Pragma("unroll") for (int n = 0; n < 2; ++n) _Pragma("unroll") for (int k = 0; k < 2; ++k) dst[n][k] = *(const PG8_LAS bf16x8*)(lds + PG8_SB(b, h) + boff + n * 2048 + k * 1024); } while (0)
; #define PG8_MMA(ai, bj, At, Bt) do { __builtin_amdgcn_s_setprio(1); _Pragma("unroll") for (int m = 0; m < 4; ++m) _Pragma("unroll") for (int n = 0; n < 2; ++n) _Pragma("unroll") for (int k = 0; k < 2; ++k) \
;         acc[ai][bj][m][n] = __builtin_amdgcn_mfma_f32_16x16x32_bf16(Bt[n][k], At[m][k], acc[ai][bj][m][n], 0, 0, 0); __builtin_amdgcn_s_setprio(0); } while (0)
; #define PG8_WAIT_V(n) asm volatile("s_waitcnt vmcnt(" #n ")" ::: "memory")
; #define PG8_WAIT_L(n) asm volatile("s_waitcnt lgkmcnt(" #n ")" ::: "memory")
; #define PG8_BAR __builtin_amdgcn_s_barrier()
; #define PG8_SCHED __builtin_amdgcn_sched_barrier(0)
; template <class Epi, class Sched, bool ALIGN_EPI = false, bool SP2 = false>
; __device__ __forceinline__ void gemm_phase(PG8_LAS unsigned char* lds, const Gemm g, const Sched& S, const Epi& E) {
;     ...
;             const bool last = (t == nt - 2);
;             const char* a1 = cA + (size_t)(t + 1) * kstep;
;             const char* a2 = last ? nA : cA + (size_t)(t + 2) * kstep; const char* b2 = last ? nB : cB + (size_t)(t + 2) * kstep;
;             const char* a3 = a2 + kstep; const char* b3 = b2 + kstep;
;             if (last && has_next) S.a_ready(nxt);
;             if constexpr (SP2) {
;             PG8_LDB(B0, 0, 0); PG8_LDB(B1, 0, 1); PG8_SCHED; PG8_LDA(At, 0, 0); PG8_STAGE(PG8_SA(1, 1), a1 + hstep, voffA);
;             PG8_WAIT_V(8); PG8_WAIT_L(0); PG8_BAR; PG8_MMA(0, 0, At, B0); PG8_MMA(0, 1, At, B1); PG8_BAR; PG8_SCHED;
;             PG8_LDA(At, 0, 1); PG8_STAGE(PG8_SB(0, 0), b2, voffB); PG8_STAGE(PG8_SB(0, 1), b2 + hstep, voffB); PG8_STAGE(PG8_SA(0, 0), a2, voffA);
.LBB0_429:
	s_add_i32 s78, s0, 2
	s_or_b32 s42, s0, 1
	s_lshl_b64 s[44:45], s[78:79], 7
	s_add_u32 s33, s26, s44
	s_addc_u32 s1, s27, s45
	s_add_i32 s46, 0, 0x10000
	s_cmp_eq_u32 s0, s40
	s_cselect_b32 s43, 0, s44
	s_cselect_b32 s1, s23, s1
	s_cselect_b32 s0, s22, s33
	s_cselect_b32 s33, 0, s45
	s_add_u32 s44, s8, s43
	s_addc_u32 s45, s9, s33
	s_add_i32 s33, 0, 0x14000
	v_add_u32_e32 v148, s46, v156
	v_add_u32_e32 v158, s33, v156
	ds_read_b128 v[128:131], v148
	ds_read_b128 v[132:135], v148 offset:1024
	ds_read_b128 v[144:147], v148 offset:2048
	ds_read_b128 v[148:151], v148 offset:3072
	ds_read_b128 v[152:155], v158
	ds_read_b128 v[162:165], v158 offset:1024
	ds_read_b128 v[166:169], v158 offset:2048
	ds_read_b128 v[170:173], v158 offset:3072
	s_mov_b32 s43, s79
	s_lshl_b64 s[42:43], s[42:43], 7
	s_add_u32 s42, s19, s42
	s_addc_u32 s43, s25, s43
	v_lshl_add_u64 v[158:159], s[42:43], 0, v[142:143]
	s_add_i32 m0, s29, 0xc000
	ds_read_b128 v[174:177], v157
	ds_read_b128 v[178:181], v157 offset:1024
	ds_read_b128 v[182:185], v157 offset:2048
	ds_read_b128 v[186:189], v157 offset:3072
	ds_read_b128 v[194:197], v157 offset:4096
	ds_read_b128 v[206:209], v157 offset:5120
	ds_read_b128 v[210:213], v157 offset:6144
	ds_read_b128 v[214:217], v157 offset:7168
	global_load_lds_dwordx4 v[158:159], off
	v_lshl_add_u64 v[158:159], s[42:43], 0, v[138:139]
	s_add_i32 m0, s29, 0xe000
	s_nop 0
	global_load_lds_dwordx4 v[158:159], off
	s_waitcnt vmcnt(8)
	s_waitcnt lgkmcnt(0)
	s_barrier
	s_setprio 1
	s_waitcnt lgkmcnt(0)
	v_mfma_f32_16x16x32_bf16 v[124:127], v[128:131], v[174:177], v[124:127]
	v_mfma_f32_16x16x32_bf16 v[116:119], v[144:147], v[174:177], v[116:119]
	v_mfma_f32_16x16x32_bf16 v[108:111], v[128:131], v[182:185], v[108:111]
	v_mfma_f32_16x16x32_bf16 v[100:103], v[144:147], v[182:185], v[100:103]
	v_mfma_f32_16x16x32_bf16 v[92:95], v[128:131], v[194:197], v[92:95]
	v_mfma_f32_16x16x32_bf16 v[84:87], v[144:147], v[194:197], v[84:87]
	v_mfma_f32_16x16x32_bf16 v[76:79], v[128:131], v[210:213], v[76:79]
	v_mfma_f32_16x16x32_bf16 v[68:71], v[144:147], v[210:213], v[68:71]
	v_mfma_f32_16x16x32_bf16 v[124:127], v[132:135], v[178:181], v[124:127]
	v_mfma_f32_16x16x32_bf16 v[116:119], v[148:151], v[178:181], v[116:119]
	v_mfma_f32_16x16x32_bf16 v[108:111], v[132:135], v[186:189], v[108:111]
	v_mfma_f32_16x16x32_bf16 v[100:103], v[148:151], v[186:189], v[100:103]
	v_mfma_f32_16x16x32_bf16 v[92:95], v[132:135], v[206:209], v[92:95]
	v_mfma_f32_16x16x32_bf16 v[84:87], v[148:151], v[206:209], v[84:87]
	v_mfma_f32_16x16x32_bf16 v[76:79], v[132:135], v[214:217], v[76:79]
	v_mfma_f32_16x16x32_bf16 v[68:71], v[148:151], v[214:217], v[68:71]
	v_mfma_f32_16x16x32_bf16 v[120:123], v[152:155], v[174:177], v[120:123]
	v_mfma_f32_16x16x32_bf16 v[112:115], v[166:169], v[174:177], v[112:115]
	v_mfma_f32_16x16x32_bf16 v[104:107], v[152:155], v[182:185], v[104:107]
	v_mfma_f32_16x16x32_bf16 v[96:99], v[166:169], v[182:185], v[96:99]
	v_mfma_f32_16x16x32_bf16 v[88:91], v[152:155], v[194:197], v[88:91]
	v_mfma_f32_16x16x32_bf16 v[80:83], v[166:169], v[194:197], v[80:83]
	v_mfma_f32_16x16x32_bf16 v[72:75], v[152:155], v[210:213], v[72:75]
	v_mfma_f32_16x16x32_bf16 v[64:67], v[166:169], v[210:213], v[64:67]
	v_mfma_f32_16x16x32_bf16 v[120:123], v[162:165], v[178:181], v[120:123]
	v_mfma_f32_16x16x32_bf16 v[112:115], v[170:173], v[178:181], v[112:115]
	v_mfma_f32_16x16x32_bf16 v[104:107], v[162:165], v[186:189], v[104:107]
	v_mfma_f32_16x16x32_bf16 v[96:99], v[170:173], v[186:189], v[96:99]
	v_mfma_f32_16x16x32_bf16 v[88:91], v[162:165], v[206:209], v[88:91]
	v_mfma_f32_16x16x32_bf16 v[80:83], v[170:173], v[206:209], v[80:83]
	v_mfma_f32_16x16x32_bf16 v[72:75], v[162:165], v[214:217], v[72:75]
	v_mfma_f32_16x16x32_bf16 v[64:67], v[170:173], v[214:217], v[64:67]
	s_setprio 0
	s_barrier
	s_add_i32 s42, s46, s28
	v_lshl_add_u64 v[158:159], s[44:45], 0, v[140:141]
	s_mov_b32 m0, s42
	ds_read_b128 v[174:177], v157 offset:16384
	ds_read_b128 v[178:181], v157 offset:17408
	ds_read_b128 v[182:185], v157 offset:18432
	ds_read_b128 v[186:189], v157 offset:19456
	ds_read_b128 v[194:197], v157 offset:20480
	ds_read_b128 v[206:209], v157 offset:21504
	ds_read_b128 v[210:213], v157 offset:22528
	ds_read_b128 v[214:217], v157 offset:23552
	global_load_lds_dwordx4 v[158:159], off
	s_add_i32 m0, s42, 0x2000
	s_add_u32 s42, s44, s10
	v_lshl_add_u64 v[218:219], s[44:45], 0, v[136:137]
	s_addc_u32 s43, s45, s11
	s_add_i32 s33, s33, s28
	global_load_lds_dwordx4 v[218:219], off
	v_lshl_add_u64 v[220:221], s[42:43], 0, v[140:141]
	s_mov_b32 m0, s33
	v_lshl_add_u64 v[222:223], s[42:43], 0, v[136:137]
	global_load_lds_dwordx4 v[220:221], off
	s_add_i32 m0, s33, 0x2000
	v_lshl_add_u64 v[224:225], s[0:1], 0, v[142:143]
	global_load_lds_dwordx4 v[222:223], off
	s_mov_b32 m0, s29
	v_lshl_add_u64 v[226:227], s[0:1], 0, v[138:139]
	global_load_lds_dwordx4 v[224:225], off
	s_mov_b32 m0, s30
	s_nop 0
	global_load_lds_dwordx4 v[226:227], off
	s_waitcnt vmcnt(8)
	s_waitcnt lgkmcnt(0)
	s_barrier
; #define PG8_STAGE(bufoff, gbase, voff) do { _Pragma("unroll") for (int _i = 0; _i < 2; ++_i) \
;         __builtin_amdgcn_global_load_lds((const unsigned*)((const char*)(gbase) + (voff)[_i]), (PG8_LAS unsigned*)(lds + (bufoff) + ldsw + _i * 8192), 16, 0, 0); } while (0)
; #define PG8_LDA(dst, b, h) do { _Pragma("unroll") for (int m = 0; m < 4; ++m) _Pragma("unroll") for (int k = 0; k < 2; ++k) dst[m][k] = *(const PG8_LAS bf16x8*)(lds + PG8_SA(b, h) + aoff + m * 2048 + k * 1024); } while (0)
; #define PG8_LDB(dst, b, h) do { _Pragma("unroll") for (int n = 0; n < 2; ++n) _Pragma("unroll") for (int k = 0; k < 2; ++k) dst[n][k] = *(const PG8_LAS bf16x8*)(lds + PG8_SB(b, h) + boff + n * 2048 + k * 1024); } while (0)
; #define PG8_MMA(ai, bj, At, Bt) do { __builtin_amdgcn_s_setprio(1); _Pragma("unroll") for (int m = 0; m < 4; ++m) _Pragma("unroll") for (int n = 0; n < 2; ++n) _Pragma("unroll") for (int k = 0; k < 2; ++k) \
;         acc[ai][bj][m][n] = __builtin_amdgcn_mfma_f32_16x16x32_bf16(Bt[n][k], At[m][k], acc[ai][bj][m][n], 0, 0, 0); __builtin_amdgcn_s_setprio(0); } while (0)
; #define PG8_WAIT_V(n) asm volatile("s_waitcnt vmcnt(" #n ")" ::: "memory")
; #define PG8_WAIT_L(n) asm volatile("s_waitcnt lgkmcnt(" #n ")" ::: "memory")
; #define PG8_BAR __builtin_amdgcn_s_barrier()
; #define PG8_SCHED __builtin_amdgcn_sched_barrier(0)
; template <class Epi, class Sched, bool ALIGN_EPI = false, bool SP2 = false>
; __device__ __forceinline__ void gemm_phase(PG8_LAS unsigned char* lds, const Gemm g, const Sched& S, const Epi& E) {
;     ...
;             PG8_WAIT_V(8); PG8_WAIT_L(0); PG8_BAR; PG8_MMA(1, 0, At, B0); PG8_MMA(1, 1, At, B1); PG8_BAR; PG8_SCHED;
;             PG8_LDB(B0, 1, 0); PG8_LDB(B1, 1, 1); PG8_SCHED; PG8_LDA(At, 1, 0); PG8_STAGE(PG8_SA(0, 1), a2 + hstep, voffA);
;             PG8_WAIT_V(8); PG8_WAIT_L(0); PG8_BAR; PG8_MMA(0, 0, At, B0); PG8_MMA(0, 1, At, B1); PG8_BAR; PG8_SCHED;
	s_setprio 1
	s_waitcnt lgkmcnt(0)
	v_mfma_f32_16x16x32_bf16 v[60:63], v[128:131], v[174:177], v[60:63]
	v_mfma_f32_16x16x32_bf16 v[52:55], v[144:147], v[174:177], v[52:55]
	v_mfma_f32_16x16x32_bf16 v[44:47], v[128:131], v[182:185], v[44:47]
	v_mfma_f32_16x16x32_bf16 v[36:39], v[144:147], v[182:185], v[36:39]
	v_mfma_f32_16x16x32_bf16 v[28:31], v[128:131], v[194:197], v[28:31]
	v_mfma_f32_16x16x32_bf16 v[20:23], v[144:147], v[194:197], v[20:23]
	v_mfma_f32_16x16x32_bf16 v[12:15], v[128:131], v[210:213], v[12:15]
	v_mfma_f32_16x16x32_bf16 v[4:7], v[144:147], v[210:213], v[4:7]
	v_mfma_f32_16x16x32_bf16 v[60:63], v[132:135], v[178:181], v[60:63]
	v_mfma_f32_16x16x32_bf16 v[52:55], v[148:151], v[178:181], v[52:55]
	v_mfma_f32_16x16x32_bf16 v[44:47], v[132:135], v[186:189], v[44:47]
	v_mfma_f32_16x16x32_bf16 v[36:39], v[148:151], v[186:189], v[36:39]
	v_mfma_f32_16x16x32_bf16 v[28:31], v[132:135], v[206:209], v[28:31]
	v_mfma_f32_16x16x32_bf16 v[20:23], v[148:151], v[206:209], v[20:23]
	v_mfma_f32_16x16x32_bf16 v[12:15], v[132:135], v[214:217], v[12:15]
	v_mfma_f32_16x16x32_bf16 v[4:7], v[148:151], v[214:217], v[4:7]
	v_mfma_f32_16x16x32_bf16 v[56:59], v[152:155], v[174:177], v[56:59]
	v_mfma_f32_16x16x32_bf16 v[48:51], v[166:169], v[174:177], v[48:51]
	v_mfma_f32_16x16x32_bf16 v[40:43], v[152:155], v[182:185], v[40:43]
	v_mfma_f32_16x16x32_bf16 v[32:35], v[166:169], v[182:185], v[32:35]
	v_mfma_f32_16x16x32_bf16 v[24:27], v[152:155], v[194:197], v[24:27]
	v_mfma_f32_16x16x32_bf16 v[16:19], v[166:169], v[194:197], v[16:19]
	v_mfma_f32_16x16x32_bf16 v[8:11], v[152:155], v[210:213], v[8:11]
	v_mfma_f32_16x16x32_bf16 v[0:3], v[166:169], v[210:213], v[0:3]
	v_mfma_f32_16x16x32_bf16 v[56:59], v[162:165], v[178:181], v[56:59]
	v_mfma_f32_16x16x32_bf16 v[48:51], v[170:173], v[178:181], v[48:51]
	v_mfma_f32_16x16x32_bf16 v[40:43], v[162:165], v[186:189], v[40:43]
	v_mfma_f32_16x16x32_bf16 v[32:35], v[170:173], v[186:189], v[32:35]
	v_mfma_f32_16x16x32_bf16 v[24:27], v[162:165], v[206:209], v[24:27]
	v_mfma_f32_16x16x32_bf16 v[16:19], v[170:173], v[206:209], v[16:19]
	v_mfma_f32_16x16x32_bf16 v[8:11], v[162:165], v[214:217], v[8:11]
	v_mfma_f32_16x16x32_bf16 v[0:3], v[170:173], v[214:217], v[0:3]
	s_setprio 0
	s_barrier
	s_add_i32 s33, 0, 0x18000
	s_add_i32 s42, 0, 0x1c000
	v_add_u32_e32 v148, s33, v156
	v_add_u32_e32 v160, s42, v156
	ds_read_b128 v[128:131], v148
	ds_read_b128 v[132:135], v148 offset:1024
	ds_read_b128 v[144:147], v148 offset:2048
	ds_read_b128 v[148:151], v148 offset:3072
	ds_read_b128 v[152:155], v160
	ds_read_b128 v[162:165], v160 offset:1024
	ds_read_b128 v[166:169], v160 offset:2048
	ds_read_b128 v[170:173], v160 offset:3072
	s_add_u32 s0, s0, s10
	s_addc_u32 s1, s1, s11
	s_mov_b32 m0, s31
	v_lshl_add_u64 v[228:229], s[0:1], 0, v[142:143]
	ds_read_b128 v[174:177], v157 offset:32768
	ds_read_b128 v[178:181], v157 offset:33792
	ds_read_b128 v[182:185], v157 offset:34816
	ds_read_b128 v[186:189], v157 offset:35840
	ds_read_b128 v[194:197], v157 offset:36864
	ds_read_b128 v[206:209], v157 offset:37888
	ds_read_b128 v[210:213], v157 offset:38912
	ds_read_b128 v[214:217], v157 offset:39936
	global_load_lds_dwordx4 v[228:229], off
	v_lshl_add_u64 v[228:229], s[0:1], 0, v[138:139]
	s_mov_b32 m0, s34
	s_nop 0
	global_load_lds_dwordx4 v[228:229], off
	s_waitcnt vmcnt(8)
	s_waitcnt lgkmcnt(0)
	s_barrier
	s_setprio 1
	s_waitcnt lgkmcnt(0)
	v_mfma_f32_16x16x32_bf16 v[124:127], v[128:131], v[174:177], v[124:127]
	v_mfma_f32_16x16x32_bf16 v[116:119], v[144:147], v[174:177], v[116:119]
	v_mfma_f32_16x16x32_bf16 v[108:111], v[128:131], v[182:185], v[108:111]
	v_mfma_f32_16x16x32_bf16 v[100:103], v[144:147], v[182:185], v[100:103]
	v_mfma_f32_16x16x32_bf16 v[92:95], v[128:131], v[194:197], v[92:95]
	v_mfma_f32_16x16x32_bf16 v[84:87], v[144:147], v[194:197], v[84:87]
	v_mfma_f32_16x16x32_bf16 v[76:79], v[128:131], v[210:213], v[76:79]
	v_mfma_f32_16x16x32_bf16 v[68:71], v[144:147], v[210:213], v[68:71]
	v_mfma_f32_16x16x32_bf16 v[124:127], v[132:135], v[178:181], v[124:127]
	v_mfma_f32_16x16x32_bf16 v[116:119], v[148:151], v[178:181], v[116:119]
	v_mfma_f32_16x16x32_bf16 v[108:111], v[132:135], v[186:189], v[108:111]
	v_mfma_f32_16x16x32_bf16 v[100:103], v[148:151], v[186:189], v[100:103]
	v_mfma_f32_16x16x32_bf16 v[92:95], v[132:135], v[206:209], v[92:95]
	v_mfma_f32_16x16x32_bf16 v[84:87], v[148:151], v[206:209], v[84:87]
	v_mfma_f32_16x16x32_bf16 v[76:79], v[132:135], v[214:217], v[76:79]
	v_mfma_f32_16x16x32_bf16 v[68:71], v[148:151], v[214:217], v[68:71]
	v_mfma_f32_16x16x32_bf16 v[120:123], v[152:155], v[174:177], v[120:123]
	v_mfma_f32_16x16x32_bf16 v[112:115], v[166:169], v[174:177], v[112:115]
	v_mfma_f32_16x16x32_bf16 v[104:107], v[152:155], v[182:185], v[104:107]
	v_mfma_f32_16x16x32_bf16 v[96:99], v[166:169], v[182:185], v[96:99]
	v_mfma_f32_16x16x32_bf16 v[88:91], v[152:155], v[194:197], v[88:91]
	v_mfma_f32_16x16x32_bf16 v[80:83], v[166:169], v[194:197], v[80:83]
	v_mfma_f32_16x16x32_bf16 v[72:75], v[152:155], v[210:213], v[72:75]
	v_mfma_f32_16x16x32_bf16 v[64:67], v[166:169], v[210:213], v[64:67]
	v_mfma_f32_16x16x32_bf16 v[120:123], v[162:165], v[178:181], v[120:123]
	v_mfma_f32_16x16x32_bf16 v[112:115], v[170:173], v[178:181], v[112:115]
	v_mfma_f32_16x16x32_bf16 v[104:107], v[162:165], v[186:189], v[104:107]
	v_mfma_f32_16x16x32_bf16 v[96:99], v[170:173], v[186:189], v[96:99]
	v_mfma_f32_16x16x32_bf16 v[88:91], v[162:165], v[206:209], v[88:91]
	v_mfma_f32_16x16x32_bf16 v[80:83], v[170:173], v[206:209], v[80:83]
	v_mfma_f32_16x16x32_bf16 v[72:75], v[162:165], v[214:217], v[72:75]
	v_mfma_f32_16x16x32_bf16 v[64:67], v[170:173], v[214:217], v[64:67]
	s_setprio 0
	s_barrier
; #define PG8_STAGE(bufoff, gbase, voff) do { _Pragma("unroll") for (int _i = 0; _i < 2; ++_i) \
;         __builtin_amdgcn_global_load_lds((const unsigned*)((const char*)(gbase) + (voff)[_i]), (PG8_LAS unsigned*)(lds + (bufoff) + ldsw + _i * 8192), 16, 0, 0); } while (0)
; #define PG8_LDA(dst, b, h) do { _Pragma("unroll") for (int m = 0; m < 4; ++m) _Pragma("unroll") for (int k = 0; k < 2; ++k) dst[m][k] = *(const PG8_LAS bf16x8*)(lds + PG8_SA(b, h) + aoff + m * 2048 + k * 1024); } while (0)
; #define PG8_MMA(ai, bj, At, Bt) do { __builtin_amdgcn_s_setprio(1); _Pragma("unroll") for (int m = 0; m < 4; ++m) _Pragma("unroll") for (int n = 0; n < 2; ++n) _Pragma("unroll") for (int k = 0; k < 2; ++k) \
;         acc[ai][bj][m][n] = __builtin_amdgcn_mfma_f32_16x16x32_bf16(Bt[n][k], At[m][k], acc[ai][bj][m][n], 0, 0, 0); __builtin_amdgcn_s_setprio(0); } while (0)
; #define PG8_WAIT_V(n) asm volatile("s_waitcnt vmcnt(" #n ")" ::: "memory")
; #define PG8_WAIT_L(n) asm volatile("s_waitcnt lgkmcnt(" #n ")" ::: "memory")
; #define PG8_BAR __builtin_amdgcn_s_barrier()
; #define PG8_SCHED __builtin_amdgcn_sched_barrier(0)
; template <class Epi, class Sched, bool ALIGN_EPI = false, bool SP2 = false>
; __device__ __forceinline__ void gemm_phase(PG8_LAS unsigned char* lds, const Gemm g, const Sched& S, const Epi& E) {
;     ...
;             PG8_LDA(At, 1, 1); PG8_STAGE(PG8_SB(1, 0), b3, voffB); PG8_STAGE(PG8_SB(1, 1), b3 + hstep, voffB); PG8_STAGE(PG8_SA(1, 0), a3, voffA);
;             PG8_WAIT_V(8); PG8_WAIT_L(0); PG8_BAR; PG8_MMA(1, 0, At, B0); PG8_MMA(1, 1, At, B1); PG8_BAR; PG8_SCHED;
	s_add_i32 s0, s33, s28
	v_lshl_add_u64 v[158:159], v[158:159], 0, s[38:39]
	s_mov_b32 m0, s0
	ds_read_b128 v[174:177], v157 offset:49152
	ds_read_b128 v[178:181], v157 offset:50176
	ds_read_b128 v[182:185], v157 offset:51200
	ds_read_b128 v[186:189], v157 offset:52224
	ds_read_b128 v[194:197], v157 offset:53248
	ds_read_b128 v[206:209], v157 offset:54272
	ds_read_b128 v[210:213], v157 offset:55296
	ds_read_b128 v[214:217], v157 offset:56320
	global_load_lds_dwordx4 v[158:159], off
	v_lshl_add_u64 v[158:159], v[218:219], 0, s[38:39]
	s_add_i32 m0, s0, 0x2000
	s_add_i32 s0, s42, s28
	global_load_lds_dwordx4 v[158:159], off
	v_lshl_add_u64 v[158:159], v[220:221], 0, s[38:39]
	s_mov_b32 m0, s0
	s_nop 0
	global_load_lds_dwordx4 v[158:159], off
	v_lshl_add_u64 v[158:159], v[222:223], 0, s[38:39]
	s_add_i32 m0, s0, 0x2000
	s_nop 0
	global_load_lds_dwordx4 v[158:159], off
	v_lshl_add_u64 v[158:159], v[224:225], 0, s[38:39]
	s_mov_b32 m0, s36
	s_nop 0
	global_load_lds_dwordx4 v[158:159], off
	v_lshl_add_u64 v[158:159], v[226:227], 0, s[38:39]
	s_mov_b32 m0, s37
	s_nop 0
	global_load_lds_dwordx4 v[158:159], off
	s_waitcnt vmcnt(8)
	s_waitcnt lgkmcnt(0)
	s_barrier
	s_setprio 1
	s_waitcnt lgkmcnt(0)
	v_mfma_f32_16x16x32_bf16 v[60:63], v[128:131], v[174:177], v[60:63]
	v_mfma_f32_16x16x32_bf16 v[52:55], v[144:147], v[174:177], v[52:55]
	v_mfma_f32_16x16x32_bf16 v[44:47], v[128:131], v[182:185], v[44:47]
	v_mfma_f32_16x16x32_bf16 v[36:39], v[144:147], v[182:185], v[36:39]
	v_mfma_f32_16x16x32_bf16 v[28:31], v[128:131], v[194:197], v[28:31]
	v_mfma_f32_16x16x32_bf16 v[20:23], v[144:147], v[194:197], v[20:23]
	v_mfma_f32_16x16x32_bf16 v[12:15], v[128:131], v[210:213], v[12:15]
	v_mfma_f32_16x16x32_bf16 v[4:7], v[144:147], v[210:213], v[4:7]
	v_mfma_f32_16x16x32_bf16 v[60:63], v[132:135], v[178:181], v[60:63]
	v_mfma_f32_16x16x32_bf16 v[52:55], v[148:151], v[178:181], v[52:55]
	v_mfma_f32_16x16x32_bf16 v[44:47], v[132:135], v[186:189], v[44:47]
	v_mfma_f32_16x16x32_bf16 v[36:39], v[148:151], v[186:189], v[36:39]
	v_mfma_f32_16x16x32_bf16 v[28:31], v[132:135], v[206:209], v[28:31]
	v_mfma_f32_16x16x32_bf16 v[20:23], v[148:151], v[206:209], v[20:23]
	v_mfma_f32_16x16x32_bf16 v[12:15], v[132:135], v[214:217], v[12:15]
	v_mfma_f32_16x16x32_bf16 v[4:7], v[148:151], v[214:217], v[4:7]
	v_mfma_f32_16x16x32_bf16 v[56:59], v[152:155], v[174:177], v[56:59]
	v_mfma_f32_16x16x32_bf16 v[48:51], v[166:169], v[174:177], v[48:51]
	v_mfma_f32_16x16x32_bf16 v[40:43], v[152:155], v[182:185], v[40:43]
	v_mfma_f32_16x16x32_bf16 v[32:35], v[166:169], v[182:185], v[32:35]
	v_mfma_f32_16x16x32_bf16 v[24:27], v[152:155], v[194:197], v[24:27]
	v_mfma_f32_16x16x32_bf16 v[16:19], v[166:169], v[194:197], v[16:19]
	v_mfma_f32_16x16x32_bf16 v[8:11], v[152:155], v[210:213], v[8:11]
	v_mfma_f32_16x16x32_bf16 v[0:3], v[166:169], v[210:213], v[0:3]
	v_mfma_f32_16x16x32_bf16 v[56:59], v[162:165], v[178:181], v[56:59]
	v_mfma_f32_16x16x32_bf16 v[48:51], v[170:173], v[178:181], v[48:51]
	v_mfma_f32_16x16x32_bf16 v[40:43], v[162:165], v[186:189], v[40:43]
	v_mfma_f32_16x16x32_bf16 v[32:35], v[170:173], v[186:189], v[32:35]
	v_mfma_f32_16x16x32_bf16 v[24:27], v[162:165], v[206:209], v[24:27]
	v_mfma_f32_16x16x32_bf16 v[16:19], v[170:173], v[206:209], v[16:19]
	v_mfma_f32_16x16x32_bf16 v[8:11], v[162:165], v[214:217], v[8:11]
	v_mfma_f32_16x16x32_bf16 v[0:3], v[170:173], v[214:217], v[0:3]
	s_setprio 0
	s_barrier
	s_cmp_ge_i32 s78, s35
	s_mov_b32 s0, s78
	s_cbranch_scc0 .LBB0_429

; #define PG8_STAGE(bufoff, gbase, voff) do { _Pragma("unroll") for (int _i = 0; _i < 2; ++_i) \
;         __builtin_amdgcn_global_load_lds((const unsigned*)((const char*)(gbase) + (voff)[_i]), (PG8_LAS unsigned*)(lds + (bufoff) + ldsw + _i * 8192), 16, 0, 0); } while (0)
; #define PG8_LDA(dst, b, h) do { _Pragma("unroll") for (int m = 0; m < 4; ++m) _Pragma("unroll") for (int k = 0; k < 2; ++k) dst[m][k] = *(const PG8_LAS bf16x8*)(lds + PG8_SA(b, h) + aoff + m * 2048 + k * 1024); } while (0)
; #define PG8_LDB(dst, b, h) do { _Pragma("unroll") for (int n = 0; n < 2; ++n) _Pragma("unroll") for (int k = 0; k < 2; ++k) dst[n][k] = *(const PG8_LAS bf16x8*)(lds + PG8_SB(b, h) + boff + n * 2048 + k * 1024); } while (0)
; #define PG8_MMA(ai, bj, At, Bt) do { __builtin_amdgcn_s_setprio(1); _Pragma("unroll") for (int m = 0; m < 4; ++m) _Pragma("unroll") for (int n = 0; n < 2; ++n) _Pragma("unroll") for (int k = 0; k < 2; ++k) \
;         acc[ai][bj][m][n] = __builtin_amdgcn_mfma_f32_16x16x32_bf16(Bt[n][k], At[m][k], acc[ai][bj][m][n], 0, 0, 0); __builtin_amdgcn_s_setprio(0); } while (0)
; #define PG8_WAIT_V(n) asm volatile("s_waitcnt vmcnt(" #n ")" ::: "memory")
; #define PG8_WAIT_L(n) asm volatile("s_waitcnt lgkmcnt(" #n ")" ::: "memory")
; #define PG8_BAR __builtin_amdgcn_s_barrier()
; #define PG8_SCHED __builtin_amdgcn_sched_barrier(0)
; template <class Epi, class Sched, bool ALIGN_EPI = false, bool SP2 = false>
; __device__ __forceinline__ void gemm_phase(PG8_LAS unsigned char* lds, const Gemm g, const Sched& S, const Epi& E) {
;     ...
;             const bool last = (t == nt - 2);
;             const char* a1 = cA + (size_t)(t + 1) * kstep;
;             const char* a2 = last ? nA : cA + (size_t)(t + 2) * kstep; const char* b2 = last ? nB : cB + (size_t)(t + 2) * kstep;
;             const char* a3 = a2 + kstep; const char* b3 = b2 + kstep;
;             if (last && has_next) S.a_ready(nxt);
;             if constexpr (SP2) {
;             PG8_LDB(B0, 0, 0); PG8_LDB(B1, 0, 1); PG8_SCHED; PG8_LDA(At, 0, 0); PG8_STAGE(PG8_SA(1, 1), a1 + hstep, voffA);
;             PG8_WAIT_V(8); PG8_WAIT_L(0); PG8_BAR; PG8_MMA(0, 0, At, B0); PG8_MMA(0, 1, At, B1); PG8_BAR; PG8_SCHED;
;             PG8_LDA(At, 0, 1); PG8_STAGE(PG8_SB(0, 0), b2, voffB); PG8_STAGE(PG8_SB(0, 1), b2 + hstep, voffB); PG8_STAGE(PG8_SA(0, 0), a2, voffA);
.LBB0_454:
	s_add_i32 s44, s22, 2
	s_add_u32 s45, s6, 0x80
	s_addc_u32 s23, s7, 0
	s_add_i32 s48, 0, 0x10000
	s_cmp_eq_u32 s40, s22
	s_cselect_b32 s23, s19, s23
	s_cselect_b32 s22, s18, s45
	v_add_u32_e32 v144, s48, v147
	s_cselect_b32 s47, s21, s25
	s_cselect_b32 s46, s20, s24
	s_add_i32 s45, 0, 0x14000
	ds_read_b128 v[140:143], v144
	ds_read_b128 v[150:153], v144 offset:1024
	ds_read_b128 v[154:157], v144 offset:2048
	ds_read_b128 v[162:165], v144 offset:3072
	v_add_u32_e32 v144, s45, v147
	ds_read_b128 v[166:169], v144
	ds_read_b128 v[170:173], v144 offset:1024
	ds_read_b128 v[174:177], v144 offset:2048
	ds_read_b128 v[178:181], v144 offset:3072
	v_lshl_add_u64 v[144:145], s[6:7], 0, v[136:137]
	s_add_i32 m0, s29, 0xc000
	ds_read_b128 v[182:185], v148
	ds_read_b128 v[186:189], v148 offset:1024
	ds_read_b128 v[194:197], v148 offset:2048
	ds_read_b128 v[206:209], v148 offset:3072
	ds_read_b128 v[210:213], v148 offset:4096
	ds_read_b128 v[214:217], v148 offset:5120
	ds_read_b128 v[218:221], v148 offset:6144
	ds_read_b128 v[222:225], v148 offset:7168
	global_load_lds_dwordx4 v[144:145], off
	v_lshl_add_u64 v[144:145], s[6:7], 0, v[138:139]
	s_add_i32 m0, s29, 0xe000
	s_nop 0
	global_load_lds_dwordx4 v[144:145], off
	s_waitcnt vmcnt(8)
	s_waitcnt lgkmcnt(0)
	s_barrier
	s_setprio 1
	s_waitcnt lgkmcnt(0)
	v_mfma_f32_16x16x32_bf16 v[124:127], v[140:143], v[182:185], v[124:127]
	v_mfma_f32_16x16x32_bf16 v[116:119], v[154:157], v[182:185], v[116:119]
	v_mfma_f32_16x16x32_bf16 v[108:111], v[140:143], v[194:197], v[108:111]
	v_mfma_f32_16x16x32_bf16 v[100:103], v[154:157], v[194:197], v[100:103]
	v_mfma_f32_16x16x32_bf16 v[92:95], v[140:143], v[210:213], v[92:95]
	v_mfma_f32_16x16x32_bf16 v[84:87], v[154:157], v[210:213], v[84:87]
	v_mfma_f32_16x16x32_bf16 v[76:79], v[140:143], v[218:221], v[76:79]
	v_mfma_f32_16x16x32_bf16 v[68:71], v[154:157], v[218:221], v[68:71]
	v_mfma_f32_16x16x32_bf16 v[124:127], v[150:153], v[186:189], v[124:127]
	v_mfma_f32_16x16x32_bf16 v[116:119], v[162:165], v[186:189], v[116:119]
	v_mfma_f32_16x16x32_bf16 v[108:111], v[150:153], v[206:209], v[108:111]
	v_mfma_f32_16x16x32_bf16 v[100:103], v[162:165], v[206:209], v[100:103]
	v_mfma_f32_16x16x32_bf16 v[92:95], v[150:153], v[214:217], v[92:95]
	v_mfma_f32_16x16x32_bf16 v[84:87], v[162:165], v[214:217], v[84:87]
	v_mfma_f32_16x16x32_bf16 v[76:79], v[150:153], v[222:225], v[76:79]
	v_mfma_f32_16x16x32_bf16 v[68:71], v[162:165], v[222:225], v[68:71]
	v_mfma_f32_16x16x32_bf16 v[120:123], v[166:169], v[182:185], v[120:123]
	v_mfma_f32_16x16x32_bf16 v[112:115], v[174:177], v[182:185], v[112:115]
	v_mfma_f32_16x16x32_bf16 v[104:107], v[166:169], v[194:197], v[104:107]
	v_mfma_f32_16x16x32_bf16 v[96:99], v[174:177], v[194:197], v[96:99]
	v_mfma_f32_16x16x32_bf16 v[88:91], v[166:169], v[210:213], v[88:91]
	v_mfma_f32_16x16x32_bf16 v[80:83], v[174:177], v[210:213], v[80:83]
	v_mfma_f32_16x16x32_bf16 v[72:75], v[166:169], v[218:221], v[72:75]
	v_mfma_f32_16x16x32_bf16 v[64:67], v[174:177], v[218:221], v[64:67]
	v_mfma_f32_16x16x32_bf16 v[120:123], v[170:173], v[186:189], v[120:123]
	v_mfma_f32_16x16x32_bf16 v[112:115], v[178:181], v[186:189], v[112:115]
	v_mfma_f32_16x16x32_bf16 v[104:107], v[170:173], v[206:209], v[104:107]
	v_mfma_f32_16x16x32_bf16 v[96:99], v[178:181], v[206:209], v[96:99]
	v_mfma_f32_16x16x32_bf16 v[88:91], v[170:173], v[214:217], v[88:91]
	v_mfma_f32_16x16x32_bf16 v[80:83], v[178:181], v[214:217], v[80:83]
	v_mfma_f32_16x16x32_bf16 v[72:75], v[170:173], v[222:225], v[72:75]
	v_mfma_f32_16x16x32_bf16 v[64:67], v[178:181], v[222:225], v[64:67]
	s_setprio 0
	s_barrier
	s_add_i32 s48, s48, s28
	v_lshl_add_u64 v[144:145], s[46:47], 0, v[132:133]
	s_mov_b32 m0, s48
	ds_read_b128 v[182:185], v148 offset:16384
	ds_read_b128 v[186:189], v148 offset:17408
	ds_read_b128 v[194:197], v148 offset:18432
	ds_read_b128 v[206:209], v148 offset:19456
	ds_read_b128 v[210:213], v148 offset:20480
	ds_read_b128 v[214:217], v148 offset:21504
	ds_read_b128 v[218:221], v148 offset:22528
	ds_read_b128 v[222:225], v148 offset:23552
	global_load_lds_dwordx4 v[144:145], off
	s_add_i32 m0, s48, 0x2000
	v_lshl_add_u64 v[158:159], s[46:47], 0, v[128:129]
	s_add_u32 s46, s46, s2
	s_addc_u32 s47, s47, s3
	s_add_i32 s45, s45, s28
	global_load_lds_dwordx4 v[158:159], off
	v_lshl_add_u64 v[226:227], s[46:47], 0, v[132:133]
	s_mov_b32 m0, s45
	v_lshl_add_u64 v[228:229], s[46:47], 0, v[128:129]
	global_load_lds_dwordx4 v[226:227], off
	s_add_i32 m0, s45, 0x2000
	v_lshl_add_u64 v[230:231], s[22:23], 0, v[134:135]
	global_load_lds_dwordx4 v[228:229], off
	s_mov_b32 m0, s29
	v_lshl_add_u64 v[232:233], s[22:23], 0, v[130:131]
	global_load_lds_dwordx4 v[230:231], off
	s_mov_b32 m0, s30
	s_nop 0
	global_load_lds_dwordx4 v[232:233], off
	s_waitcnt vmcnt(8)
	s_waitcnt lgkmcnt(0)
	s_barrier
; #define PG8_STAGE(bufoff, gbase, voff) do { _Pragma("unroll") for (int _i = 0; _i < 2; ++_i) \
;         __builtin_amdgcn_global_load_lds((const unsigned*)((const char*)(gbase) + (voff)[_i]), (PG8_LAS unsigned*)(lds + (bufoff) + ldsw + _i * 8192), 16, 0, 0); } while (0)
; #define PG8_LDA(dst, b, h) do { _Pragma("unroll") for (int m = 0; m < 4; ++m) _Pragma("unroll") for (int k = 0; k < 2; ++k) dst[m][k] = *(const PG8_LAS bf16x8*)(lds + PG8_SA(b, h) + aoff + m * 2048 + k * 1024); } while (0)
; #define PG8_LDB(dst, b, h) do { _Pragma("unroll") for (int n = 0; n < 2; ++n) _Pragma("unroll") for (int k = 0; k < 2; ++k) dst[n][k] = *(const PG8_LAS bf16x8*)(lds + PG8_SB(b, h) + boff + n * 2048 + k * 1024); } while (0)
; #define PG8_MMA(ai, bj, At, Bt) do { __builtin_amdgcn_s_setprio(1); _Pragma("unroll") for (int m = 0; m < 4; ++m) _Pragma("unroll") for (int n = 0; n < 2; ++n) _Pragma("unroll") for (int k = 0; k < 2; ++k) \
;         acc[ai][bj][m][n] = __builtin_amdgcn_mfma_f32_16x16x32_bf16(Bt[n][k], At[m][k], acc[ai][bj][m][n], 0, 0, 0); __builtin_amdgcn_s_setprio(0); } while (0)
; #define PG8_WAIT_V(n) asm volatile("s_waitcnt vmcnt(" #n ")" ::: "memory")
; #define PG8_WAIT_L(n) asm volatile("s_waitcnt lgkmcnt(" #n ")" ::: "memory")
; #define PG8_BAR __builtin_amdgcn_s_barrier()
; #define PG8_SCHED __builtin_amdgcn_sched_barrier(0)
; template <class Epi, class Sched, bool ALIGN_EPI = false, bool SP2 = false>
; __device__ __forceinline__ void gemm_phase(PG8_LAS unsigned char* lds, const Gemm g, const Sched& S, const Epi& E) {
;     ...
;             PG8_WAIT_V(8); PG8_WAIT_L(0); PG8_BAR; PG8_MMA(1, 0, At, B0); PG8_MMA(1, 1, At, B1); PG8_BAR; PG8_SCHED;
;             PG8_LDB(B0, 1, 0); PG8_LDB(B1, 1, 1); PG8_SCHED; PG8_LDA(At, 1, 0); PG8_STAGE(PG8_SA(0, 1), a2 + hstep, voffA);
;             PG8_WAIT_V(8); PG8_WAIT_L(0); PG8_BAR; PG8_MMA(0, 0, At, B0); PG8_MMA(0, 1, At, B1); PG8_BAR; PG8_SCHED;
	s_setprio 1
	s_waitcnt lgkmcnt(0)
	v_mfma_f32_16x16x32_bf16 v[60:63], v[140:143], v[182:185], v[60:63]
	v_mfma_f32_16x16x32_bf16 v[52:55], v[154:157], v[182:185], v[52:55]
	v_mfma_f32_16x16x32_bf16 v[44:47], v[140:143], v[194:197], v[44:47]
	v_mfma_f32_16x16x32_bf16 v[36:39], v[154:157], v[194:197], v[36:39]
	v_mfma_f32_16x16x32_bf16 v[28:31], v[140:143], v[210:213], v[28:31]
	v_mfma_f32_16x16x32_bf16 v[20:23], v[154:157], v[210:213], v[20:23]
	v_mfma_f32_16x16x32_bf16 v[12:15], v[140:143], v[218:221], v[12:15]
	v_mfma_f32_16x16x32_bf16 v[4:7], v[154:157], v[218:221], v[4:7]
	v_mfma_f32_16x16x32_bf16 v[60:63], v[150:153], v[186:189], v[60:63]
	v_mfma_f32_16x16x32_bf16 v[52:55], v[162:165], v[186:189], v[52:55]
	v_mfma_f32_16x16x32_bf16 v[44:47], v[150:153], v[206:209], v[44:47]
	v_mfma_f32_16x16x32_bf16 v[36:39], v[162:165], v[206:209], v[36:39]
	v_mfma_f32_16x16x32_bf16 v[28:31], v[150:153], v[214:217], v[28:31]
	v_mfma_f32_16x16x32_bf16 v[20:23], v[162:165], v[214:217], v[20:23]
	v_mfma_f32_16x16x32_bf16 v[12:15], v[150:153], v[222:225], v[12:15]
	v_mfma_f32_16x16x32_bf16 v[4:7], v[162:165], v[222:225], v[4:7]
	v_mfma_f32_16x16x32_bf16 v[56:59], v[166:169], v[182:185], v[56:59]
	v_mfma_f32_16x16x32_bf16 v[48:51], v[174:177], v[182:185], v[48:51]
	v_mfma_f32_16x16x32_bf16 v[40:43], v[166:169], v[194:197], v[40:43]
	v_mfma_f32_16x16x32_bf16 v[32:35], v[174:177], v[194:197], v[32:35]
	v_mfma_f32_16x16x32_bf16 v[24:27], v[166:169], v[210:213], v[24:27]
	v_mfma_f32_16x16x32_bf16 v[16:19], v[174:177], v[210:213], v[16:19]
	v_mfma_f32_16x16x32_bf16 v[8:11], v[166:169], v[218:221], v[8:11]
	v_mfma_f32_16x16x32_bf16 v[0:3], v[174:177], v[218:221], v[0:3]
	v_mfma_f32_16x16x32_bf16 v[56:59], v[170:173], v[186:189], v[56:59]
	v_mfma_f32_16x16x32_bf16 v[48:51], v[178:181], v[186:189], v[48:51]
	v_mfma_f32_16x16x32_bf16 v[40:43], v[170:173], v[206:209], v[40:43]
	v_mfma_f32_16x16x32_bf16 v[32:35], v[178:181], v[206:209], v[32:35]
	v_mfma_f32_16x16x32_bf16 v[24:27], v[170:173], v[214:217], v[24:27]
	v_mfma_f32_16x16x32_bf16 v[16:19], v[178:181], v[214:217], v[16:19]
	v_mfma_f32_16x16x32_bf16 v[8:11], v[170:173], v[222:225], v[8:11]
	v_mfma_f32_16x16x32_bf16 v[0:3], v[178:181], v[222:225], v[0:3]
	s_setprio 0
	s_barrier
	s_add_i32 s45, 0, 0x18000
	v_add_u32_e32 v146, s45, v147
	s_add_i32 s46, 0, 0x1c000
	ds_read_b128 v[140:143], v146
	ds_read_b128 v[150:153], v146 offset:1024
	ds_read_b128 v[154:157], v146 offset:2048
	ds_read_b128 v[162:165], v146 offset:3072
	v_add_u32_e32 v146, s46, v147
	ds_read_b128 v[166:169], v146
	ds_read_b128 v[170:173], v146 offset:1024
	ds_read_b128 v[174:177], v146 offset:2048
	ds_read_b128 v[178:181], v146 offset:3072
	s_add_u32 s22, s22, s2
	s_addc_u32 s23, s23, s3
	s_mov_b32 m0, s31
	v_lshl_add_u64 v[234:235], s[22:23], 0, v[134:135]
	ds_read_b128 v[182:185], v148 offset:32768
	ds_read_b128 v[186:189], v148 offset:33792
	ds_read_b128 v[194:197], v148 offset:34816
	ds_read_b128 v[206:209], v148 offset:35840
	ds_read_b128 v[210:213], v148 offset:36864
	ds_read_b128 v[214:217], v148 offset:37888
	ds_read_b128 v[218:221], v148 offset:38912
	ds_read_b128 v[222:225], v148 offset:39936
	global_load_lds_dwordx4 v[234:235], off
	v_lshl_add_u64 v[234:235], s[22:23], 0, v[130:131]
	s_mov_b32 m0, s34
	s_nop 0
	global_load_lds_dwordx4 v[234:235], off
	s_waitcnt vmcnt(8)
	s_waitcnt lgkmcnt(0)
	s_barrier
	s_setprio 1
	s_waitcnt lgkmcnt(0)
	v_mfma_f32_16x16x32_bf16 v[124:127], v[140:143], v[182:185], v[124:127]
	v_mfma_f32_16x16x32_bf16 v[116:119], v[154:157], v[182:185], v[116:119]
	v_mfma_f32_16x16x32_bf16 v[108:111], v[140:143], v[194:197], v[108:111]
	v_mfma_f32_16x16x32_bf16 v[100:103], v[154:157], v[194:197], v[100:103]
	v_mfma_f32_16x16x32_bf16 v[92:95], v[140:143], v[210:213], v[92:95]
	v_mfma_f32_16x16x32_bf16 v[84:87], v[154:157], v[210:213], v[84:87]
	v_mfma_f32_16x16x32_bf16 v[76:79], v[140:143], v[218:221], v[76:79]
	v_mfma_f32_16x16x32_bf16 v[68:71], v[154:157], v[218:221], v[68:71]
	v_mfma_f32_16x16x32_bf16 v[124:127], v[150:153], v[186:189], v[124:127]
	v_mfma_f32_16x16x32_bf16 v[116:119], v[162:165], v[186:189], v[116:119]
	v_mfma_f32_16x16x32_bf16 v[108:111], v[150:153], v[206:209], v[108:111]
	v_mfma_f32_16x16x32_bf16 v[100:103], v[162:165], v[206:209], v[100:103]
	v_mfma_f32_16x16x32_bf16 v[92:95], v[150:153], v[214:217], v[92:95]
	v_mfma_f32_16x16x32_bf16 v[84:87], v[162:165], v[214:217], v[84:87]
	v_mfma_f32_16x16x32_bf16 v[76:79], v[150:153], v[222:225], v[76:79]
	v_mfma_f32_16x16x32_bf16 v[68:71], v[162:165], v[222:225], v[68:71]
	v_mfma_f32_16x16x32_bf16 v[120:123], v[166:169], v[182:185], v[120:123]
	v_mfma_f32_16x16x32_bf16 v[112:115], v[174:177], v[182:185], v[112:115]
	v_mfma_f32_16x16x32_bf16 v[104:107], v[166:169], v[194:197], v[104:107]
	v_mfma_f32_16x16x32_bf16 v[96:99], v[174:177], v[194:197], v[96:99]
	v_mfma_f32_16x16x32_bf16 v[88:91], v[166:169], v[210:213], v[88:91]
	v_mfma_f32_16x16x32_bf16 v[80:83], v[174:177], v[210:213], v[80:83]
	v_mfma_f32_16x16x32_bf16 v[72:75], v[166:169], v[218:221], v[72:75]
	v_mfma_f32_16x16x32_bf16 v[64:67], v[174:177], v[218:221], v[64:67]
	v_mfma_f32_16x16x32_bf16 v[120:123], v[170:173], v[186:189], v[120:123]
	v_mfma_f32_16x16x32_bf16 v[112:115], v[178:181], v[186:189], v[112:115]
	v_mfma_f32_16x16x32_bf16 v[104:107], v[170:173], v[206:209], v[104:107]
	v_mfma_f32_16x16x32_bf16 v[96:99], v[178:181], v[206:209], v[96:99]
	v_mfma_f32_16x16x32_bf16 v[88:91], v[170:173], v[214:217], v[88:91]
	v_mfma_f32_16x16x32_bf16 v[80:83], v[178:181], v[214:217], v[80:83]
	v_mfma_f32_16x16x32_bf16 v[72:75], v[170:173], v[222:225], v[72:75]
	v_mfma_f32_16x16x32_bf16 v[64:67], v[178:181], v[222:225], v[64:67]
	s_setprio 0
	s_barrier
; #define PG8_STAGE(bufoff, gbase, voff) do { _Pragma("unroll") for (int _i = 0; _i < 2; ++_i) \
;         __builtin_amdgcn_global_load_lds((const unsigned*)((const char*)(gbase) + (voff)[_i]), (PG8_LAS unsigned*)(lds + (bufoff) + ldsw + _i * 8192), 16, 0, 0); } while (0)
; #define PG8_LDA(dst, b, h) do { _Pragma("unroll") for (int m = 0; m < 4; ++m) _Pragma("unroll") for (int k = 0; k < 2; ++k) dst[m][k] = *(const PG8_LAS bf16x8*)(lds + PG8_SA(b, h) + aoff + m * 2048 + k * 1024); } while (0)
; #define PG8_MMA(ai, bj, At, Bt) do { __builtin_amdgcn_s_setprio(1); _Pragma("unroll") for (int m = 0; m < 4; ++m) _Pragma("unroll") for (int n = 0; n < 2; ++n) _Pragma("unroll") for (int k = 0; k < 2; ++k) \
;         acc[ai][bj][m][n] = __builtin_amdgcn_mfma_f32_16x16x32_bf16(Bt[n][k], At[m][k], acc[ai][bj][m][n], 0, 0, 0); __builtin_amdgcn_s_setprio(0); } while (0)
; #define PG8_WAIT_V(n) asm volatile("s_waitcnt vmcnt(" #n ")" ::: "memory")
; #define PG8_WAIT_L(n) asm volatile("s_waitcnt lgkmcnt(" #n ")" ::: "memory")
; #define PG8_BAR __builtin_amdgcn_s_barrier()
; #define PG8_SCHED __builtin_amdgcn_sched_barrier(0)
; template <class Epi, class Sched, bool ALIGN_EPI = false, bool SP2 = false>
; __device__ __forceinline__ void gemm_phase(PG8_LAS unsigned char* lds, const Gemm g, const Sched& S, const Epi& E) {
;     ...
;             PG8_LDA(At, 1, 1); PG8_STAGE(PG8_SB(1, 0), b3, voffB); PG8_STAGE(PG8_SB(1, 1), b3 + hstep, voffB); PG8_STAGE(PG8_SA(1, 0), a3, voffA);
;             PG8_WAIT_V(8); PG8_WAIT_L(0); PG8_BAR; PG8_MMA(1, 0, At, B0); PG8_MMA(1, 1, At, B1); PG8_BAR; PG8_SCHED;
	s_add_i32 s22, s45, s28
	v_lshl_add_u64 v[144:145], v[144:145], 0, s[38:39]
	s_mov_b32 m0, s22
	ds_read_b128 v[182:185], v148 offset:49152
	ds_read_b128 v[186:189], v148 offset:50176
	ds_read_b128 v[194:197], v148 offset:51200
	ds_read_b128 v[206:209], v148 offset:52224
	ds_read_b128 v[210:213], v148 offset:53248
	ds_read_b128 v[214:217], v148 offset:54272
	ds_read_b128 v[218:221], v148 offset:55296
	ds_read_b128 v[222:225], v148 offset:56320
	global_load_lds_dwordx4 v[144:145], off
	v_lshl_add_u64 v[144:145], v[158:159], 0, s[38:39]
	s_add_i32 m0, s22, 0x2000
	s_add_i32 s22, s46, s28
	global_load_lds_dwordx4 v[144:145], off
	v_lshl_add_u64 v[144:145], v[226:227], 0, s[38:39]
	s_mov_b32 m0, s22
	s_nop 0
	global_load_lds_dwordx4 v[144:145], off
	v_lshl_add_u64 v[144:145], v[228:229], 0, s[38:39]
	s_add_i32 m0, s22, 0x2000
	s_nop 0
	global_load_lds_dwordx4 v[144:145], off
	v_lshl_add_u64 v[144:145], v[230:231], 0, s[38:39]
	s_mov_b32 m0, s35
	s_nop 0
	global_load_lds_dwordx4 v[144:145], off
	v_lshl_add_u64 v[144:145], v[232:233], 0, s[38:39]
	s_mov_b32 m0, s36
	s_nop 0
	global_load_lds_dwordx4 v[144:145], off
	s_waitcnt vmcnt(8)
	s_waitcnt lgkmcnt(0)
	s_barrier
	s_setprio 1
	s_waitcnt lgkmcnt(0)
	v_mfma_f32_16x16x32_bf16 v[60:63], v[140:143], v[182:185], v[60:63]
	v_mfma_f32_16x16x32_bf16 v[52:55], v[154:157], v[182:185], v[52:55]
	v_mfma_f32_16x16x32_bf16 v[44:47], v[140:143], v[194:197], v[44:47]
	v_mfma_f32_16x16x32_bf16 v[36:39], v[154:157], v[194:197], v[36:39]
	v_mfma_f32_16x16x32_bf16 v[28:31], v[140:143], v[210:213], v[28:31]
	v_mfma_f32_16x16x32_bf16 v[20:23], v[154:157], v[210:213], v[20:23]
	v_mfma_f32_16x16x32_bf16 v[12:15], v[140:143], v[218:221], v[12:15]
	v_mfma_f32_16x16x32_bf16 v[4:7], v[154:157], v[218:221], v[4:7]
	v_mfma_f32_16x16x32_bf16 v[60:63], v[150:153], v[186:189], v[60:63]
	v_mfma_f32_16x16x32_bf16 v[52:55], v[162:165], v[186:189], v[52:55]
	v_mfma_f32_16x16x32_bf16 v[44:47], v[150:153], v[206:209], v[44:47]
	v_mfma_f32_16x16x32_bf16 v[36:39], v[162:165], v[206:209], v[36:39]
	v_mfma_f32_16x16x32_bf16 v[28:31], v[150:153], v[214:217], v[28:31]
	v_mfma_f32_16x16x32_bf16 v[20:23], v[162:165], v[214:217], v[20:23]
	v_mfma_f32_16x16x32_bf16 v[12:15], v[150:153], v[222:225], v[12:15]
	v_mfma_f32_16x16x32_bf16 v[4:7], v[162:165], v[222:225], v[4:7]
	v_mfma_f32_16x16x32_bf16 v[56:59], v[166:169], v[182:185], v[56:59]
	v_mfma_f32_16x16x32_bf16 v[48:51], v[174:177], v[182:185], v[48:51]
	v_mfma_f32_16x16x32_bf16 v[40:43], v[166:169], v[194:197], v[40:43]
	v_mfma_f32_16x16x32_bf16 v[32:35], v[174:177], v[194:197], v[32:35]
	v_mfma_f32_16x16x32_bf16 v[24:27], v[166:169], v[210:213], v[24:27]
	v_mfma_f32_16x16x32_bf16 v[16:19], v[174:177], v[210:213], v[16:19]
	v_mfma_f32_16x16x32_bf16 v[8:11], v[166:169], v[218:221], v[8:11]
	v_mfma_f32_16x16x32_bf16 v[0:3], v[174:177], v[218:221], v[0:3]
	v_mfma_f32_16x16x32_bf16 v[56:59], v[170:173], v[186:189], v[56:59]
	v_mfma_f32_16x16x32_bf16 v[48:51], v[178:181], v[186:189], v[48:51]
	v_mfma_f32_16x16x32_bf16 v[40:43], v[170:173], v[206:209], v[40:43]
	v_mfma_f32_16x16x32_bf16 v[32:35], v[178:181], v[206:209], v[32:35]
	v_mfma_f32_16x16x32_bf16 v[24:27], v[170:173], v[214:217], v[24:27]
	v_mfma_f32_16x16x32_bf16 v[16:19], v[178:181], v[214:217], v[16:19]
	v_mfma_f32_16x16x32_bf16 v[8:11], v[170:173], v[222:225], v[8:11]
	v_mfma_f32_16x16x32_bf16 v[0:3], v[178:181], v[222:225], v[0:3]
	s_setprio 0
	s_barrier
	s_add_u32 s6, s6, 0x100
	s_addc_u32 s7, s7, 0
	s_add_u32 s24, s24, 0x100
	s_addc_u32 s25, s25, 0
	s_cmp_ge_i32 s44, s37
	s_mov_b32 s22, s44
	s_cbranch_scc0 .LBB0_454

; #define PG8_STAGE(bufoff, gbase, voff) do { _Pragma("unroll") for (int _i = 0; _i < 2; ++_i) \
;         __builtin_amdgcn_global_load_lds((const unsigned*)((const char*)(gbase) + (voff)[_i]), (PG8_LAS unsigned*)(lds + (bufoff) + ldsw + _i * 8192), 16, 0, 0); } while (0)
; #define PG8_LDA(dst, b, h) do { _Pragma("unroll") for (int m = 0; m < 4; ++m) _Pragma("unroll") for (int k = 0; k < 2; ++k) dst[m][k] = *(const PG8_LAS bf16x8*)(lds + PG8_SA(b, h) + aoff + m * 2048 + k * 1024); } while (0)
; #define PG8_LDB(dst, b, h) do { _Pragma("unroll") for (int n = 0; n < 2; ++n) _Pragma("unroll") for (int k = 0; k < 2; ++k) dst[n][k] = *(const PG8_LAS bf16x8*)(lds + PG8_SB(b, h) + boff + n * 2048 + k * 1024); } while (0)
; #define PG8_MMA(ai, bj, At, Bt) do { __builtin_amdgcn_s_setprio(1); _Pragma("unroll") for (int m = 0; m < 4; ++m) _Pragma("unroll") for (int n = 0; n < 2; ++n) _Pragma("unroll") for (int k = 0; k < 2; ++k) \
;         acc[ai][bj][m][n] = __builtin_amdgcn_mfma_f32_16x16x32_bf16(Bt[n][k], At[m][k], acc[ai][bj][m][n], 0, 0, 0); __builtin_amdgcn_s_setprio(0); } while (0)
; #define PG8_WAIT_V(n) asm volatile("s_waitcnt vmcnt(" #n ")" ::: "memory")
; #define PG8_WAIT_L(n) asm volatile("s_waitcnt lgkmcnt(" #n ")" ::: "memory")
; #define PG8_BAR __builtin_amdgcn_s_barrier()
; #define PG8_SCHED __builtin_amdgcn_sched_barrier(0)
; template <class Epi, class Sched, bool ALIGN_EPI = false, bool SP2 = false>
; __device__ __forceinline__ void gemm_phase(PG8_LAS unsigned char* lds, const Gemm g, const Sched& S, const Epi& E) {
;     ...
;             const bool last = (t == nt - 2);
;             const char* a1 = cA + (size_t)(t + 1) * kstep;
;             const char* a2 = last ? nA : cA + (size_t)(t + 2) * kstep; const char* b2 = last ? nB : cB + (size_t)(t + 2) * kstep;
;             const char* a3 = a2 + kstep; const char* b3 = b2 + kstep;
;             if (last && has_next) S.a_ready(nxt);
;             if constexpr (SP2) {
;             PG8_LDB(B0, 0, 0); PG8_LDB(B1, 0, 1); PG8_SCHED; PG8_LDA(At, 0, 0); PG8_STAGE(PG8_SA(1, 1), a1 + hstep, voffA);
;             PG8_WAIT_V(8); PG8_WAIT_L(0); PG8_BAR; PG8_MMA(0, 0, At, B0); PG8_MMA(0, 1, At, B1); PG8_BAR; PG8_SCHED;
;             PG8_LDA(At, 0, 1); PG8_STAGE(PG8_SB(0, 0), b2, voffB); PG8_STAGE(PG8_SB(0, 1), b2 + hstep, voffB); PG8_STAGE(PG8_SA(0, 0), a2, voffA);
.LBB0_945:
	s_add_u32 s6, s4, 0xfffc0080
	s_addc_u32 s7, s5, -1
	s_add_i32 s49, 0, 0x10000
	s_cmp_eq_u32 s48, 12
	s_cselect_b32 s23, s15, s7
	s_cselect_b32 s22, s44, s6
	s_cselect_b32 s7, s17, s47
	s_cselect_b32 s6, s45, s46
	s_add_i32 s52, 0, 0x14000
	v_add_u32_e32 v56, s49, v205
	v_add_u32_e32 v158, s52, v205
	ds_read_b128 v[40:43], v56
	ds_read_b128 v[44:47], v56 offset:1024
	ds_read_b128 v[52:55], v56 offset:2048
	ds_read_b128 v[56:59], v56 offset:3072
	ds_read_b128 v[144:147], v158
	ds_read_b128 v[162:165], v158 offset:1024
	ds_read_b128 v[166:169], v158 offset:2048
	ds_read_b128 v[170:173], v158 offset:3072
	v_lshl_add_u64 v[158:159], s[4:5], 0, v[154:155]
	s_add_i32 m0, s29, 0xc000
	ds_read_b128 v[174:177], v206
	ds_read_b128 v[178:181], v206 offset:1024
	ds_read_b128 v[182:185], v206 offset:2048
	ds_read_b128 v[186:189], v206 offset:3072
	ds_read_b128 v[194:197], v206 offset:4096
	ds_read_b128 v[208:211], v206 offset:5120
	ds_read_b128 v[212:215], v206 offset:6144
	ds_read_b128 v[216:219], v206 offset:7168
	global_load_lds_dwordx4 v[158:159], off
	v_lshl_add_u64 v[158:159], s[4:5], 0, v[156:157]
	s_add_i32 m0, s29, 0xe000
	s_nop 0
	global_load_lds_dwordx4 v[158:159], off
	s_waitcnt vmcnt(8)
	s_waitcnt lgkmcnt(0)
	s_barrier
	s_setprio 1
	s_waitcnt lgkmcnt(0)
	v_mfma_f32_16x16x32_bf16 v[140:143], v[40:43], v[174:177], v[140:143]
	v_mfma_f32_16x16x32_bf16 v[136:139], v[52:55], v[174:177], v[136:139]
	v_mfma_f32_16x16x32_bf16 v[124:127], v[40:43], v[182:185], v[124:127]
	v_mfma_f32_16x16x32_bf16 v[120:123], v[52:55], v[182:185], v[120:123]
	v_mfma_f32_16x16x32_bf16 v[108:111], v[40:43], v[194:197], v[108:111]
	v_mfma_f32_16x16x32_bf16 v[104:107], v[52:55], v[194:197], v[104:107]
	v_mfma_f32_16x16x32_bf16 v[92:95], v[40:43], v[212:215], v[92:95]
	v_mfma_f32_16x16x32_bf16 v[88:91], v[52:55], v[212:215], v[88:91]
	v_mfma_f32_16x16x32_bf16 v[140:143], v[44:47], v[178:181], v[140:143]
	v_mfma_f32_16x16x32_bf16 v[136:139], v[56:59], v[178:181], v[136:139]
	v_mfma_f32_16x16x32_bf16 v[124:127], v[44:47], v[186:189], v[124:127]
	v_mfma_f32_16x16x32_bf16 v[120:123], v[56:59], v[186:189], v[120:123]
	v_mfma_f32_16x16x32_bf16 v[108:111], v[44:47], v[208:211], v[108:111]
	v_mfma_f32_16x16x32_bf16 v[104:107], v[56:59], v[208:211], v[104:107]
	v_mfma_f32_16x16x32_bf16 v[92:95], v[44:47], v[216:219], v[92:95]
	v_mfma_f32_16x16x32_bf16 v[88:91], v[56:59], v[216:219], v[88:91]
	v_mfma_f32_16x16x32_bf16 v[132:135], v[144:147], v[174:177], v[132:135]
	v_mfma_f32_16x16x32_bf16 v[128:131], v[166:169], v[174:177], v[128:131]
	v_mfma_f32_16x16x32_bf16 v[116:119], v[144:147], v[182:185], v[116:119]
	v_mfma_f32_16x16x32_bf16 v[112:115], v[166:169], v[182:185], v[112:115]
	v_mfma_f32_16x16x32_bf16 v[100:103], v[144:147], v[194:197], v[100:103]
	v_mfma_f32_16x16x32_bf16 v[96:99], v[166:169], v[194:197], v[96:99]
	v_mfma_f32_16x16x32_bf16 v[84:87], v[144:147], v[212:215], v[84:87]
	v_mfma_f32_16x16x32_bf16 v[80:83], v[166:169], v[212:215], v[80:83]
	v_mfma_f32_16x16x32_bf16 v[132:135], v[162:165], v[178:181], v[132:135]
	v_mfma_f32_16x16x32_bf16 v[128:131], v[170:173], v[178:181], v[128:131]
	v_mfma_f32_16x16x32_bf16 v[116:119], v[162:165], v[186:189], v[116:119]
	v_mfma_f32_16x16x32_bf16 v[112:115], v[170:173], v[186:189], v[112:115]
	v_mfma_f32_16x16x32_bf16 v[100:103], v[162:165], v[208:211], v[100:103]
	v_mfma_f32_16x16x32_bf16 v[96:99], v[170:173], v[208:211], v[96:99]
	v_mfma_f32_16x16x32_bf16 v[84:87], v[162:165], v[216:219], v[84:87]
	v_mfma_f32_16x16x32_bf16 v[80:83], v[170:173], v[216:219], v[80:83]
	s_setprio 0
	s_barrier
	s_add_i32 s49, s49, s28
	v_lshl_add_u64 v[158:159], s[6:7], 0, v[160:161]
	s_mov_b32 m0, s49
	ds_read_b128 v[174:177], v206 offset:16384
	ds_read_b128 v[178:181], v206 offset:17408
	ds_read_b128 v[182:185], v206 offset:18432
	ds_read_b128 v[186:189], v206 offset:19456
	ds_read_b128 v[194:197], v206 offset:20480
	ds_read_b128 v[208:211], v206 offset:21504
	ds_read_b128 v[212:215], v206 offset:22528
	ds_read_b128 v[216:219], v206 offset:23552
	global_load_lds_dwordx4 v[158:159], off
	s_add_i32 m0, s49, 0x2000
	s_add_u32 s50, s6, 0x40000
	v_lshl_add_u64 v[220:221], s[6:7], 0, v[148:149]
	s_addc_u32 s51, s7, 0
	s_add_i32 s49, s52, s28
	global_load_lds_dwordx4 v[220:221], off
	v_lshl_add_u64 v[222:223], s[50:51], 0, v[160:161]
	s_mov_b32 m0, s49
	v_lshl_add_u64 v[224:225], s[22:23], 0, v[150:151]
	global_load_lds_dwordx4 v[222:223], off
	v_lshl_add_u64 v[222:223], s[50:51], 0, v[148:149]
	s_add_i32 m0, s49, 0x2000
	s_nop 0
	global_load_lds_dwordx4 v[222:223], off
	v_lshl_add_u64 v[222:223], s[22:23], 0, v[152:153]
	s_mov_b32 m0, s29
	s_nop 0
	global_load_lds_dwordx4 v[222:223], off
	s_mov_b32 m0, s30
	s_nop 0
	global_load_lds_dwordx4 v[224:225], off
	s_waitcnt vmcnt(8)
	s_waitcnt lgkmcnt(0)
	s_barrier
; #define PG8_STAGE(bufoff, gbase, voff) do { _Pragma("unroll") for (int _i = 0; _i < 2; ++_i) \
;         __builtin_amdgcn_global_load_lds((const unsigned*)((const char*)(gbase) + (voff)[_i]), (PG8_LAS unsigned*)(lds + (bufoff) + ldsw + _i * 8192), 16, 0, 0); } while (0)
; #define PG8_LDA(dst, b, h) do { _Pragma("unroll") for (int m = 0; m < 4; ++m) _Pragma("unroll") for (int k = 0; k < 2; ++k) dst[m][k] = *(const PG8_LAS bf16x8*)(lds + PG8_SA(b, h) + aoff + m * 2048 + k * 1024); } while (0)
; #define PG8_LDB(dst, b, h) do { _Pragma("unroll") for (int n = 0; n < 2; ++n) _Pragma("unroll") for (int k = 0; k < 2; ++k) dst[n][k] = *(const PG8_LAS bf16x8*)(lds + PG8_SB(b, h) + boff + n * 2048 + k * 1024); } while (0)
; #define PG8_MMA(ai, bj, At, Bt) do { __builtin_amdgcn_s_setprio(1); _Pragma("unroll") for (int m = 0; m < 4; ++m) _Pragma("unroll") for (int n = 0; n < 2; ++n) _Pragma("unroll") for (int k = 0; k < 2; ++k) \
;         acc[ai][bj][m][n] = __builtin_amdgcn_mfma_f32_16x16x32_bf16(Bt[n][k], At[m][k], acc[ai][bj][m][n], 0, 0, 0); __builtin_amdgcn_s_setprio(0); } while (0)
; #define PG8_WAIT_V(n) asm volatile("s_waitcnt vmcnt(" #n ")" ::: "memory")
; #define PG8_WAIT_L(n) asm volatile("s_waitcnt lgkmcnt(" #n ")" ::: "memory")
; #define PG8_BAR __builtin_amdgcn_s_barrier()
; #define PG8_SCHED __builtin_amdgcn_sched_barrier(0)
; template <class Epi, class Sched, bool ALIGN_EPI = false, bool SP2 = false>
; __device__ __forceinline__ void gemm_phase(PG8_LAS unsigned char* lds, const Gemm g, const Sched& S, const Epi& E) {
;     ...
;             PG8_WAIT_V(8); PG8_WAIT_L(0); PG8_BAR; PG8_MMA(1, 0, At, B0); PG8_MMA(1, 1, At, B1); PG8_BAR; PG8_SCHED;
;             PG8_LDB(B0, 1, 0); PG8_LDB(B1, 1, 1); PG8_SCHED; PG8_LDA(At, 1, 0); PG8_STAGE(PG8_SA(0, 1), a2 + hstep, voffA);
;             PG8_WAIT_V(8); PG8_WAIT_L(0); PG8_BAR; PG8_MMA(0, 0, At, B0); PG8_MMA(0, 1, At, B1); PG8_BAR; PG8_SCHED;
	s_setprio 1
	s_waitcnt lgkmcnt(0)
	v_mfma_f32_16x16x32_bf16 v[76:79], v[40:43], v[174:177], v[76:79]
	v_mfma_f32_16x16x32_bf16 v[72:75], v[52:55], v[174:177], v[72:75]
	v_mfma_f32_16x16x32_bf16 v[60:63], v[40:43], v[182:185], v[60:63]
	v_mfma_f32_16x16x32_bf16 v[48:51], v[52:55], v[182:185], v[48:51]
	v_mfma_f32_16x16x32_bf16 v[28:31], v[40:43], v[194:197], v[28:31]
	v_mfma_f32_16x16x32_bf16 v[24:27], v[52:55], v[194:197], v[24:27]
	v_mfma_f32_16x16x32_bf16 v[12:15], v[40:43], v[212:215], v[12:15]
	v_mfma_f32_16x16x32_bf16 v[8:11], v[52:55], v[212:215], v[8:11]
	v_mfma_f32_16x16x32_bf16 v[76:79], v[44:47], v[178:181], v[76:79]
	v_mfma_f32_16x16x32_bf16 v[72:75], v[56:59], v[178:181], v[72:75]
	v_mfma_f32_16x16x32_bf16 v[60:63], v[44:47], v[186:189], v[60:63]
	v_mfma_f32_16x16x32_bf16 v[48:51], v[56:59], v[186:189], v[48:51]
	v_mfma_f32_16x16x32_bf16 v[28:31], v[44:47], v[208:211], v[28:31]
	v_mfma_f32_16x16x32_bf16 v[24:27], v[56:59], v[208:211], v[24:27]
	v_mfma_f32_16x16x32_bf16 v[12:15], v[44:47], v[216:219], v[12:15]
	v_mfma_f32_16x16x32_bf16 v[8:11], v[56:59], v[216:219], v[8:11]
	v_mfma_f32_16x16x32_bf16 v[36:39], v[144:147], v[182:185], v[36:39]
	v_mfma_f32_16x16x32_bf16 v[32:35], v[166:169], v[182:185], v[32:35]
	v_mfma_f32_16x16x32_bf16 v[20:23], v[144:147], v[194:197], v[20:23]
	v_mfma_f32_16x16x32_bf16 v[16:19], v[166:169], v[194:197], v[16:19]
	v_mfma_f32_16x16x32_bf16 v[4:7], v[144:147], v[212:215], v[4:7]
	v_mfma_f32_16x16x32_bf16 v[0:3], v[166:169], v[212:215], v[0:3]
	v_mfma_f32_16x16x32_bf16 v[40:43], v[144:147], v[174:177], v[68:71]
	v_mfma_f32_16x16x32_bf16 v[44:47], v[166:169], v[174:177], v[64:67]
	v_mfma_f32_16x16x32_bf16 v[36:39], v[162:165], v[186:189], v[36:39]
	v_mfma_f32_16x16x32_bf16 v[32:35], v[170:173], v[186:189], v[32:35]
	v_mfma_f32_16x16x32_bf16 v[20:23], v[162:165], v[208:211], v[20:23]
	v_mfma_f32_16x16x32_bf16 v[16:19], v[170:173], v[208:211], v[16:19]
	v_mfma_f32_16x16x32_bf16 v[4:7], v[162:165], v[216:219], v[4:7]
	v_mfma_f32_16x16x32_bf16 v[0:3], v[170:173], v[216:219], v[0:3]
	v_mfma_f32_16x16x32_bf16 v[40:43], v[162:165], v[178:181], v[40:43]
	v_mfma_f32_16x16x32_bf16 v[44:47], v[170:173], v[178:181], v[44:47]
	s_setprio 0
	s_barrier
	s_add_i32 s49, 0, 0x18000
	s_add_i32 s50, 0, 0x1c000
	v_add_u32_e32 v68, s49, v205
	v_add_u32_e32 v170, s50, v205
	ds_read_b128 v[52:55], v68
	ds_read_b128 v[56:59], v68 offset:1024
	ds_read_b128 v[64:67], v68 offset:2048
	ds_read_b128 v[68:71], v68 offset:3072
	ds_read_b128 v[144:147], v170
	ds_read_b128 v[162:165], v170 offset:1024
	ds_read_b128 v[166:169], v170 offset:2048
	ds_read_b128 v[170:173], v170 offset:3072
	s_add_u32 s22, s22, 0x40000
	s_addc_u32 s23, s23, 0
	s_mov_b32 m0, s31
	v_lshl_add_u64 v[226:227], s[22:23], 0, v[152:153]
	ds_read_b128 v[174:177], v206 offset:32768
	ds_read_b128 v[178:181], v206 offset:33792
	ds_read_b128 v[182:185], v206 offset:34816
	ds_read_b128 v[186:189], v206 offset:35840
	ds_read_b128 v[194:197], v206 offset:36864
	ds_read_b128 v[208:211], v206 offset:37888
	ds_read_b128 v[212:215], v206 offset:38912
	ds_read_b128 v[216:219], v206 offset:39936
	global_load_lds_dwordx4 v[226:227], off
	v_lshl_add_u64 v[226:227], s[22:23], 0, v[150:151]
	s_mov_b32 m0, s34
	s_nop 0
	global_load_lds_dwordx4 v[226:227], off
	s_waitcnt vmcnt(8)
	s_waitcnt lgkmcnt(0)
	s_barrier
	s_setprio 1
	s_waitcnt lgkmcnt(0)
	v_mfma_f32_16x16x32_bf16 v[140:143], v[52:55], v[174:177], v[140:143]
	v_mfma_f32_16x16x32_bf16 v[136:139], v[64:67], v[174:177], v[136:139]
	v_mfma_f32_16x16x32_bf16 v[124:127], v[52:55], v[182:185], v[124:127]
	v_mfma_f32_16x16x32_bf16 v[120:123], v[64:67], v[182:185], v[120:123]
	v_mfma_f32_16x16x32_bf16 v[108:111], v[52:55], v[194:197], v[108:111]
	v_mfma_f32_16x16x32_bf16 v[104:107], v[64:67], v[194:197], v[104:107]
	v_mfma_f32_16x16x32_bf16 v[92:95], v[52:55], v[212:215], v[92:95]
	v_mfma_f32_16x16x32_bf16 v[88:91], v[64:67], v[212:215], v[88:91]
	v_mfma_f32_16x16x32_bf16 v[140:143], v[56:59], v[178:181], v[140:143]
	v_mfma_f32_16x16x32_bf16 v[136:139], v[68:71], v[178:181], v[136:139]
	v_mfma_f32_16x16x32_bf16 v[124:127], v[56:59], v[186:189], v[124:127]
	v_mfma_f32_16x16x32_bf16 v[120:123], v[68:71], v[186:189], v[120:123]
	v_mfma_f32_16x16x32_bf16 v[108:111], v[56:59], v[208:211], v[108:111]
	v_mfma_f32_16x16x32_bf16 v[104:107], v[68:71], v[208:211], v[104:107]
	v_mfma_f32_16x16x32_bf16 v[92:95], v[56:59], v[216:219], v[92:95]
	v_mfma_f32_16x16x32_bf16 v[88:91], v[68:71], v[216:219], v[88:91]
	v_mfma_f32_16x16x32_bf16 v[132:135], v[144:147], v[174:177], v[132:135]
	v_mfma_f32_16x16x32_bf16 v[128:131], v[166:169], v[174:177], v[128:131]
	v_mfma_f32_16x16x32_bf16 v[116:119], v[144:147], v[182:185], v[116:119]
	v_mfma_f32_16x16x32_bf16 v[112:115], v[166:169], v[182:185], v[112:115]
	v_mfma_f32_16x16x32_bf16 v[100:103], v[144:147], v[194:197], v[100:103]
	v_mfma_f32_16x16x32_bf16 v[96:99], v[166:169], v[194:197], v[96:99]
	v_mfma_f32_16x16x32_bf16 v[84:87], v[144:147], v[212:215], v[84:87]
	v_mfma_f32_16x16x32_bf16 v[80:83], v[166:169], v[212:215], v[80:83]
	v_mfma_f32_16x16x32_bf16 v[132:135], v[162:165], v[178:181], v[132:135]
	v_mfma_f32_16x16x32_bf16 v[128:131], v[170:173], v[178:181], v[128:131]
	v_mfma_f32_16x16x32_bf16 v[116:119], v[162:165], v[186:189], v[116:119]
	v_mfma_f32_16x16x32_bf16 v[112:115], v[170:173], v[186:189], v[112:115]
	v_mfma_f32_16x16x32_bf16 v[100:103], v[162:165], v[208:211], v[100:103]
	v_mfma_f32_16x16x32_bf16 v[96:99], v[170:173], v[208:211], v[96:99]
	v_mfma_f32_16x16x32_bf16 v[84:87], v[162:165], v[216:219], v[84:87]
	v_mfma_f32_16x16x32_bf16 v[80:83], v[170:173], v[216:219], v[80:83]
	s_setprio 0
	s_barrier
; #define PG8_STAGE(bufoff, gbase, voff) do { _Pragma("unroll") for (int _i = 0; _i < 2; ++_i) \
;         __builtin_amdgcn_global_load_lds((const unsigned*)((const char*)(gbase) + (voff)[_i]), (PG8_LAS unsigned*)(lds + (bufoff) + ldsw + _i * 8192), 16, 0, 0); } while (0)
; #define PG8_LDA(dst, b, h) do { _Pragma("unroll") for (int m = 0; m < 4; ++m) _Pragma("unroll") for (int k = 0; k < 2; ++k) dst[m][k] = *(const PG8_LAS bf16x8*)(lds + PG8_SA(b, h) + aoff + m * 2048 + k * 1024); } while (0)
; #define PG8_MMA(ai, bj, At, Bt) do { __builtin_amdgcn_s_setprio(1); _Pragma("unroll") for (int m = 0; m < 4; ++m) _Pragma("unroll") for (int n = 0; n < 2; ++n) _Pragma("unroll") for (int k = 0; k < 2; ++k) \
;         acc[ai][bj][m][n] = __builtin_amdgcn_mfma_f32_16x16x32_bf16(Bt[n][k], At[m][k], acc[ai][bj][m][n], 0, 0, 0); __builtin_amdgcn_s_setprio(0); } while (0)
; #define PG8_WAIT_V(n) asm volatile("s_waitcnt vmcnt(" #n ")" ::: "memory")
; #define PG8_WAIT_L(n) asm volatile("s_waitcnt lgkmcnt(" #n ")" ::: "memory")
; #define PG8_BAR __builtin_amdgcn_s_barrier()
; #define PG8_SCHED __builtin_amdgcn_sched_barrier(0)
; template <class Epi, class Sched, bool ALIGN_EPI = false, bool SP2 = false>
; __device__ __forceinline__ void gemm_phase(PG8_LAS unsigned char* lds, const Gemm g, const Sched& S, const Epi& E) {
;     ...
;             PG8_LDA(At, 1, 1); PG8_STAGE(PG8_SB(1, 0), b3, voffB); PG8_STAGE(PG8_SB(1, 1), b3 + hstep, voffB); PG8_STAGE(PG8_SA(1, 0), a3, voffA);
;             PG8_WAIT_V(8); PG8_WAIT_L(0); PG8_BAR; PG8_MMA(1, 0, At, B0); PG8_MMA(1, 1, At, B1); PG8_BAR; PG8_SCHED;
	s_add_i32 s22, s49, s28
	v_lshl_add_u64 v[158:159], v[158:159], 0, s[38:39]
	s_mov_b32 m0, s22
	ds_read_b128 v[174:177], v206 offset:49152
	ds_read_b128 v[178:181], v206 offset:50176
	ds_read_b128 v[182:185], v206 offset:51200
	ds_read_b128 v[186:189], v206 offset:52224
	ds_read_b128 v[194:197], v206 offset:53248
	ds_read_b128 v[208:211], v206 offset:54272
	ds_read_b128 v[212:215], v206 offset:55296
	ds_read_b128 v[216:219], v206 offset:56320
	global_load_lds_dwordx4 v[158:159], off
	s_add_i32 m0, s22, 0x2000
	s_add_u32 s6, s6, 0x40080
	v_lshl_add_u64 v[158:159], v[220:221], 0, s[38:39]
	s_addc_u32 s7, s7, 0
	s_add_i32 s22, s50, s28
	global_load_lds_dwordx4 v[158:159], off
	v_lshl_add_u64 v[158:159], s[6:7], 0, v[160:161]
	s_mov_b32 m0, s22
	s_nop 0
	global_load_lds_dwordx4 v[158:159], off
	v_lshl_add_u64 v[158:159], s[6:7], 0, v[148:149]
	s_add_i32 m0, s22, 0x2000
	s_nop 0
	global_load_lds_dwordx4 v[158:159], off
	v_lshl_add_u64 v[158:159], v[222:223], 0, s[38:39]
	s_mov_b32 m0, s41
	s_nop 0
	global_load_lds_dwordx4 v[158:159], off
	v_lshl_add_u64 v[158:159], v[224:225], 0, s[38:39]
	s_mov_b32 m0, s42
	s_nop 0
	global_load_lds_dwordx4 v[158:159], off
	s_waitcnt vmcnt(8)
	s_waitcnt lgkmcnt(0)
	s_barrier
	s_setprio 1
	s_waitcnt lgkmcnt(0)
	v_mfma_f32_16x16x32_bf16 v[76:79], v[52:55], v[174:177], v[76:79]
	v_mfma_f32_16x16x32_bf16 v[72:75], v[64:67], v[174:177], v[72:75]
	v_mfma_f32_16x16x32_bf16 v[60:63], v[52:55], v[182:185], v[60:63]
	v_mfma_f32_16x16x32_bf16 v[48:51], v[64:67], v[182:185], v[48:51]
	v_mfma_f32_16x16x32_bf16 v[28:31], v[52:55], v[194:197], v[28:31]
	v_mfma_f32_16x16x32_bf16 v[24:27], v[64:67], v[194:197], v[24:27]
	v_mfma_f32_16x16x32_bf16 v[12:15], v[52:55], v[212:215], v[12:15]
	v_mfma_f32_16x16x32_bf16 v[8:11], v[64:67], v[212:215], v[8:11]
	v_mfma_f32_16x16x32_bf16 v[76:79], v[56:59], v[178:181], v[76:79]
	v_mfma_f32_16x16x32_bf16 v[72:75], v[68:71], v[178:181], v[72:75]
	v_mfma_f32_16x16x32_bf16 v[60:63], v[56:59], v[186:189], v[60:63]
	v_mfma_f32_16x16x32_bf16 v[48:51], v[68:71], v[186:189], v[48:51]
	v_mfma_f32_16x16x32_bf16 v[28:31], v[56:59], v[208:211], v[28:31]
	v_mfma_f32_16x16x32_bf16 v[24:27], v[68:71], v[208:211], v[24:27]
	v_mfma_f32_16x16x32_bf16 v[12:15], v[56:59], v[216:219], v[12:15]
	v_mfma_f32_16x16x32_bf16 v[8:11], v[68:71], v[216:219], v[8:11]
	v_mfma_f32_16x16x32_bf16 v[40:43], v[144:147], v[174:177], v[40:43]
	v_mfma_f32_16x16x32_bf16 v[68:71], v[162:165], v[178:181], v[40:43]
	v_mfma_f32_16x16x32_bf16 v[40:43], v[166:169], v[174:177], v[44:47]
	v_mfma_f32_16x16x32_bf16 v[36:39], v[144:147], v[182:185], v[36:39]
	v_mfma_f32_16x16x32_bf16 v[32:35], v[166:169], v[182:185], v[32:35]
	v_mfma_f32_16x16x32_bf16 v[20:23], v[144:147], v[194:197], v[20:23]
	v_mfma_f32_16x16x32_bf16 v[16:19], v[166:169], v[194:197], v[16:19]
	v_mfma_f32_16x16x32_bf16 v[4:7], v[144:147], v[212:215], v[4:7]
	v_mfma_f32_16x16x32_bf16 v[0:3], v[166:169], v[212:215], v[0:3]
	v_mfma_f32_16x16x32_bf16 v[64:67], v[170:173], v[178:181], v[40:43]
	v_mfma_f32_16x16x32_bf16 v[36:39], v[162:165], v[186:189], v[36:39]
	v_mfma_f32_16x16x32_bf16 v[32:35], v[170:173], v[186:189], v[32:35]
	v_mfma_f32_16x16x32_bf16 v[20:23], v[162:165], v[208:211], v[20:23]
	v_mfma_f32_16x16x32_bf16 v[16:19], v[170:173], v[208:211], v[16:19]
	v_mfma_f32_16x16x32_bf16 v[4:7], v[162:165], v[216:219], v[4:7]
	v_mfma_f32_16x16x32_bf16 v[0:3], v[170:173], v[216:219], v[0:3]
	s_setprio 0
	s_barrier
	s_add_i32 s48, s48, 2
	s_add_u32 s4, s4, 0x100
	s_addc_u32 s5, s5, 0
	s_add_u32 s46, s46, 0x100
	s_addc_u32 s47, s47, 0
	s_cmp_gt_u32 s48, 13
	s_cbranch_scc0 .LBB0_945
	s_and_b64 vcc, exec, s[12:13]
	s_cbranch_vccz .LBB0_948
	s_barrier

; #define PG8_STAGE(bufoff, gbase, voff) do { _Pragma("unroll") for (int _i = 0; _i < 2; ++_i) \
;         __builtin_amdgcn_global_load_lds((const unsigned*)((const char*)(gbase) + (voff)[_i]), (PG8_LAS unsigned*)(lds + (bufoff) + ldsw + _i * 8192), 16, 0, 0); } while (0)
; #define PG8_LDA(dst, b, h) do { _Pragma("unroll") for (int m = 0; m < 4; ++m) _Pragma("unroll") for (int k = 0; k < 2; ++k) dst[m][k] = *(const PG8_LAS bf16x8*)(lds + PG8_SA(b, h) + aoff + m * 2048 + k * 1024); } while (0)
; #define PG8_LDB(dst, b, h) do { _Pragma("unroll") for (int n = 0; n < 2; ++n) _Pragma("unroll") for (int k = 0; k < 2; ++k) dst[n][k] = *(const PG8_LAS bf16x8*)(lds + PG8_SB(b, h) + boff + n * 2048 + k * 1024); } while (0)
; #define PG8_MMA(ai, bj, At, Bt) do { __builtin_amdgcn_s_setprio(1); _Pragma("unroll") for (int m = 0; m < 4; ++m) _Pragma("unroll") for (int n = 0; n < 2; ++n) _Pragma("unroll") for (int k = 0; k < 2; ++k) \
;         acc[ai][bj][m][n] = __builtin_amdgcn_mfma_f32_16x16x32_bf16(Bt[n][k], At[m][k], acc[ai][bj][m][n], 0, 0, 0); __builtin_amdgcn_s_setprio(0); } while (0)
; #define PG8_WAIT_V(n) asm volatile("s_waitcnt vmcnt(" #n ")" ::: "memory")
; #define PG8_WAIT_L(n) asm volatile("s_waitcnt lgkmcnt(" #n ")" ::: "memory")
; #define PG8_BAR __builtin_amdgcn_s_barrier()
; #define PG8_SCHED __builtin_amdgcn_sched_barrier(0)
; template <class Epi, class Sched, bool ALIGN_EPI = false, bool SP2 = false>
; __device__ __forceinline__ void gemm_phase(PG8_LAS unsigned char* lds, const Gemm g, const Sched& S, const Epi& E) {
;     ...
;             const bool last = (t == nt - 2);
;             const char* a1 = cA + (size_t)(t + 1) * kstep;
;             const char* a2 = last ? nA : cA + (size_t)(t + 2) * kstep; const char* b2 = last ? nB : cB + (size_t)(t + 2) * kstep;
;             const char* a3 = a2 + kstep; const char* b3 = b2 + kstep;
;             if (last && has_next) S.a_ready(nxt);
;             if constexpr (SP2) {
;             PG8_LDB(B0, 0, 0); PG8_LDB(B1, 0, 1); PG8_SCHED; PG8_LDA(At, 0, 0); PG8_STAGE(PG8_SA(1, 1), a1 + hstep, voffA);
;             PG8_WAIT_V(8); PG8_WAIT_L(0); PG8_BAR; PG8_MMA(0, 0, At, B0); PG8_MMA(0, 1, At, B1); PG8_BAR; PG8_SCHED;
;             PG8_LDA(At, 0, 1); PG8_STAGE(PG8_SB(0, 0), b2, voffB); PG8_STAGE(PG8_SB(0, 1), b2 + hstep, voffB); PG8_STAGE(PG8_SA(0, 0), a2, voffA);
.LBB0_1135:
	s_add_u32 s18, s4, 0xfffc0080
	s_addc_u32 s19, s5, -1
	s_add_i32 s45, 0, 0x10000
	s_cmp_eq_u32 s44, 12
	s_cselect_b32 s21, s11, s19
	s_cselect_b32 s20, s40, s18
	s_cselect_b32 s19, s13, s43
	s_cselect_b32 s18, s41, s42
	s_add_i32 s48, 0, 0x14000
	v_add_u32_e32 v68, s45, v169
	v_add_u32_e32 v158, s48, v169
	ds_read_b128 v[56:59], v68
	ds_read_b128 v[60:63], v68 offset:1024
	ds_read_b128 v[64:67], v68 offset:2048
	ds_read_b128 v[68:71], v68 offset:3072
	ds_read_b128 v[154:157], v158
	ds_read_b128 v[162:165], v158 offset:1024
	ds_read_b128 v[172:175], v158 offset:2048
	ds_read_b128 v[176:179], v158 offset:3072
	v_lshl_add_u64 v[158:159], s[4:5], 0, v[150:151]
	s_add_i32 m0, s27, 0xc000
	ds_read_b128 v[180:183], v171
	ds_read_b128 v[184:187], v171 offset:1024
	ds_read_b128 v[194:197], v171 offset:2048
	ds_read_b128 v[206:209], v171 offset:3072
	ds_read_b128 v[210:213], v171 offset:4096
	ds_read_b128 v[214:217], v171 offset:5120
	ds_read_b128 v[218:221], v171 offset:6144
	ds_read_b128 v[222:225], v171 offset:7168
	global_load_lds_dwordx4 v[158:159], off
	v_lshl_add_u64 v[158:159], s[4:5], 0, v[152:153]
	s_add_i32 m0, s27, 0xe000
	s_nop 0
	global_load_lds_dwordx4 v[158:159], off
	s_waitcnt vmcnt(8)
	s_waitcnt lgkmcnt(0)
	s_barrier
	s_setprio 1
	s_waitcnt lgkmcnt(0)
	v_mfma_f32_16x16x32_bf16 v[140:143], v[56:59], v[180:183], v[140:143]
	v_mfma_f32_16x16x32_bf16 v[136:139], v[64:67], v[180:183], v[136:139]
	v_mfma_f32_16x16x32_bf16 v[124:127], v[56:59], v[194:197], v[124:127]
	v_mfma_f32_16x16x32_bf16 v[120:123], v[64:67], v[194:197], v[120:123]
	v_mfma_f32_16x16x32_bf16 v[108:111], v[56:59], v[210:213], v[108:111]
	v_mfma_f32_16x16x32_bf16 v[104:107], v[64:67], v[210:213], v[104:107]
	v_mfma_f32_16x16x32_bf16 v[92:95], v[56:59], v[218:221], v[92:95]
	v_mfma_f32_16x16x32_bf16 v[88:91], v[64:67], v[218:221], v[88:91]
	v_mfma_f32_16x16x32_bf16 v[140:143], v[60:63], v[184:187], v[140:143]
	v_mfma_f32_16x16x32_bf16 v[136:139], v[68:71], v[184:187], v[136:139]
	v_mfma_f32_16x16x32_bf16 v[124:127], v[60:63], v[206:209], v[124:127]
	v_mfma_f32_16x16x32_bf16 v[120:123], v[68:71], v[206:209], v[120:123]
	v_mfma_f32_16x16x32_bf16 v[108:111], v[60:63], v[214:217], v[108:111]
	v_mfma_f32_16x16x32_bf16 v[104:107], v[68:71], v[214:217], v[104:107]
	v_mfma_f32_16x16x32_bf16 v[92:95], v[60:63], v[222:225], v[92:95]
	v_mfma_f32_16x16x32_bf16 v[88:91], v[68:71], v[222:225], v[88:91]
	v_mfma_f32_16x16x32_bf16 v[132:135], v[154:157], v[180:183], v[132:135]
	v_mfma_f32_16x16x32_bf16 v[128:131], v[172:175], v[180:183], v[128:131]
	v_mfma_f32_16x16x32_bf16 v[116:119], v[154:157], v[194:197], v[116:119]
	v_mfma_f32_16x16x32_bf16 v[112:115], v[172:175], v[194:197], v[112:115]
	v_mfma_f32_16x16x32_bf16 v[100:103], v[154:157], v[210:213], v[100:103]
	v_mfma_f32_16x16x32_bf16 v[96:99], v[172:175], v[210:213], v[96:99]
	v_mfma_f32_16x16x32_bf16 v[84:87], v[154:157], v[218:221], v[84:87]
	v_mfma_f32_16x16x32_bf16 v[80:83], v[172:175], v[218:221], v[80:83]
	v_mfma_f32_16x16x32_bf16 v[132:135], v[162:165], v[184:187], v[132:135]
	v_mfma_f32_16x16x32_bf16 v[128:131], v[176:179], v[184:187], v[128:131]
	v_mfma_f32_16x16x32_bf16 v[116:119], v[162:165], v[206:209], v[116:119]
	v_mfma_f32_16x16x32_bf16 v[112:115], v[176:179], v[206:209], v[112:115]
	v_mfma_f32_16x16x32_bf16 v[100:103], v[162:165], v[214:217], v[100:103]
	v_mfma_f32_16x16x32_bf16 v[96:99], v[176:179], v[214:217], v[96:99]
	v_mfma_f32_16x16x32_bf16 v[84:87], v[162:165], v[222:225], v[84:87]
	v_mfma_f32_16x16x32_bf16 v[80:83], v[176:179], v[222:225], v[80:83]
	s_setprio 0
	s_barrier
	s_add_i32 s45, s45, s26
	v_lshl_add_u64 v[158:159], s[18:19], 0, v[160:161]
	s_mov_b32 m0, s45
	ds_read_b128 v[180:183], v171 offset:16384
	ds_read_b128 v[184:187], v171 offset:17408
	ds_read_b128 v[194:197], v171 offset:18432
	ds_read_b128 v[206:209], v171 offset:19456
	ds_read_b128 v[210:213], v171 offset:20480
	ds_read_b128 v[214:217], v171 offset:21504
	ds_read_b128 v[218:221], v171 offset:22528
	ds_read_b128 v[222:225], v171 offset:23552
	global_load_lds_dwordx4 v[158:159], off
	s_add_i32 m0, s45, 0x2000
	s_add_u32 s46, s18, 0x40000
	v_lshl_add_u64 v[166:167], s[18:19], 0, v[144:145]
	s_addc_u32 s47, s19, 0
	s_add_i32 s45, s48, s26
	global_load_lds_dwordx4 v[166:167], off
	v_lshl_add_u64 v[188:189], s[46:47], 0, v[160:161]
	s_mov_b32 m0, s45
	v_lshl_add_u64 v[226:227], s[20:21], 0, v[146:147]
	global_load_lds_dwordx4 v[188:189], off
	v_lshl_add_u64 v[188:189], s[46:47], 0, v[144:145]
	s_add_i32 m0, s45, 0x2000
	s_nop 0
	global_load_lds_dwordx4 v[188:189], off
	v_lshl_add_u64 v[188:189], s[20:21], 0, v[148:149]
	s_mov_b32 m0, s27
	s_nop 0
	global_load_lds_dwordx4 v[188:189], off
	s_mov_b32 m0, s28
	s_nop 0
	global_load_lds_dwordx4 v[226:227], off
	s_waitcnt vmcnt(8)
	s_waitcnt lgkmcnt(0)
	s_barrier
; #define PG8_STAGE(bufoff, gbase, voff) do { _Pragma("unroll") for (int _i = 0; _i < 2; ++_i) \
;         __builtin_amdgcn_global_load_lds((const unsigned*)((const char*)(gbase) + (voff)[_i]), (PG8_LAS unsigned*)(lds + (bufoff) + ldsw + _i * 8192), 16, 0, 0); } while (0)
; #define PG8_LDA(dst, b, h) do { _Pragma("unroll") for (int m = 0; m < 4; ++m) _Pragma("unroll") for (int k = 0; k < 2; ++k) dst[m][k] = *(const PG8_LAS bf16x8*)(lds + PG8_SA(b, h) + aoff + m * 2048 + k * 1024); } while (0)
; #define PG8_LDB(dst, b, h) do { _Pragma("unroll") for (int n = 0; n < 2; ++n) _Pragma("unroll") for (int k = 0; k < 2; ++k) dst[n][k] = *(const PG8_LAS bf16x8*)(lds + PG8_SB(b, h) + boff + n * 2048 + k * 1024); } while (0)
; #define PG8_MMA(ai, bj, At, Bt) do { __builtin_amdgcn_s_setprio(1); _Pragma("unroll") for (int m = 0; m < 4; ++m) _Pragma("unroll") for (int n = 0; n < 2; ++n) _Pragma("unroll") for (int k = 0; k < 2; ++k) \
;         acc[ai][bj][m][n] = __builtin_amdgcn_mfma_f32_16x16x32_bf16(Bt[n][k], At[m][k], acc[ai][bj][m][n], 0, 0, 0); __builtin_amdgcn_s_setprio(0); } while (0)
; #define PG8_WAIT_V(n) asm volatile("s_waitcnt vmcnt(" #n ")" ::: "memory")
; #define PG8_WAIT_L(n) asm volatile("s_waitcnt lgkmcnt(" #n ")" ::: "memory")
; #define PG8_BAR __builtin_amdgcn_s_barrier()
; #define PG8_SCHED __builtin_amdgcn_sched_barrier(0)
; template <class Epi, class Sched, bool ALIGN_EPI = false, bool SP2 = false>
; __device__ __forceinline__ void gemm_phase(PG8_LAS unsigned char* lds, const Gemm g, const Sched& S, const Epi& E) {
;     ...
;             PG8_WAIT_V(8); PG8_WAIT_L(0); PG8_BAR; PG8_MMA(1, 0, At, B0); PG8_MMA(1, 1, At, B1); PG8_BAR; PG8_SCHED;
;             PG8_LDB(B0, 1, 0); PG8_LDB(B1, 1, 1); PG8_SCHED; PG8_LDA(At, 1, 0); PG8_STAGE(PG8_SA(0, 1), a2 + hstep, voffA);
;             PG8_WAIT_V(8); PG8_WAIT_L(0); PG8_BAR; PG8_MMA(0, 0, At, B0); PG8_MMA(0, 1, At, B1); PG8_BAR; PG8_SCHED;
	s_setprio 1
	s_waitcnt lgkmcnt(0)
	v_mfma_f32_16x16x32_bf16 v[76:79], v[56:59], v[180:183], v[76:79]
	v_mfma_f32_16x16x32_bf16 v[72:75], v[64:67], v[180:183], v[72:75]
	v_mfma_f32_16x16x32_bf16 v[44:47], v[56:59], v[194:197], v[44:47]
	v_mfma_f32_16x16x32_bf16 v[40:43], v[64:67], v[194:197], v[40:43]
	v_mfma_f32_16x16x32_bf16 v[28:31], v[56:59], v[210:213], v[28:31]
	v_mfma_f32_16x16x32_bf16 v[24:27], v[64:67], v[210:213], v[24:27]
	v_mfma_f32_16x16x32_bf16 v[12:15], v[56:59], v[218:221], v[12:15]
	v_mfma_f32_16x16x32_bf16 v[8:11], v[64:67], v[218:221], v[8:11]
	v_mfma_f32_16x16x32_bf16 v[76:79], v[60:63], v[184:187], v[76:79]
	v_mfma_f32_16x16x32_bf16 v[72:75], v[68:71], v[184:187], v[72:75]
	v_mfma_f32_16x16x32_bf16 v[44:47], v[60:63], v[206:209], v[44:47]
	v_mfma_f32_16x16x32_bf16 v[40:43], v[68:71], v[206:209], v[40:43]
	v_mfma_f32_16x16x32_bf16 v[28:31], v[60:63], v[214:217], v[28:31]
	v_mfma_f32_16x16x32_bf16 v[24:27], v[68:71], v[214:217], v[24:27]
	v_mfma_f32_16x16x32_bf16 v[12:15], v[60:63], v[222:225], v[12:15]
	v_mfma_f32_16x16x32_bf16 v[8:11], v[68:71], v[222:225], v[8:11]
	v_mfma_f32_16x16x32_bf16 v[52:55], v[154:157], v[180:183], v[52:55]
	v_mfma_f32_16x16x32_bf16 v[48:51], v[172:175], v[180:183], v[48:51]
	v_mfma_f32_16x16x32_bf16 v[36:39], v[154:157], v[194:197], v[36:39]
	v_mfma_f32_16x16x32_bf16 v[32:35], v[172:175], v[194:197], v[32:35]
	v_mfma_f32_16x16x32_bf16 v[20:23], v[154:157], v[210:213], v[20:23]
	v_mfma_f32_16x16x32_bf16 v[16:19], v[172:175], v[210:213], v[16:19]
	v_mfma_f32_16x16x32_bf16 v[4:7], v[154:157], v[218:221], v[4:7]
	v_mfma_f32_16x16x32_bf16 v[0:3], v[172:175], v[218:221], v[0:3]
	v_mfma_f32_16x16x32_bf16 v[52:55], v[162:165], v[184:187], v[52:55]
	v_mfma_f32_16x16x32_bf16 v[48:51], v[176:179], v[184:187], v[48:51]
	v_mfma_f32_16x16x32_bf16 v[36:39], v[162:165], v[206:209], v[36:39]
	v_mfma_f32_16x16x32_bf16 v[32:35], v[176:179], v[206:209], v[32:35]
	v_mfma_f32_16x16x32_bf16 v[20:23], v[162:165], v[214:217], v[20:23]
	v_mfma_f32_16x16x32_bf16 v[16:19], v[176:179], v[214:217], v[16:19]
	v_mfma_f32_16x16x32_bf16 v[4:7], v[162:165], v[222:225], v[4:7]
	v_mfma_f32_16x16x32_bf16 v[0:3], v[176:179], v[222:225], v[0:3]
	s_setprio 0
	s_barrier
	s_add_i32 s45, 0, 0x18000
	s_add_i32 s46, 0, 0x1c000
	v_add_u32_e32 v68, s45, v169
	v_add_u32_e32 v176, s46, v169
	ds_read_b128 v[56:59], v68
	ds_read_b128 v[60:63], v68 offset:1024
	ds_read_b128 v[64:67], v68 offset:2048
	ds_read_b128 v[68:71], v68 offset:3072
	ds_read_b128 v[154:157], v176
	ds_read_b128 v[162:165], v176 offset:1024
	ds_read_b128 v[172:175], v176 offset:2048
	ds_read_b128 v[176:179], v176 offset:3072
	s_add_u32 s20, s20, 0x40000
	s_addc_u32 s21, s21, 0
	s_mov_b32 m0, s29
	v_lshl_add_u64 v[228:229], s[20:21], 0, v[148:149]
	ds_read_b128 v[180:183], v171 offset:32768
	ds_read_b128 v[184:187], v171 offset:33792
	ds_read_b128 v[194:197], v171 offset:34816
	ds_read_b128 v[206:209], v171 offset:35840
	ds_read_b128 v[210:213], v171 offset:36864
	ds_read_b128 v[214:217], v171 offset:37888
	ds_read_b128 v[218:221], v171 offset:38912
	ds_read_b128 v[222:225], v171 offset:39936
	global_load_lds_dwordx4 v[228:229], off
	v_lshl_add_u64 v[228:229], s[20:21], 0, v[146:147]
	s_mov_b32 m0, s30
	s_nop 0
	global_load_lds_dwordx4 v[228:229], off
	s_waitcnt vmcnt(8)
	s_waitcnt lgkmcnt(0)
	s_barrier
	s_setprio 1
	s_waitcnt lgkmcnt(0)
	v_mfma_f32_16x16x32_bf16 v[140:143], v[56:59], v[180:183], v[140:143]
	v_mfma_f32_16x16x32_bf16 v[136:139], v[64:67], v[180:183], v[136:139]
	v_mfma_f32_16x16x32_bf16 v[124:127], v[56:59], v[194:197], v[124:127]
	v_mfma_f32_16x16x32_bf16 v[120:123], v[64:67], v[194:197], v[120:123]
	v_mfma_f32_16x16x32_bf16 v[108:111], v[56:59], v[210:213], v[108:111]
	v_mfma_f32_16x16x32_bf16 v[104:107], v[64:67], v[210:213], v[104:107]
	v_mfma_f32_16x16x32_bf16 v[92:95], v[56:59], v[218:221], v[92:95]
	v_mfma_f32_16x16x32_bf16 v[88:91], v[64:67], v[218:221], v[88:91]
	v_mfma_f32_16x16x32_bf16 v[140:143], v[60:63], v[184:187], v[140:143]
	v_mfma_f32_16x16x32_bf16 v[136:139], v[68:71], v[184:187], v[136:139]
	v_mfma_f32_16x16x32_bf16 v[124:127], v[60:63], v[206:209], v[124:127]
	v_mfma_f32_16x16x32_bf16 v[120:123], v[68:71], v[206:209], v[120:123]
	v_mfma_f32_16x16x32_bf16 v[108:111], v[60:63], v[214:217], v[108:111]
	v_mfma_f32_16x16x32_bf16 v[104:107], v[68:71], v[214:217], v[104:107]
	v_mfma_f32_16x16x32_bf16 v[92:95], v[60:63], v[222:225], v[92:95]
	v_mfma_f32_16x16x32_bf16 v[88:91], v[68:71], v[222:225], v[88:91]
	v_mfma_f32_16x16x32_bf16 v[132:135], v[154:157], v[180:183], v[132:135]
	v_mfma_f32_16x16x32_bf16 v[128:131], v[172:175], v[180:183], v[128:131]
	v_mfma_f32_16x16x32_bf16 v[116:119], v[154:157], v[194:197], v[116:119]
	v_mfma_f32_16x16x32_bf16 v[112:115], v[172:175], v[194:197], v[112:115]
	v_mfma_f32_16x16x32_bf16 v[100:103], v[154:157], v[210:213], v[100:103]
	v_mfma_f32_16x16x32_bf16 v[96:99], v[172:175], v[210:213], v[96:99]
	v_mfma_f32_16x16x32_bf16 v[84:87], v[154:157], v[218:221], v[84:87]
	v_mfma_f32_16x16x32_bf16 v[80:83], v[172:175], v[218:221], v[80:83]
	v_mfma_f32_16x16x32_bf16 v[132:135], v[162:165], v[184:187], v[132:135]
	v_mfma_f32_16x16x32_bf16 v[128:131], v[176:179], v[184:187], v[128:131]
	v_mfma_f32_16x16x32_bf16 v[116:119], v[162:165], v[206:209], v[116:119]
	v_mfma_f32_16x16x32_bf16 v[112:115], v[176:179], v[206:209], v[112:115]
	v_mfma_f32_16x16x32_bf16 v[100:103], v[162:165], v[214:217], v[100:103]
	v_mfma_f32_16x16x32_bf16 v[96:99], v[176:179], v[214:217], v[96:99]
	v_mfma_f32_16x16x32_bf16 v[84:87], v[162:165], v[222:225], v[84:87]
	v_mfma_f32_16x16x32_bf16 v[80:83], v[176:179], v[222:225], v[80:83]
	s_setprio 0
	s_barrier
; #define PG8_STAGE(bufoff, gbase, voff) do { _Pragma("unroll") for (int _i = 0; _i < 2; ++_i) \
;         __builtin_amdgcn_global_load_lds((const unsigned*)((const char*)(gbase) + (voff)[_i]), (PG8_LAS unsigned*)(lds + (bufoff) + ldsw + _i * 8192), 16, 0, 0); } while (0)
; #define PG8_LDA(dst, b, h) do { _Pragma("unroll") for (int m = 0; m < 4; ++m) _Pragma("unroll") for (int k = 0; k < 2; ++k) dst[m][k] = *(const PG8_LAS bf16x8*)(lds + PG8_SA(b, h) + aoff + m * 2048 + k * 1024); } while (0)
; #define PG8_MMA(ai, bj, At, Bt) do { __builtin_amdgcn_s_setprio(1); _Pragma("unroll") for (int m = 0; m < 4; ++m) _Pragma("unroll") for (int n = 0; n < 2; ++n) _Pragma("unroll") for (int k = 0; k < 2; ++k) \
;         acc[ai][bj][m][n] = __builtin_amdgcn_mfma_f32_16x16x32_bf16(Bt[n][k], At[m][k], acc[ai][bj][m][n], 0, 0, 0); __builtin_amdgcn_s_setprio(0); } while (0)
; #define PG8_WAIT_V(n) asm volatile("s_waitcnt vmcnt(" #n ")" ::: "memory")
; #define PG8_WAIT_L(n) asm volatile("s_waitcnt lgkmcnt(" #n ")" ::: "memory")
; #define PG8_BAR __builtin_amdgcn_s_barrier()
; #define PG8_SCHED __builtin_amdgcn_sched_barrier(0)
; template <class Epi, class Sched, bool ALIGN_EPI = false, bool SP2 = false>
; __device__ __forceinline__ void gemm_phase(PG8_LAS unsigned char* lds, const Gemm g, const Sched& S, const Epi& E) {
;     ...
;             PG8_LDA(At, 1, 1); PG8_STAGE(PG8_SB(1, 0), b3, voffB); PG8_STAGE(PG8_SB(1, 1), b3 + hstep, voffB); PG8_STAGE(PG8_SA(1, 0), a3, voffA);
;             PG8_WAIT_V(8); PG8_WAIT_L(0); PG8_BAR; PG8_MMA(1, 0, At, B0); PG8_MMA(1, 1, At, B1); PG8_BAR; PG8_SCHED;
	s_add_i32 s20, s45, s26
	v_lshl_add_u64 v[158:159], v[158:159], 0, s[38:39]
	s_mov_b32 m0, s20
	ds_read_b128 v[180:183], v171 offset:49152
	ds_read_b128 v[184:187], v171 offset:50176
	ds_read_b128 v[194:197], v171 offset:51200
	ds_read_b128 v[206:209], v171 offset:52224
	ds_read_b128 v[210:213], v171 offset:53248
	ds_read_b128 v[214:217], v171 offset:54272
	ds_read_b128 v[218:221], v171 offset:55296
	ds_read_b128 v[222:225], v171 offset:56320
	global_load_lds_dwordx4 v[158:159], off
	s_add_i32 m0, s20, 0x2000
	s_add_u32 s18, s18, 0x40080
	v_lshl_add_u64 v[158:159], v[166:167], 0, s[38:39]
	s_addc_u32 s19, s19, 0
	s_add_i32 s20, s46, s26
	global_load_lds_dwordx4 v[158:159], off
	v_lshl_add_u64 v[158:159], s[18:19], 0, v[160:161]
	s_mov_b32 m0, s20
	s_nop 0
	global_load_lds_dwordx4 v[158:159], off
	v_lshl_add_u64 v[158:159], s[18:19], 0, v[144:145]
	s_add_i32 m0, s20, 0x2000
	s_nop 0
	global_load_lds_dwordx4 v[158:159], off
	v_lshl_add_u64 v[158:159], v[188:189], 0, s[38:39]
	s_mov_b32 m0, s35
	s_nop 0
	global_load_lds_dwordx4 v[158:159], off
	v_lshl_add_u64 v[158:159], v[226:227], 0, s[38:39]
	s_mov_b32 m0, s36
	s_nop 0
	global_load_lds_dwordx4 v[158:159], off
	s_waitcnt vmcnt(8)
	s_waitcnt lgkmcnt(0)
	s_barrier
	s_setprio 1
	s_waitcnt lgkmcnt(0)
	v_mfma_f32_16x16x32_bf16 v[76:79], v[56:59], v[180:183], v[76:79]
	v_mfma_f32_16x16x32_bf16 v[72:75], v[64:67], v[180:183], v[72:75]
	v_mfma_f32_16x16x32_bf16 v[44:47], v[56:59], v[194:197], v[44:47]
	v_mfma_f32_16x16x32_bf16 v[40:43], v[64:67], v[194:197], v[40:43]
	v_mfma_f32_16x16x32_bf16 v[28:31], v[56:59], v[210:213], v[28:31]
	v_mfma_f32_16x16x32_bf16 v[24:27], v[64:67], v[210:213], v[24:27]
	v_mfma_f32_16x16x32_bf16 v[12:15], v[56:59], v[218:221], v[12:15]
	v_mfma_f32_16x16x32_bf16 v[8:11], v[64:67], v[218:221], v[8:11]
	v_mfma_f32_16x16x32_bf16 v[76:79], v[60:63], v[184:187], v[76:79]
	v_mfma_f32_16x16x32_bf16 v[72:75], v[68:71], v[184:187], v[72:75]
	v_mfma_f32_16x16x32_bf16 v[44:47], v[60:63], v[206:209], v[44:47]
	v_mfma_f32_16x16x32_bf16 v[40:43], v[68:71], v[206:209], v[40:43]
	v_mfma_f32_16x16x32_bf16 v[28:31], v[60:63], v[214:217], v[28:31]
	v_mfma_f32_16x16x32_bf16 v[24:27], v[68:71], v[214:217], v[24:27]
	v_mfma_f32_16x16x32_bf16 v[12:15], v[60:63], v[222:225], v[12:15]
	v_mfma_f32_16x16x32_bf16 v[8:11], v[68:71], v[222:225], v[8:11]
	v_mfma_f32_16x16x32_bf16 v[52:55], v[154:157], v[180:183], v[52:55]
	v_mfma_f32_16x16x32_bf16 v[48:51], v[172:175], v[180:183], v[48:51]
	v_mfma_f32_16x16x32_bf16 v[36:39], v[154:157], v[194:197], v[36:39]
	v_mfma_f32_16x16x32_bf16 v[32:35], v[172:175], v[194:197], v[32:35]
	v_mfma_f32_16x16x32_bf16 v[20:23], v[154:157], v[210:213], v[20:23]
	v_mfma_f32_16x16x32_bf16 v[16:19], v[172:175], v[210:213], v[16:19]
	v_mfma_f32_16x16x32_bf16 v[4:7], v[154:157], v[218:221], v[4:7]
	v_mfma_f32_16x16x32_bf16 v[0:3], v[172:175], v[218:221], v[0:3]
	v_mfma_f32_16x16x32_bf16 v[52:55], v[162:165], v[184:187], v[52:55]
	v_mfma_f32_16x16x32_bf16 v[48:51], v[176:179], v[184:187], v[48:51]
	v_mfma_f32_16x16x32_bf16 v[36:39], v[162:165], v[206:209], v[36:39]
	v_mfma_f32_16x16x32_bf16 v[32:35], v[176:179], v[206:209], v[32:35]
	v_mfma_f32_16x16x32_bf16 v[20:23], v[162:165], v[214:217], v[20:23]
	v_mfma_f32_16x16x32_bf16 v[16:19], v[176:179], v[214:217], v[16:19]
	v_mfma_f32_16x16x32_bf16 v[4:7], v[162:165], v[222:225], v[4:7]
	v_mfma_f32_16x16x32_bf16 v[0:3], v[176:179], v[222:225], v[0:3]
	s_setprio 0
	s_barrier
	s_add_i32 s44, s44, 2
	s_add_u32 s4, s4, 0x100
	s_addc_u32 s5, s5, 0
	s_add_u32 s42, s42, 0x100
	s_addc_u32 s43, s43, 0
	s_cmp_gt_u32 s44, 13
	s_cbranch_scc0 .LBB0_1135
	s_and_b64 vcc, exec, s[6:7]
	s_cbranch_vccz .LBB0_1138
	s_barrier

; #define PG8_STAGE(bufoff, gbase, voff) do { _Pragma("unroll") for (int _i = 0; _i < 2; ++_i) \
;         __builtin_amdgcn_global_load_lds((const unsigned*)((const char*)(gbase) + (voff)[_i]), (PG8_LAS unsigned*)(lds + (bufoff) + ldsw + _i * 8192), 16, 0, 0); } while (0)
; #define PG8_LDA(dst, b, h) do { _Pragma("unroll") for (int m = 0; m < 4; ++m) _Pragma("unroll") for (int k = 0; k < 2; ++k) dst[m][k] = *(const PG8_LAS bf16x8*)(lds + PG8_SA(b, h) + aoff + m * 2048 + k * 1024); } while (0)
; #define PG8_LDB(dst, b, h) do { _Pragma("unroll") for (int n = 0; n < 2; ++n) _Pragma("unroll") for (int k = 0; k < 2; ++k) dst[n][k] = *(const PG8_LAS bf16x8*)(lds + PG8_SB(b, h) + boff + n * 2048 + k * 1024); } while (0)
; #define PG8_MMA(ai, bj, At, Bt) do { __builtin_amdgcn_s_setprio(1); _Pragma("unroll") for (int m = 0; m < 4; ++m) _Pragma("unroll") for (int n = 0; n < 2; ++n) _Pragma("unroll") for (int k = 0; k < 2; ++k) \
;         acc[ai][bj][m][n] = __builtin_amdgcn_mfma_f32_16x16x32_bf16(Bt[n][k], At[m][k], acc[ai][bj][m][n], 0, 0, 0); __builtin_amdgcn_s_setprio(0); } while (0)
; #define PG8_WAIT_V(n) asm volatile("s_waitcnt vmcnt(" #n ")" ::: "memory")
; #define PG8_WAIT_L(n) asm volatile("s_waitcnt lgkmcnt(" #n ")" ::: "memory")
; #define PG8_BAR __builtin_amdgcn_s_barrier()
; #define PG8_SCHED __builtin_amdgcn_sched_barrier(0)
; template <class Epi, class Sched, bool ALIGN_EPI = false, bool SP2 = false>
; __device__ __forceinline__ void gemm_phase(PG8_LAS unsigned char* lds, const Gemm g, const Sched& S, const Epi& E) {
;     ...
;             const bool last = (t == nt - 2);
;             const char* a1 = cA + (size_t)(t + 1) * kstep;
;             const char* a2 = last ? nA : cA + (size_t)(t + 2) * kstep; const char* b2 = last ? nB : cB + (size_t)(t + 2) * kstep;
;             const char* a3 = a2 + kstep; const char* b3 = b2 + kstep;
;             if (last && has_next) S.a_ready(nxt);
;             if constexpr (SP2) {
;             PG8_LDB(B0, 0, 0); PG8_LDB(B1, 0, 1); PG8_SCHED; PG8_LDA(At, 0, 0); PG8_STAGE(PG8_SA(1, 1), a1 + hstep, voffA);
;             PG8_WAIT_V(8); PG8_WAIT_L(0); PG8_BAR; PG8_MMA(0, 0, At, B0); PG8_MMA(0, 1, At, B1); PG8_BAR; PG8_SCHED;
;             PG8_LDA(At, 0, 1); PG8_STAGE(PG8_SB(0, 0), b2, voffB); PG8_STAGE(PG8_SB(0, 1), b2 + hstep, voffB); PG8_STAGE(PG8_SA(0, 0), a2, voffA);
.LBB0_1215:
	s_add_u32 s4, s2, 0xfff00080
	s_addc_u32 s5, s3, -1
	s_add_i32 s47, 0, 0x10000
	s_cmp_eq_u32 s46, 60
	s_cselect_b32 s23, s15, s5
	s_cselect_b32 s22, s42, s4
	s_cselect_b32 s5, s17, s45
	s_cselect_b32 s4, s43, s44
	s_add_i32 s50, 0, 0x14000
	v_add_u32_e32 v76, s47, v188
	v_add_u32_e32 v158, s50, v188
	ds_read_b128 v[56:59], v76
	ds_read_b128 v[60:63], v76 offset:1024
	ds_read_b128 v[68:71], v76 offset:2048
	ds_read_b128 v[76:79], v76 offset:3072
	ds_read_b128 v[144:147], v158
	ds_read_b128 v[162:165], v158 offset:1024
	ds_read_b128 v[166:169], v158 offset:2048
	ds_read_b128 v[170:173], v158 offset:3072
	v_lshl_add_u64 v[158:159], s[2:3], 0, v[154:155]
	s_add_i32 m0, s29, 0xc000
	ds_read_b128 v[174:177], v189
	ds_read_b128 v[178:181], v189 offset:1024
	ds_read_b128 v[182:185], v189 offset:2048
	ds_read_b128 v[194:197], v189 offset:3072
	ds_read_b128 v[206:209], v189 offset:4096
	ds_read_b128 v[210:213], v189 offset:5120
	ds_read_b128 v[214:217], v189 offset:6144
	ds_read_b128 v[218:221], v189 offset:7168
	global_load_lds_dwordx4 v[158:159], off
	v_lshl_add_u64 v[158:159], s[2:3], 0, v[156:157]
	s_add_i32 m0, s29, 0xe000
	s_nop 0
	global_load_lds_dwordx4 v[158:159], off
	s_waitcnt vmcnt(8)
	s_waitcnt lgkmcnt(0)
	s_barrier
	s_setprio 1
	s_waitcnt lgkmcnt(0)
	v_mfma_f32_16x16x32_bf16 v[64:67], v[56:59], v[174:177], v[64:67]
	v_mfma_f32_16x16x32_bf16 v[140:143], v[68:71], v[174:177], v[140:143]
	v_mfma_f32_16x16x32_bf16 v[128:131], v[56:59], v[182:185], v[128:131]
	v_mfma_f32_16x16x32_bf16 v[124:127], v[68:71], v[182:185], v[124:127]
	v_mfma_f32_16x16x32_bf16 v[112:115], v[56:59], v[206:209], v[112:115]
	v_mfma_f32_16x16x32_bf16 v[108:111], v[68:71], v[206:209], v[108:111]
	v_mfma_f32_16x16x32_bf16 v[96:99], v[56:59], v[214:217], v[96:99]
	v_mfma_f32_16x16x32_bf16 v[92:95], v[68:71], v[214:217], v[92:95]
	v_mfma_f32_16x16x32_bf16 v[64:67], v[60:63], v[178:181], v[64:67]
	v_mfma_f32_16x16x32_bf16 v[140:143], v[76:79], v[178:181], v[140:143]
	v_mfma_f32_16x16x32_bf16 v[128:131], v[60:63], v[194:197], v[128:131]
	v_mfma_f32_16x16x32_bf16 v[124:127], v[76:79], v[194:197], v[124:127]
	v_mfma_f32_16x16x32_bf16 v[112:115], v[60:63], v[210:213], v[112:115]
	v_mfma_f32_16x16x32_bf16 v[108:111], v[76:79], v[210:213], v[108:111]
	v_mfma_f32_16x16x32_bf16 v[96:99], v[60:63], v[218:221], v[96:99]
	v_mfma_f32_16x16x32_bf16 v[92:95], v[76:79], v[218:221], v[92:95]
	v_mfma_f32_16x16x32_bf16 v[136:139], v[144:147], v[174:177], v[136:139]
	v_mfma_f32_16x16x32_bf16 v[132:135], v[166:169], v[174:177], v[132:135]
	v_mfma_f32_16x16x32_bf16 v[120:123], v[144:147], v[182:185], v[120:123]
	v_mfma_f32_16x16x32_bf16 v[116:119], v[166:169], v[182:185], v[116:119]
	v_mfma_f32_16x16x32_bf16 v[104:107], v[144:147], v[206:209], v[104:107]
	v_mfma_f32_16x16x32_bf16 v[100:103], v[166:169], v[206:209], v[100:103]
	v_mfma_f32_16x16x32_bf16 v[88:91], v[144:147], v[214:217], v[88:91]
	v_mfma_f32_16x16x32_bf16 v[84:87], v[166:169], v[214:217], v[84:87]
	v_mfma_f32_16x16x32_bf16 v[136:139], v[162:165], v[178:181], v[136:139]
	v_mfma_f32_16x16x32_bf16 v[132:135], v[170:173], v[178:181], v[132:135]
	v_mfma_f32_16x16x32_bf16 v[120:123], v[162:165], v[194:197], v[120:123]
	v_mfma_f32_16x16x32_bf16 v[116:119], v[170:173], v[194:197], v[116:119]
	v_mfma_f32_16x16x32_bf16 v[104:107], v[162:165], v[210:213], v[104:107]
	v_mfma_f32_16x16x32_bf16 v[100:103], v[170:173], v[210:213], v[100:103]
	v_mfma_f32_16x16x32_bf16 v[88:91], v[162:165], v[218:221], v[88:91]
	v_mfma_f32_16x16x32_bf16 v[84:87], v[170:173], v[218:221], v[84:87]
	s_setprio 0
	s_barrier
	s_add_i32 s47, s47, s28
	v_lshl_add_u64 v[158:159], s[4:5], 0, v[160:161]
	s_mov_b32 m0, s47
	ds_read_b128 v[174:177], v189 offset:16384
	ds_read_b128 v[178:181], v189 offset:17408
	ds_read_b128 v[182:185], v189 offset:18432
	ds_read_b128 v[194:197], v189 offset:19456
	ds_read_b128 v[206:209], v189 offset:20480
	ds_read_b128 v[210:213], v189 offset:21504
	ds_read_b128 v[214:217], v189 offset:22528
	ds_read_b128 v[218:221], v189 offset:23552
	global_load_lds_dwordx4 v[158:159], off
	s_add_i32 m0, s47, 0x2000
	s_add_u32 s48, s4, 0x100000
	v_lshl_add_u64 v[186:187], s[4:5], 0, v[148:149]
	s_addc_u32 s49, s5, 0
	s_add_i32 s47, s50, s28
	global_load_lds_dwordx4 v[186:187], off
	v_lshl_add_u64 v[222:223], s[48:49], 0, v[160:161]
	s_mov_b32 m0, s47
	v_lshl_add_u64 v[224:225], s[22:23], 0, v[150:151]
	global_load_lds_dwordx4 v[222:223], off
	v_lshl_add_u64 v[222:223], s[48:49], 0, v[148:149]
	s_add_i32 m0, s47, 0x2000
	s_nop 0
	global_load_lds_dwordx4 v[222:223], off
	v_lshl_add_u64 v[222:223], s[22:23], 0, v[152:153]
	s_mov_b32 m0, s29
	s_nop 0
	global_load_lds_dwordx4 v[222:223], off
	s_mov_b32 m0, s30
	s_nop 0
	global_load_lds_dwordx4 v[224:225], off
	s_waitcnt vmcnt(8)
	s_waitcnt lgkmcnt(0)
	s_barrier
; #define PG8_STAGE(bufoff, gbase, voff) do { _Pragma("unroll") for (int _i = 0; _i < 2; ++_i) \
;         __builtin_amdgcn_global_load_lds((const unsigned*)((const char*)(gbase) + (voff)[_i]), (PG8_LAS unsigned*)(lds + (bufoff) + ldsw + _i * 8192), 16, 0, 0); } while (0)
; #define PG8_LDA(dst, b, h) do { _Pragma("unroll") for (int m = 0; m < 4; ++m) _Pragma("unroll") for (int k = 0; k < 2; ++k) dst[m][k] = *(const PG8_LAS bf16x8*)(lds + PG8_SA(b, h) + aoff + m * 2048 + k * 1024); } while (0)
; #define PG8_LDB(dst, b, h) do { _Pragma("unroll") for (int n = 0; n < 2; ++n) _Pragma("unroll") for (int k = 0; k < 2; ++k) dst[n][k] = *(const PG8_LAS bf16x8*)(lds + PG8_SB(b, h) + boff + n * 2048 + k * 1024); } while (0)
; #define PG8_MMA(ai, bj, At, Bt) do { __builtin_amdgcn_s_setprio(1); _Pragma("unroll") for (int m = 0; m < 4; ++m) _Pragma("unroll") for (int n = 0; n < 2; ++n) _Pragma("unroll") for (int k = 0; k < 2; ++k) \
;         acc[ai][bj][m][n] = __builtin_amdgcn_mfma_f32_16x16x32_bf16(Bt[n][k], At[m][k], acc[ai][bj][m][n], 0, 0, 0); __builtin_amdgcn_s_setprio(0); } while (0)
; #define PG8_WAIT_V(n) asm volatile("s_waitcnt vmcnt(" #n ")" ::: "memory")
; #define PG8_WAIT_L(n) asm volatile("s_waitcnt lgkmcnt(" #n ")" ::: "memory")
; #define PG8_BAR __builtin_amdgcn_s_barrier()
; #define PG8_SCHED __builtin_amdgcn_sched_barrier(0)
; template <class Epi, class Sched, bool ALIGN_EPI = false, bool SP2 = false>
; __device__ __forceinline__ void gemm_phase(PG8_LAS unsigned char* lds, const Gemm g, const Sched& S, const Epi& E) {
;     ...
;             PG8_WAIT_V(8); PG8_WAIT_L(0); PG8_BAR; PG8_MMA(1, 0, At, B0); PG8_MMA(1, 1, At, B1); PG8_BAR; PG8_SCHED;
;             PG8_LDB(B0, 1, 0); PG8_LDB(B1, 1, 1); PG8_SCHED; PG8_LDA(At, 1, 0); PG8_STAGE(PG8_SA(0, 1), a2 + hstep, voffA);
;             PG8_WAIT_V(8); PG8_WAIT_L(0); PG8_BAR; PG8_MMA(0, 0, At, B0); PG8_MMA(0, 1, At, B1); PG8_BAR; PG8_SCHED;
	s_setprio 1
	s_waitcnt lgkmcnt(0)
	v_mfma_f32_16x16x32_bf16 v[80:83], v[56:59], v[174:177], v[80:83]
	v_mfma_f32_16x16x32_bf16 v[72:75], v[68:71], v[174:177], v[72:75]
	v_mfma_f32_16x16x32_bf16 v[44:47], v[56:59], v[182:185], v[44:47]
	v_mfma_f32_16x16x32_bf16 v[40:43], v[68:71], v[182:185], v[40:43]
	v_mfma_f32_16x16x32_bf16 v[28:31], v[56:59], v[206:209], v[28:31]
	v_mfma_f32_16x16x32_bf16 v[24:27], v[68:71], v[206:209], v[24:27]
	v_mfma_f32_16x16x32_bf16 v[12:15], v[56:59], v[214:217], v[12:15]
	v_mfma_f32_16x16x32_bf16 v[8:11], v[68:71], v[214:217], v[8:11]
	v_mfma_f32_16x16x32_bf16 v[80:83], v[60:63], v[178:181], v[80:83]
	v_mfma_f32_16x16x32_bf16 v[72:75], v[76:79], v[178:181], v[72:75]
	v_mfma_f32_16x16x32_bf16 v[44:47], v[60:63], v[194:197], v[44:47]
	v_mfma_f32_16x16x32_bf16 v[40:43], v[76:79], v[194:197], v[40:43]
	v_mfma_f32_16x16x32_bf16 v[28:31], v[60:63], v[210:213], v[28:31]
	v_mfma_f32_16x16x32_bf16 v[24:27], v[76:79], v[210:213], v[24:27]
	v_mfma_f32_16x16x32_bf16 v[12:15], v[60:63], v[218:221], v[12:15]
	v_mfma_f32_16x16x32_bf16 v[8:11], v[76:79], v[218:221], v[8:11]
	v_mfma_f32_16x16x32_bf16 v[52:55], v[144:147], v[174:177], v[52:55]
	v_mfma_f32_16x16x32_bf16 v[48:51], v[166:169], v[174:177], v[48:51]
	v_mfma_f32_16x16x32_bf16 v[36:39], v[144:147], v[182:185], v[36:39]
	v_mfma_f32_16x16x32_bf16 v[32:35], v[166:169], v[182:185], v[32:35]
	v_mfma_f32_16x16x32_bf16 v[20:23], v[144:147], v[206:209], v[20:23]
	v_mfma_f32_16x16x32_bf16 v[16:19], v[166:169], v[206:209], v[16:19]
	v_mfma_f32_16x16x32_bf16 v[4:7], v[144:147], v[214:217], v[4:7]
	v_mfma_f32_16x16x32_bf16 v[0:3], v[166:169], v[214:217], v[0:3]
	v_mfma_f32_16x16x32_bf16 v[52:55], v[162:165], v[178:181], v[52:55]
	v_mfma_f32_16x16x32_bf16 v[48:51], v[170:173], v[178:181], v[48:51]
	v_mfma_f32_16x16x32_bf16 v[36:39], v[162:165], v[194:197], v[36:39]
	v_mfma_f32_16x16x32_bf16 v[32:35], v[170:173], v[194:197], v[32:35]
	v_mfma_f32_16x16x32_bf16 v[20:23], v[162:165], v[210:213], v[20:23]
	v_mfma_f32_16x16x32_bf16 v[16:19], v[170:173], v[210:213], v[16:19]
	v_mfma_f32_16x16x32_bf16 v[4:7], v[162:165], v[218:221], v[4:7]
	v_mfma_f32_16x16x32_bf16 v[0:3], v[170:173], v[218:221], v[0:3]
	s_setprio 0
	s_barrier
	s_add_i32 s47, 0, 0x18000
	s_add_i32 s48, 0, 0x1c000
	v_add_u32_e32 v76, s47, v188
	v_add_u32_e32 v170, s48, v188
	ds_read_b128 v[56:59], v76
	ds_read_b128 v[60:63], v76 offset:1024
	ds_read_b128 v[68:71], v76 offset:2048
	ds_read_b128 v[76:79], v76 offset:3072
	ds_read_b128 v[144:147], v170
	ds_read_b128 v[162:165], v170 offset:1024
	ds_read_b128 v[166:169], v170 offset:2048
	ds_read_b128 v[170:173], v170 offset:3072
	s_add_u32 s22, s22, 0x100000
	s_addc_u32 s23, s23, 0
	s_mov_b32 m0, s31
	v_lshl_add_u64 v[226:227], s[22:23], 0, v[152:153]
	ds_read_b128 v[174:177], v189 offset:32768
	ds_read_b128 v[178:181], v189 offset:33792
	ds_read_b128 v[182:185], v189 offset:34816
	ds_read_b128 v[194:197], v189 offset:35840
	ds_read_b128 v[206:209], v189 offset:36864
	ds_read_b128 v[210:213], v189 offset:37888
	ds_read_b128 v[214:217], v189 offset:38912
	ds_read_b128 v[218:221], v189 offset:39936
	global_load_lds_dwordx4 v[226:227], off
	v_lshl_add_u64 v[226:227], s[22:23], 0, v[150:151]
	s_mov_b32 m0, s34
	s_nop 0
	global_load_lds_dwordx4 v[226:227], off
	s_waitcnt vmcnt(8)
	s_waitcnt lgkmcnt(0)
	s_barrier
	s_setprio 1
	s_waitcnt lgkmcnt(0)
	v_mfma_f32_16x16x32_bf16 v[64:67], v[56:59], v[174:177], v[64:67]
	v_mfma_f32_16x16x32_bf16 v[140:143], v[68:71], v[174:177], v[140:143]
	v_mfma_f32_16x16x32_bf16 v[128:131], v[56:59], v[182:185], v[128:131]
	v_mfma_f32_16x16x32_bf16 v[124:127], v[68:71], v[182:185], v[124:127]
	v_mfma_f32_16x16x32_bf16 v[112:115], v[56:59], v[206:209], v[112:115]
	v_mfma_f32_16x16x32_bf16 v[108:111], v[68:71], v[206:209], v[108:111]
	v_mfma_f32_16x16x32_bf16 v[96:99], v[56:59], v[214:217], v[96:99]
	v_mfma_f32_16x16x32_bf16 v[92:95], v[68:71], v[214:217], v[92:95]
	v_mfma_f32_16x16x32_bf16 v[64:67], v[60:63], v[178:181], v[64:67]
	v_mfma_f32_16x16x32_bf16 v[140:143], v[76:79], v[178:181], v[140:143]
	v_mfma_f32_16x16x32_bf16 v[128:131], v[60:63], v[194:197], v[128:131]
	v_mfma_f32_16x16x32_bf16 v[124:127], v[76:79], v[194:197], v[124:127]
	v_mfma_f32_16x16x32_bf16 v[112:115], v[60:63], v[210:213], v[112:115]
	v_mfma_f32_16x16x32_bf16 v[108:111], v[76:79], v[210:213], v[108:111]
	v_mfma_f32_16x16x32_bf16 v[96:99], v[60:63], v[218:221], v[96:99]
	v_mfma_f32_16x16x32_bf16 v[92:95], v[76:79], v[218:221], v[92:95]
	v_mfma_f32_16x16x32_bf16 v[136:139], v[144:147], v[174:177], v[136:139]
	v_mfma_f32_16x16x32_bf16 v[132:135], v[166:169], v[174:177], v[132:135]
	v_mfma_f32_16x16x32_bf16 v[120:123], v[144:147], v[182:185], v[120:123]
	v_mfma_f32_16x16x32_bf16 v[116:119], v[166:169], v[182:185], v[116:119]
	v_mfma_f32_16x16x32_bf16 v[104:107], v[144:147], v[206:209], v[104:107]
	v_mfma_f32_16x16x32_bf16 v[100:103], v[166:169], v[206:209], v[100:103]
	v_mfma_f32_16x16x32_bf16 v[88:91], v[144:147], v[214:217], v[88:91]
	v_mfma_f32_16x16x32_bf16 v[84:87], v[166:169], v[214:217], v[84:87]
	v_mfma_f32_16x16x32_bf16 v[136:139], v[162:165], v[178:181], v[136:139]
	v_mfma_f32_16x16x32_bf16 v[132:135], v[170:173], v[178:181], v[132:135]
	v_mfma_f32_16x16x32_bf16 v[120:123], v[162:165], v[194:197], v[120:123]
	v_mfma_f32_16x16x32_bf16 v[116:119], v[170:173], v[194:197], v[116:119]
	v_mfma_f32_16x16x32_bf16 v[104:107], v[162:165], v[210:213], v[104:107]
	v_mfma_f32_16x16x32_bf16 v[100:103], v[170:173], v[210:213], v[100:103]
	v_mfma_f32_16x16x32_bf16 v[88:91], v[162:165], v[218:221], v[88:91]
	v_mfma_f32_16x16x32_bf16 v[84:87], v[170:173], v[218:221], v[84:87]
	s_setprio 0
	s_barrier
; #define PG8_STAGE(bufoff, gbase, voff) do { _Pragma("unroll") for (int _i = 0; _i < 2; ++_i) \
;         __builtin_amdgcn_global_load_lds((const unsigned*)((const char*)(gbase) + (voff)[_i]), (PG8_LAS unsigned*)(lds + (bufoff) + ldsw + _i * 8192), 16, 0, 0); } while (0)
; #define PG8_LDA(dst, b, h) do { _Pragma("unroll") for (int m = 0; m < 4; ++m) _Pragma("unroll") for (int k = 0; k < 2; ++k) dst[m][k] = *(const PG8_LAS bf16x8*)(lds + PG8_SA(b, h) + aoff + m * 2048 + k * 1024); } while (0)
; #define PG8_MMA(ai, bj, At, Bt) do { __builtin_amdgcn_s_setprio(1); _Pragma("unroll") for (int m = 0; m < 4; ++m) _Pragma("unroll") for (int n = 0; n < 2; ++n) _Pragma("unroll") for (int k = 0; k < 2; ++k) \
;         acc[ai][bj][m][n] = __builtin_amdgcn_mfma_f32_16x16x32_bf16(Bt[n][k], At[m][k], acc[ai][bj][m][n], 0, 0, 0); __builtin_amdgcn_s_setprio(0); } while (0)
; #define PG8_WAIT_V(n) asm volatile("s_waitcnt vmcnt(" #n ")" ::: "memory")
; #define PG8_WAIT_L(n) asm volatile("s_waitcnt lgkmcnt(" #n ")" ::: "memory")
; #define PG8_BAR __builtin_amdgcn_s_barrier()
; #define PG8_SCHED __builtin_amdgcn_sched_barrier(0)
; template <class Epi, class Sched, bool ALIGN_EPI = false, bool SP2 = false>
; __device__ __forceinline__ void gemm_phase(PG8_LAS unsigned char* lds, const Gemm g, const Sched& S, const Epi& E) {
;     ...
;             PG8_LDA(At, 1, 1); PG8_STAGE(PG8_SB(1, 0), b3, voffB); PG8_STAGE(PG8_SB(1, 1), b3 + hstep, voffB); PG8_STAGE(PG8_SA(1, 0), a3, voffA);
;             PG8_WAIT_V(8); PG8_WAIT_L(0); PG8_BAR; PG8_MMA(1, 0, At, B0); PG8_MMA(1, 1, At, B1); PG8_BAR; PG8_SCHED;
	s_add_i32 s22, s47, s28
	v_lshl_add_u64 v[158:159], v[158:159], 0, s[38:39]
	s_mov_b32 m0, s22
	ds_read_b128 v[174:177], v189 offset:49152
	ds_read_b128 v[178:181], v189 offset:50176
	ds_read_b128 v[182:185], v189 offset:51200
	ds_read_b128 v[194:197], v189 offset:52224
	ds_read_b128 v[206:209], v189 offset:53248
	ds_read_b128 v[210:213], v189 offset:54272
	ds_read_b128 v[214:217], v189 offset:55296
	ds_read_b128 v[218:221], v189 offset:56320
	global_load_lds_dwordx4 v[158:159], off
	s_add_i32 m0, s22, 0x2000
	s_add_u32 s4, s4, 0x100080
	v_lshl_add_u64 v[158:159], v[186:187], 0, s[38:39]
	s_addc_u32 s5, s5, 0
	s_add_i32 s22, s48, s28
	global_load_lds_dwordx4 v[158:159], off
	v_lshl_add_u64 v[158:159], s[4:5], 0, v[160:161]
	s_mov_b32 m0, s22
	s_nop 0
	global_load_lds_dwordx4 v[158:159], off
	v_lshl_add_u64 v[158:159], s[4:5], 0, v[148:149]
	s_add_i32 m0, s22, 0x2000
	s_nop 0
	global_load_lds_dwordx4 v[158:159], off
	v_lshl_add_u64 v[158:159], v[222:223], 0, s[38:39]
	s_mov_b32 m0, s37
	s_nop 0
	global_load_lds_dwordx4 v[158:159], off
	v_lshl_add_u64 v[158:159], v[224:225], 0, s[38:39]
	s_mov_b32 m0, s40
	s_nop 0
	global_load_lds_dwordx4 v[158:159], off
	s_waitcnt vmcnt(8)
	s_waitcnt lgkmcnt(0)
	s_barrier
	s_setprio 1
	s_waitcnt lgkmcnt(0)
	v_mfma_f32_16x16x32_bf16 v[80:83], v[56:59], v[174:177], v[80:83]
	v_mfma_f32_16x16x32_bf16 v[72:75], v[68:71], v[174:177], v[72:75]
	v_mfma_f32_16x16x32_bf16 v[44:47], v[56:59], v[182:185], v[44:47]
	v_mfma_f32_16x16x32_bf16 v[40:43], v[68:71], v[182:185], v[40:43]
	v_mfma_f32_16x16x32_bf16 v[28:31], v[56:59], v[206:209], v[28:31]
	v_mfma_f32_16x16x32_bf16 v[24:27], v[68:71], v[206:209], v[24:27]
	v_mfma_f32_16x16x32_bf16 v[12:15], v[56:59], v[214:217], v[12:15]
	v_mfma_f32_16x16x32_bf16 v[8:11], v[68:71], v[214:217], v[8:11]
	v_mfma_f32_16x16x32_bf16 v[80:83], v[60:63], v[178:181], v[80:83]
	v_mfma_f32_16x16x32_bf16 v[72:75], v[76:79], v[178:181], v[72:75]
	v_mfma_f32_16x16x32_bf16 v[44:47], v[60:63], v[194:197], v[44:47]
	v_mfma_f32_16x16x32_bf16 v[40:43], v[76:79], v[194:197], v[40:43]
	v_mfma_f32_16x16x32_bf16 v[28:31], v[60:63], v[210:213], v[28:31]
	v_mfma_f32_16x16x32_bf16 v[24:27], v[76:79], v[210:213], v[24:27]
	v_mfma_f32_16x16x32_bf16 v[12:15], v[60:63], v[218:221], v[12:15]
	v_mfma_f32_16x16x32_bf16 v[8:11], v[76:79], v[218:221], v[8:11]
	v_mfma_f32_16x16x32_bf16 v[52:55], v[144:147], v[174:177], v[52:55]
	v_mfma_f32_16x16x32_bf16 v[48:51], v[166:169], v[174:177], v[48:51]
	v_mfma_f32_16x16x32_bf16 v[36:39], v[144:147], v[182:185], v[36:39]
	v_mfma_f32_16x16x32_bf16 v[32:35], v[166:169], v[182:185], v[32:35]
	v_mfma_f32_16x16x32_bf16 v[20:23], v[144:147], v[206:209], v[20:23]
	v_mfma_f32_16x16x32_bf16 v[16:19], v[166:169], v[206:209], v[16:19]
	v_mfma_f32_16x16x32_bf16 v[4:7], v[144:147], v[214:217], v[4:7]
	v_mfma_f32_16x16x32_bf16 v[0:3], v[166:169], v[214:217], v[0:3]
	v_mfma_f32_16x16x32_bf16 v[52:55], v[162:165], v[178:181], v[52:55]
	v_mfma_f32_16x16x32_bf16 v[48:51], v[170:173], v[178:181], v[48:51]
	v_mfma_f32_16x16x32_bf16 v[36:39], v[162:165], v[194:197], v[36:39]
	v_mfma_f32_16x16x32_bf16 v[32:35], v[170:173], v[194:197], v[32:35]
	v_mfma_f32_16x16x32_bf16 v[20:23], v[162:165], v[210:213], v[20:23]
	v_mfma_f32_16x16x32_bf16 v[16:19], v[170:173], v[210:213], v[16:19]
	v_mfma_f32_16x16x32_bf16 v[4:7], v[162:165], v[218:221], v[4:7]
	v_mfma_f32_16x16x32_bf16 v[0:3], v[170:173], v[218:221], v[0:3]
	s_setprio 0
	s_barrier
	s_add_i32 s46, s46, 2
	s_add_u32 s2, s2, 0x100
	s_addc_u32 s3, s3, 0
	s_add_u32 s44, s44, 0x100
	s_addc_u32 s45, s45, 0
	s_cmp_gt_u32 s46, 61
	s_cbranch_scc0 .LBB0_1215
	s_and_b64 vcc, exec, s[10:11]
	s_cbranch_vccz .LBB0_1218
	s_barrier
